# rsqrt sites with argument >= 1e-6 by construction: dropped the never-taken denormal rescale (cmp/mul/cndmask x2) around v_rsq_f32
# speedup vs baseline: 1.0073x; 1.0046x over previous
; __device__ __forceinline__ float silu_f(float x) { return x * __builtin_amdgcn_rcpf(1.f + __expf(-x)); }
; __device__ __forceinline__ v4u pack8(const float (&y)[8]) { return (v4u){pk2(y[0], y[1]), pk2(y[2], y[3]), pk2(y[4], y[5]), pk2(y[6], y[7])}; }
;     __device__ __forceinline__ void operator()(const f32x4 (&acc)[2][2][4][2], const pg8::Unit& u, int wr, int wc, int fr, int fq) const {
;     ...
;             for (int ai = 0; ai < 2; ++ai)
; #pragma unroll
;                 for (int m = 0; m < 4; ++m) {
;                     const int lrow = lrow0 + ai * 128 + m * 16; const int row = row_base + lrow;
;                     const float rs = rsqrtf(ssq[row] * (1.f / 1024.f) + EPS);
; #pragma unroll
;                     for (int bj = 0; bj < 2; ++bj) {
;                         const int c = cb + bj * 128;
;                         const f32x4 v0 = acc[ai][bj][m][0] * rs, v1 = acc[ai][bj][m][1] * rs;
;                         const float v[8] = {v0[0], v0[1], v0[2], v0[3], v1[0], v1[1], v1[2], v1[3]};
;                         if (!gate) *(v4u*)(o0 + (size_t)lrow * 9216 + u.pn * 256 + c) = pack8(v);
;                         else { float y[8];
; #pragma unroll
;                             for (int j = 0; j < 8; ++j) y[j] = silu_f(v[j]);
;                             *(v4u*)(Y + (size_t)row * 1024 + (u.pn - 36) * 256 + c) = pack8(y); }
.LBB0_129:
	v_lshl_add_u32 v182, s25, 8, v1
	v_add_u32_e32 v178, s41, v182
	v_readlane_b32 s46, v251, 29
	v_ashrrev_i32_e32 v179, 31, v178
	v_readlane_b32 s47, v251, 30
	s_cmp_lt_i32 s24, 36
	s_movk_i32 s13, 0x4800
	v_lshl_add_u64 v[150:151], v[178:179], 2, s[46:47]
	global_load_dword v196, v[150:151], off offset:64
	global_load_dword v197, v[150:151], off offset:128
	global_load_dword v198, v[150:151], off offset:192
	global_load_dword v199, v[150:151], off offset:512
	global_load_dword v200, v[150:151], off offset:576
	global_load_dword v201, v[150:151], off offset:640
	global_load_dword v202, v[150:151], off offset:704
	global_load_dword v150, v[150:151], off
	s_cselect_b64 s[2:3], -1, 0
	s_lshl_b32 s24, s24, 8
	s_ashr_i32 s25, s24, 31
	v_readlane_b32 s20, v255, 24
	v_readlane_b32 s21, v255, 25
	s_waitcnt vmcnt(0)
	v_fmamk_f32 v150, v150, 0x3a800000, v139
	s_nop 0
	v_rsq_f32_e32 v150, v150
	s_nop 0
	s_nop 0
	v_mov_b32_e32 v168, v150
	v_mad_i64_i32 v[150:151], s[4:5], v182, s13, 0
	v_pk_mul_f32 v[174:175], v[128:129], v[168:169] op_sel_hi:[1,0]
	v_lshl_add_u64 v[128:129], s[34:35], 0, v[150:151]
	v_pk_mul_f32 v[176:177], v[126:127], v[168:169] op_sel_hi:[1,0]
	v_pk_mul_f32 v[126:127], v[124:125], v[168:169] op_sel_hi:[1,0]
	v_pk_mul_f32 v[172:173], v[122:123], v[168:169] op_sel_hi:[1,0]
	s_mov_b64 s[4:5], -1
	s_and_b64 vcc, exec, s[2:3]
	v_lshl_add_u64 v[170:171], s[24:25], 1, v[128:129]
	s_cbranch_vccz .LBB0_131
	v_cvt_pk_bf16_f32 v122, v176, v177
	v_cvt_pk_bf16_f32 v123, v174, v175
	v_cvt_pk_bf16_f32 v124, v172, v173
	v_cvt_pk_bf16_f32 v125, v126, v127
	v_lshl_add_u64 v[180:181], s[24:25], 1, v[128:129]
	s_mov_b64 s[4:5], 0

; __device__ __forceinline__ v4u pack8(const float (&y)[8]) { return (v4u){pk2(y[0], y[1]), pk2(y[2], y[3]), pk2(y[4], y[5]), pk2(y[6], y[7])}; }
;     __device__ __forceinline__ void operator()(const f32x4 (&acc)[2][2][4][2], const pg8::Unit& u, int wr, int wc, int fr, int fq) const {
;     ...
;                 for (int m = 0; m < 4; ++m) {
;                     const int lrow = lrow0 + ai * 128 + m * 16; const int row = row_base + lrow;
;                     const float rs = rsqrtf(ssq[row] * (1.f / 1024.f) + EPS);
; #pragma unroll
;                     for (int bj = 0; bj < 2; ++bj) {
;                         const int c = cb + bj * 128;
;                         const f32x4 v0 = acc[ai][bj][m][0] * rs, v1 = acc[ai][bj][m][1] * rs;
;                         const float v[8] = {v0[0], v0[1], v0[2], v0[3], v1[0], v1[1], v1[2], v1[3]};
;                         if (!gate) *(v4u*)(o0 + (size_t)lrow * 9216 + u.pn * 256 + c) = pack8(v);
.LBB0_137:
	v_mov_b32_e32 v127, v0
	v_lshl_add_u64 v[118:119], v[170:171], 0, v[126:127]
	global_store_dwordx4 v[118:119], v[114:117], off offset:256
	s_nop 1
	v_or_b32_e32 v116, 16, v182
	v_add_u32_e32 v122, s41, v116
	v_ashrrev_i32_e32 v123, 31, v122
	v_lshl_add_u64 v[114:115], v[122:123], 2, s[46:47]
	v_mov_b32_e32 v114, v196
	v_mad_i64_i32 v[116:117], s[2:3], v116, s13, 0
	s_mov_b64 s[2:3], -1
	v_fmamk_f32 v114, v114, 0x3a800000, v139
	s_nop 0
	v_rsq_f32_e32 v114, v114
	s_nop 0
	s_nop 0
	v_pk_mul_f32 v[124:125], v[110:111], v[114:115] op_sel_hi:[1,0]
	v_lshl_add_u64 v[110:111], s[34:35], 0, v[116:117]
	v_pk_mul_f32 v[120:121], v[112:113], v[114:115] op_sel_hi:[1,0]
	v_pk_mul_f32 v[112:113], v[108:109], v[114:115] op_sel_hi:[1,0]
	v_pk_mul_f32 v[118:119], v[106:107], v[114:115] op_sel_hi:[1,0]
	s_and_b64 vcc, exec, s[4:5]
	v_lshl_add_u64 v[116:117], s[24:25], 1, v[110:111]
	s_cbranch_vccnz .LBB0_139
	v_cvt_pk_bf16_f32 v106, v124, v125
	v_cvt_pk_bf16_f32 v107, v120, v121
	v_cvt_pk_bf16_f32 v108, v118, v119
	v_cvt_pk_bf16_f32 v109, v112, v113
	v_lshl_add_u64 v[128:129], s[24:25], 1, v[110:111]
	s_mov_b64 s[2:3], 0

; __device__ __forceinline__ v4u pack8(const float (&y)[8]) { return (v4u){pk2(y[0], y[1]), pk2(y[2], y[3]), pk2(y[4], y[5]), pk2(y[6], y[7])}; }
;     __device__ __forceinline__ void operator()(const f32x4 (&acc)[2][2][4][2], const pg8::Unit& u, int wr, int wc, int fr, int fq) const {
;     ...
;                 for (int m = 0; m < 4; ++m) {
;                     const int lrow = lrow0 + ai * 128 + m * 16; const int row = row_base + lrow;
;                     const float rs = rsqrtf(ssq[row] * (1.f / 1024.f) + EPS);
; #pragma unroll
;                     for (int bj = 0; bj < 2; ++bj) {
;                         const int c = cb + bj * 128;
;                         const f32x4 v0 = acc[ai][bj][m][0] * rs, v1 = acc[ai][bj][m][1] * rs;
;                         const float v[8] = {v0[0], v0[1], v0[2], v0[3], v1[0], v1[1], v1[2], v1[3]};
;                         if (!gate) *(v4u*)(o0 + (size_t)lrow * 9216 + u.pn * 256 + c) = pack8(v);
.LBB0_145:
	v_mov_b32_e32 v127, v0
	v_lshl_add_u64 v[102:103], v[116:117], 0, v[126:127]
	global_store_dwordx4 v[102:103], v[98:101], off offset:256
	s_nop 1
	v_or_b32_e32 v100, 32, v182
	v_add_u32_e32 v106, s41, v100
	v_ashrrev_i32_e32 v107, 31, v106
	v_lshl_add_u64 v[98:99], v[106:107], 2, s[46:47]
	v_mov_b32_e32 v98, v197
	v_mad_i64_i32 v[100:101], s[2:3], v100, s13, 0
	s_mov_b64 s[2:3], -1
	v_fmamk_f32 v98, v98, 0x3a800000, v139
	s_nop 0
	v_rsq_f32_e32 v98, v98
	s_nop 0
	s_nop 0
	v_pk_mul_f32 v[108:109], v[94:95], v[98:99] op_sel_hi:[1,0]
	v_lshl_add_u64 v[94:95], s[34:35], 0, v[100:101]
	v_pk_mul_f32 v[104:105], v[96:97], v[98:99] op_sel_hi:[1,0]
	v_pk_mul_f32 v[96:97], v[92:93], v[98:99] op_sel_hi:[1,0]
	v_pk_mul_f32 v[102:103], v[90:91], v[98:99] op_sel_hi:[1,0]
	s_and_b64 vcc, exec, s[4:5]
	v_lshl_add_u64 v[100:101], s[24:25], 1, v[94:95]
	s_cbranch_vccnz .LBB0_147
	v_cvt_pk_bf16_f32 v90, v108, v109
	v_cvt_pk_bf16_f32 v91, v104, v105
	v_cvt_pk_bf16_f32 v92, v102, v103
	v_cvt_pk_bf16_f32 v93, v96, v97
	v_lshl_add_u64 v[110:111], s[24:25], 1, v[94:95]
	s_mov_b64 s[2:3], 0

; __device__ __forceinline__ v4u pack8(const float (&y)[8]) { return (v4u){pk2(y[0], y[1]), pk2(y[2], y[3]), pk2(y[4], y[5]), pk2(y[6], y[7])}; }
;     __device__ __forceinline__ void operator()(const f32x4 (&acc)[2][2][4][2], const pg8::Unit& u, int wr, int wc, int fr, int fq) const {
;     ...
;                 for (int m = 0; m < 4; ++m) {
;                     const int lrow = lrow0 + ai * 128 + m * 16; const int row = row_base + lrow;
;                     const float rs = rsqrtf(ssq[row] * (1.f / 1024.f) + EPS);
; #pragma unroll
;                     for (int bj = 0; bj < 2; ++bj) {
;                         const int c = cb + bj * 128;
;                         const f32x4 v0 = acc[ai][bj][m][0] * rs, v1 = acc[ai][bj][m][1] * rs;
;                         const float v[8] = {v0[0], v0[1], v0[2], v0[3], v1[0], v1[1], v1[2], v1[3]};
;                         if (!gate) *(v4u*)(o0 + (size_t)lrow * 9216 + u.pn * 256 + c) = pack8(v);
.LBB0_153:
	v_mov_b32_e32 v127, v0
	v_lshl_add_u64 v[86:87], v[100:101], 0, v[126:127]
	global_store_dwordx4 v[86:87], v[82:85], off offset:256
	s_nop 1
	v_or_b32_e32 v84, 48, v182
	v_add_u32_e32 v90, s41, v84
	v_ashrrev_i32_e32 v91, 31, v90
	v_lshl_add_u64 v[82:83], v[90:91], 2, s[46:47]
	v_mov_b32_e32 v82, v198
	v_mad_i64_i32 v[84:85], s[2:3], v84, s13, 0
	s_mov_b64 s[2:3], -1
	v_fmamk_f32 v82, v82, 0x3a800000, v139
	s_nop 0
	v_rsq_f32_e32 v82, v82
	s_nop 0
	s_nop 0
	v_pk_mul_f32 v[92:93], v[78:79], v[82:83] op_sel_hi:[1,0]
	v_lshl_add_u64 v[78:79], s[34:35], 0, v[84:85]
	v_pk_mul_f32 v[88:89], v[80:81], v[82:83] op_sel_hi:[1,0]
	v_pk_mul_f32 v[80:81], v[76:77], v[82:83] op_sel_hi:[1,0]
	v_pk_mul_f32 v[86:87], v[74:75], v[82:83] op_sel_hi:[1,0]
	s_and_b64 vcc, exec, s[4:5]
	v_lshl_add_u64 v[84:85], s[24:25], 1, v[78:79]
	s_cbranch_vccnz .LBB0_155
	v_cvt_pk_bf16_f32 v74, v92, v93
	v_cvt_pk_bf16_f32 v75, v88, v89
	v_cvt_pk_bf16_f32 v76, v86, v87
	v_cvt_pk_bf16_f32 v77, v80, v81
	v_lshl_add_u64 v[94:95], s[24:25], 1, v[78:79]
	s_mov_b64 s[2:3], 0

; __device__ __forceinline__ v4u pack8(const float (&y)[8]) { return (v4u){pk2(y[0], y[1]), pk2(y[2], y[3]), pk2(y[4], y[5]), pk2(y[6], y[7])}; }
;     __device__ __forceinline__ void operator()(const f32x4 (&acc)[2][2][4][2], const pg8::Unit& u, int wr, int wc, int fr, int fq) const {
;     ...
;                 for (int m = 0; m < 4; ++m) {
;                     const int lrow = lrow0 + ai * 128 + m * 16; const int row = row_base + lrow;
;                     const float rs = rsqrtf(ssq[row] * (1.f / 1024.f) + EPS);
; #pragma unroll
;                     for (int bj = 0; bj < 2; ++bj) {
;                         const int c = cb + bj * 128;
;                         const f32x4 v0 = acc[ai][bj][m][0] * rs, v1 = acc[ai][bj][m][1] * rs;
;                         const float v[8] = {v0[0], v0[1], v0[2], v0[3], v1[0], v1[1], v1[2], v1[3]};
;                         if (!gate) *(v4u*)(o0 + (size_t)lrow * 9216 + u.pn * 256 + c) = pack8(v);
.LBB0_161:
	v_mov_b32_e32 v127, v0
	v_lshl_add_u64 v[70:71], v[84:85], 0, v[126:127]
	global_store_dwordx4 v[70:71], v[66:69], off offset:256
	s_nop 1
	v_add_u32_e32 v68, 0x80, v182
	v_add_u32_e32 v74, s41, v68
	v_ashrrev_i32_e32 v75, 31, v74
	v_lshl_add_u64 v[66:67], v[74:75], 2, s[46:47]
	v_mov_b32_e32 v66, v199
	v_mad_i64_i32 v[68:69], s[2:3], v68, s13, 0
	s_mov_b64 s[2:3], -1
	v_fmamk_f32 v66, v66, 0x3a800000, v139
	s_nop 0
	v_rsq_f32_e32 v66, v66
	s_nop 0
	s_nop 0
	v_pk_mul_f32 v[76:77], v[62:63], v[66:67] op_sel_hi:[1,0]
	v_lshl_add_u64 v[62:63], s[34:35], 0, v[68:69]
	v_pk_mul_f32 v[72:73], v[64:65], v[66:67] op_sel_hi:[1,0]
	v_pk_mul_f32 v[64:65], v[60:61], v[66:67] op_sel_hi:[1,0]
	v_pk_mul_f32 v[70:71], v[58:59], v[66:67] op_sel_hi:[1,0]
	s_and_b64 vcc, exec, s[4:5]
	v_lshl_add_u64 v[68:69], s[24:25], 1, v[62:63]
	s_cbranch_vccnz .LBB0_163
	v_cvt_pk_bf16_f32 v58, v76, v77
	v_cvt_pk_bf16_f32 v59, v72, v73
	v_cvt_pk_bf16_f32 v60, v70, v71
	v_cvt_pk_bf16_f32 v61, v64, v65
	v_lshl_add_u64 v[78:79], s[24:25], 1, v[62:63]
	s_mov_b64 s[2:3], 0

; __device__ __forceinline__ v4u pack8(const float (&y)[8]) { return (v4u){pk2(y[0], y[1]), pk2(y[2], y[3]), pk2(y[4], y[5]), pk2(y[6], y[7])}; }
;     __device__ __forceinline__ void operator()(const f32x4 (&acc)[2][2][4][2], const pg8::Unit& u, int wr, int wc, int fr, int fq) const {
;     ...
;                 for (int m = 0; m < 4; ++m) {
;                     const int lrow = lrow0 + ai * 128 + m * 16; const int row = row_base + lrow;
;                     const float rs = rsqrtf(ssq[row] * (1.f / 1024.f) + EPS);
; #pragma unroll
;                     for (int bj = 0; bj < 2; ++bj) {
;                         const int c = cb + bj * 128;
;                         const f32x4 v0 = acc[ai][bj][m][0] * rs, v1 = acc[ai][bj][m][1] * rs;
;                         const float v[8] = {v0[0], v0[1], v0[2], v0[3], v1[0], v1[1], v1[2], v1[3]};
;                         if (!gate) *(v4u*)(o0 + (size_t)lrow * 9216 + u.pn * 256 + c) = pack8(v);
.LBB0_169:
	v_mov_b32_e32 v127, v0
	v_lshl_add_u64 v[54:55], v[68:69], 0, v[126:127]
	global_store_dwordx4 v[54:55], v[50:53], off offset:256
	s_nop 1
	v_add_u32_e32 v52, 0x90, v182
	v_add_u32_e32 v58, s41, v52
	v_ashrrev_i32_e32 v59, 31, v58
	v_lshl_add_u64 v[50:51], v[58:59], 2, s[46:47]
	v_mov_b32_e32 v50, v200
	v_mad_i64_i32 v[52:53], s[2:3], v52, s13, 0
	s_mov_b64 s[2:3], -1
	v_fmamk_f32 v50, v50, 0x3a800000, v139
	s_nop 0
	v_rsq_f32_e32 v50, v50
	s_nop 0
	s_nop 0
	v_pk_mul_f32 v[60:61], v[46:47], v[50:51] op_sel_hi:[1,0]
	v_lshl_add_u64 v[46:47], s[34:35], 0, v[52:53]
	v_pk_mul_f32 v[56:57], v[48:49], v[50:51] op_sel_hi:[1,0]
	v_pk_mul_f32 v[48:49], v[44:45], v[50:51] op_sel_hi:[1,0]
	v_pk_mul_f32 v[54:55], v[42:43], v[50:51] op_sel_hi:[1,0]
	s_and_b64 vcc, exec, s[4:5]
	v_lshl_add_u64 v[52:53], s[24:25], 1, v[46:47]
	s_cbranch_vccnz .LBB0_171
	v_cvt_pk_bf16_f32 v42, v60, v61
	v_cvt_pk_bf16_f32 v43, v56, v57
	v_cvt_pk_bf16_f32 v44, v54, v55
	v_cvt_pk_bf16_f32 v45, v48, v49
	v_lshl_add_u64 v[62:63], s[24:25], 1, v[46:47]
	s_mov_b64 s[2:3], 0

; __device__ __forceinline__ v4u pack8(const float (&y)[8]) { return (v4u){pk2(y[0], y[1]), pk2(y[2], y[3]), pk2(y[4], y[5]), pk2(y[6], y[7])}; }
;     __device__ __forceinline__ void operator()(const f32x4 (&acc)[2][2][4][2], const pg8::Unit& u, int wr, int wc, int fr, int fq) const {
;     ...
;                 for (int m = 0; m < 4; ++m) {
;                     const int lrow = lrow0 + ai * 128 + m * 16; const int row = row_base + lrow;
;                     const float rs = rsqrtf(ssq[row] * (1.f / 1024.f) + EPS);
; #pragma unroll
;                     for (int bj = 0; bj < 2; ++bj) {
;                         const int c = cb + bj * 128;
;                         const f32x4 v0 = acc[ai][bj][m][0] * rs, v1 = acc[ai][bj][m][1] * rs;
;                         const float v[8] = {v0[0], v0[1], v0[2], v0[3], v1[0], v1[1], v1[2], v1[3]};
;                         if (!gate) *(v4u*)(o0 + (size_t)lrow * 9216 + u.pn * 256 + c) = pack8(v);
.LBB0_177:
	v_mov_b32_e32 v127, v0
	v_lshl_add_u64 v[38:39], v[52:53], 0, v[126:127]
	global_store_dwordx4 v[38:39], v[34:37], off offset:256
	s_nop 1
	v_add_u32_e32 v36, 0xa0, v182
	v_add_u32_e32 v42, s41, v36
	v_ashrrev_i32_e32 v43, 31, v42
	v_lshl_add_u64 v[34:35], v[42:43], 2, s[46:47]
	v_mov_b32_e32 v34, v201
	v_mad_i64_i32 v[36:37], s[2:3], v36, s13, 0
	s_mov_b64 s[2:3], -1
	v_fmamk_f32 v34, v34, 0x3a800000, v139
	s_nop 0
	v_rsq_f32_e32 v34, v34
	s_nop 0
	s_nop 0
	v_pk_mul_f32 v[44:45], v[30:31], v[34:35] op_sel_hi:[1,0]
	v_lshl_add_u64 v[30:31], s[34:35], 0, v[36:37]
	v_pk_mul_f32 v[40:41], v[32:33], v[34:35] op_sel_hi:[1,0]
	v_pk_mul_f32 v[32:33], v[28:29], v[34:35] op_sel_hi:[1,0]
	v_pk_mul_f32 v[38:39], v[26:27], v[34:35] op_sel_hi:[1,0]
	s_and_b64 vcc, exec, s[4:5]
	v_lshl_add_u64 v[36:37], s[24:25], 1, v[30:31]
	s_cbranch_vccnz .LBB0_179
	v_cvt_pk_bf16_f32 v26, v44, v45
	v_cvt_pk_bf16_f32 v27, v40, v41
	v_cvt_pk_bf16_f32 v28, v38, v39
	v_cvt_pk_bf16_f32 v29, v32, v33
	v_lshl_add_u64 v[46:47], s[24:25], 1, v[30:31]
	s_mov_b64 s[2:3], 0

; __device__ __forceinline__ v4u pack8(const float (&y)[8]) { return (v4u){pk2(y[0], y[1]), pk2(y[2], y[3]), pk2(y[4], y[5]), pk2(y[6], y[7])}; }
;     __device__ __forceinline__ void operator()(const f32x4 (&acc)[2][2][4][2], const pg8::Unit& u, int wr, int wc, int fr, int fq) const {
;     ...
;                 for (int m = 0; m < 4; ++m) {
;                     const int lrow = lrow0 + ai * 128 + m * 16; const int row = row_base + lrow;
;                     const float rs = rsqrtf(ssq[row] * (1.f / 1024.f) + EPS);
; #pragma unroll
;                     for (int bj = 0; bj < 2; ++bj) {
;                         const int c = cb + bj * 128;
;                         const f32x4 v0 = acc[ai][bj][m][0] * rs, v1 = acc[ai][bj][m][1] * rs;
;                         const float v[8] = {v0[0], v0[1], v0[2], v0[3], v1[0], v1[1], v1[2], v1[3]};
;                         if (!gate) *(v4u*)(o0 + (size_t)lrow * 9216 + u.pn * 256 + c) = pack8(v);
.LBB0_185:
	v_mov_b32_e32 v127, v0
	v_lshl_add_u64 v[22:23], v[36:37], 0, v[126:127]
	global_store_dwordx4 v[22:23], v[18:21], off offset:256
	s_nop 1
	v_add_u32_e32 v20, 0xb0, v182
	v_add_u32_e32 v26, s41, v20
	v_ashrrev_i32_e32 v27, 31, v26
	v_lshl_add_u64 v[18:19], v[26:27], 2, s[46:47]
	v_mov_b32_e32 v18, v202
	v_mad_i64_i32 v[20:21], s[2:3], v20, s13, 0
	s_mov_b64 s[2:3], -1
	v_fmamk_f32 v18, v18, 0x3a800000, v139
	s_nop 0
	v_rsq_f32_e32 v18, v18
	s_nop 0
	s_nop 0
	v_pk_mul_f32 v[28:29], v[14:15], v[18:19] op_sel_hi:[1,0]
	v_lshl_add_u64 v[14:15], s[34:35], 0, v[20:21]
	v_pk_mul_f32 v[24:25], v[16:17], v[18:19] op_sel_hi:[1,0]
	v_pk_mul_f32 v[16:17], v[12:13], v[18:19] op_sel_hi:[1,0]
	v_pk_mul_f32 v[22:23], v[10:11], v[18:19] op_sel_hi:[1,0]
	s_and_b64 vcc, exec, s[4:5]
	v_lshl_add_u64 v[20:21], s[24:25], 1, v[14:15]
	s_cbranch_vccnz .LBB0_187
	v_cvt_pk_bf16_f32 v10, v28, v29
	v_cvt_pk_bf16_f32 v11, v24, v25
	v_cvt_pk_bf16_f32 v12, v22, v23
	v_cvt_pk_bf16_f32 v13, v16, v17
	v_lshl_add_u64 v[30:31], s[24:25], 1, v[14:15]
	s_mov_b64 s[2:3], 0

; #define LAS __attribute__((address_space(3)))
; __device__ __forceinline__ float bflo(unsigned u) { return __uint_as_float(u << 16); }
; __device__ __forceinline__ void attn_phase(LAS unsigned char* lds, const bf16* PROJ, const bf16* Ygate, bf16* OG0, bf16* OG1, bf16* OG2, float* LSE, const float* qnw, const float* knw, int bx, int G) {
;     ...
;         const int sub = t & 15, gi = (t >> 4) % 3, bh = t / 48, h = bh & 15, bl = bh >> 4;
;         const int sh = 2 * gi, d = 1 << sh, r = sub & (d - 1), n = sub >> sh;
;         const float ad = exp2f(-8.f * (float)(gi * 16 + h + 1) / 48.f) * (float)d;
;         bf16* OG = gi == 0 ? OG0 : (gi == 1 ? OG1 : OG2);
;         {
;             const f32x4 kw0 = *(const f32x4*)(knw + gi * 64 + 8 * oct), kw1 = *(const f32x4*)(knw + gi * 64 + 8 * oct + 4);
; #pragma unroll
;             for (int jj = 0; jj < 4; ++jj) {
;                 const int key = (tid >> 3) + 64 * jj; const v4u kq = kr[half][jj];
;                 float kf[8] = {bflo(kq.x), bfhi(kq.x), bflo(kq.y), bfhi(kq.y), bflo(kq.z), bfhi(kq.z), bflo(kq.w), bfhi(kq.w)};
;                 float ss = 0.f;
; #pragma unroll
;                 for (int e = 0; e < 8; ++e) ss += kf[e] * kf[e];
;                 ss += __shfl_xor(ss, 1); ss += __shfl_xor(ss, 2); ss += __shfl_xor(ss, 4);
;                 const float rs = rsqrtf(ss * (1.f / 64.f) + EPS);
;                 v4u ko; ko.x = pk2(kf[0] * rs * kw0[0], kf[1] * rs * kw0[1]); ko.y = pk2(kf[2] * rs * kw0[2], kf[3] * rs * kw0[3]);
;                 ko.z = pk2(kf[4] * rs * kw1[0], kf[5] * rs * kw1[1]); ko.w = pk2(kf[6] * rs * kw1[2], kf[7] * rs * kw1[3]);
;                 *(LAS v4u*)(Ks + key * 72 + 8 * oct) = ko;
;                 *(LAS v4u*)(Vs + key * 80 + 8 * oct) = vr[half][jj];
;             }
;         }
;         const int qi = 16 * w + l16;
;         const size_t qrow = (size_t)bl * SEQL + (size_t)(128 * n + qi) * d + r;
;         bf16x8 qreg[2];
;         {
;             float qf[2][8]; float ss = 0.f;
; #pragma unroll
;             for (int ks = 0; ks < 2; ++ks) {
;                 const v4u qq = qr[half][ks];
;                 qf[ks][0] = bflo(qq.x); qf[ks][1] = bfhi(qq.x); qf[ks][2] = bflo(qq.y); qf[ks][3] = bfhi(qq.y); qf[ks][4] = bflo(qq.z); qf[ks][5] = bfhi(qq.z); qf[ks][6] = bflo(qq.w); qf[ks][7] = bfhi(qq.w);
; #pragma unroll
;                 for (int e = 0; e < 8; ++e) ss += qf[ks][e] * qf[ks][e];
.LBB0_269:
	s_ashr_i32 s0, s51, 4
	s_mul_hi_i32 s1, s0, 0x55555556
	s_lshr_b32 s2, s1, 31
	s_add_i32 s1, s1, s2
	s_mul_i32 s1, s1, 3
	s_sub_i32 s2, s0, s1
	s_mul_hi_i32 s0, s51, 0x2aaaaaab
	s_lshl_b32 s3, s2, 1
	s_and_b32 s20, s51, 15
	s_lshr_b32 s1, s0, 31
	s_ashr_i32 s21, s0, 3
	s_bfm_b32 s0, s3, 0
	s_and_b32 s22, s0, s20
	s_lshl_b32 s0, s2, 6
	s_add_i32 s21, s21, s1
	s_ashr_i32 s1, s0, 31
	s_lshl_b64 s[24:25], s[0:1], 2
	v_lshl_add_u64 v[2:3], v[110:111], 0, s[24:25]
	global_load_dwordx4 v[84:87], v[2:3], off offset:16
	global_load_dwordx4 v[88:91], v[2:3], off
	s_waitcnt vmcnt(5)
	v_lshlrev_b32_e32 v102, 16, v8
	v_and_b32_e32 v103, 0xffff0000, v8
	v_lshlrev_b32_e32 v98, 16, v9
	v_and_b32_e32 v99, 0xffff0000, v9
	v_pk_mul_f32 v[104:105], v[102:103], v[102:103]
	v_pk_mul_f32 v[100:101], v[98:99], v[98:99]
	v_add_f32_e32 v1, v104, v105
	v_lshlrev_b32_e32 v94, 16, v10
	v_and_b32_e32 v95, 0xffff0000, v10
	v_add_f32_e32 v1, v100, v1
	v_pk_mul_f32 v[96:97], v[94:95], v[94:95]
	v_add_f32_e32 v1, v101, v1
	v_lshlrev_b32_e32 v2, 16, v11
	v_and_b32_e32 v3, 0xffff0000, v11
	v_add_f32_e32 v1, v96, v1
	v_pk_mul_f32 v[92:93], v[2:3], v[2:3]
	v_add_f32_e32 v1, v97, v1
	v_add_f32_e32 v1, v92, v1
	v_add_f32_e32 v1, v93, v1
	s_nop 1
	v_mov_b32_dpp v92, v1 quad_perm:[1,0,3,2] row_mask:0xf bank_mask:0xf
	v_lshlrev_b32_e32 v156, 16, v20
	v_and_b32_e32 v157, 0xffff0000, v20
	v_lshlrev_b32_e32 v152, 16, v21
	v_and_b32_e32 v153, 0xffff0000, v21
	s_waitcnt lgkmcnt(0)
	v_add_f32_e32 v1, v1, v92
	s_nop 1
	v_mov_b32_dpp v92, v1 quad_perm:[2,3,0,1] row_mask:0xf bank_mask:0xf
	v_pk_mul_f32 v[158:159], v[156:157], v[156:157]
	v_pk_mul_f32 v[154:155], v[152:153], v[152:153]
	v_mov_b32_e32 v162, v158
	v_lshlrev_b32_e32 v136, 16, v22
	s_waitcnt lgkmcnt(0)
	v_add_f32_e32 v1, v1, v92
	s_nop 1
	v_mov_b32_dpp v92, v1 row_half_mirror row_mask:0xf bank_mask:0xf
	v_and_b32_e32 v137, 0xffff0000, v22
	v_mov_b32_e32 v158, v154
	v_pk_mul_f32 v[150:151], v[136:137], v[136:137]
	v_lshlrev_b32_e32 v106, 16, v23
	s_waitcnt lgkmcnt(0)
	v_add_f32_e32 v1, v1, v92
	v_fmamk_f32 v1, v1, 0x3c800000, v139
	v_and_b32_e32 v107, 0xffff0000, v23
	v_rsq_f32_e32 v1, v1
	v_pk_mul_f32 v[134:135], v[106:107], v[106:107]
	s_mov_b32 s0, 0x358637bd
	s_mov_b32 s26, 0x3c800000
	s_nop 0
	v_mov_b32_e32 v96, v1
	v_pk_mul_f32 v[92:93], v[96:97], v[102:103] op_sel_hi:[0,1]
	v_pk_mul_f32 v[98:99], v[96:97], v[98:99] op_sel_hi:[0,1]
	v_pk_mul_f32 v[94:95], v[96:97], v[94:95] op_sel_hi:[0,1]
	v_pk_mul_f32 v[2:3], v[96:97], v[2:3] op_sel_hi:[0,1]
	v_lshlrev_b32_e32 v102, 16, v4
	v_and_b32_e32 v103, 0xffff0000, v4
	v_pk_mul_f32 v[104:105], v[102:103], v[102:103]
	s_waitcnt vmcnt(3)
	v_and_b32_e32 v179, 0xffff0000, v48
	v_mov_b32_e32 v163, v104
	v_mov_b32_e32 v104, v159
	v_pk_add_f32 v[104:105], v[162:163], v[104:105]
	v_lshlrev_b32_e32 v178, 16, v48
	v_mul_f32_e32 v240, v179, v179
	v_lshlrev_b32_e32 v176, 16, v49
	v_and_b32_e32 v177, 0xffff0000, v49
	v_pk_fma_f32 v[240:241], v[178:179], v[178:179], v[240:241] op_sel_hi:[1,1,0]
	v_mul_f32_e32 v242, v177, v177
	v_pk_fma_f32 v[240:241], v[176:177], v[176:177], v[240:241]
	v_lshlrev_b32_e32 v174, 16, v50
	v_and_b32_e32 v175, 0xffff0000, v50
	v_pk_add_f32 v[240:241], v[242:243], v[240:241] op_sel_hi:[0,1]
	v_pk_fma_f32 v[240:241], v[174:175], v[174:175], v[240:241]
	v_mul_f32_e32 v242, v175, v175
	v_lshlrev_b32_e32 v172, 16, v51
	v_and_b32_e32 v173, 0xffff0000, v51
	v_pk_add_f32 v[240:241], v[242:243], v[240:241] op_sel_hi:[0,1]
	v_add_u32_e32 v231, v113, v188
	v_lshlrev_b32_e32 v162, 16, v40
	v_and_b32_e32 v163, 0xffff0000, v40
	s_waitcnt vmcnt(2)
	v_lshlrev_b32_e32 v170, 16, v52
	s_waitcnt vmcnt(1)
	v_pk_mul_f32 v[94:95], v[84:85], v[94:95]
	s_waitcnt vmcnt(0)
	v_pk_mul_f32 v[92:93], v[88:89], v[92:93]
	v_pk_mul_f32 v[98:99], v[90:91], v[98:99]
	v_cvt_pk_bf16_f32 v92, v92, v93
	v_cvt_pk_bf16_f32 v93, v98, v99
	v_pk_mul_f32 v[2:3], v[86:87], v[2:3]
	v_lshlrev_b32_e32 v98, 16, v5
	v_and_b32_e32 v99, 0xffff0000, v5
	v_cvt_pk_bf16_f32 v94, v94, v95
	v_cvt_pk_bf16_f32 v95, v2, v3
	v_pk_mul_f32 v[100:101], v[98:99], v[98:99]
	ds_write_b128 v229, v[92:95]
	v_lshlrev_b32_e32 v94, 16, v6
	v_and_b32_e32 v95, 0xffff0000, v6
	v_mov_b32_e32 v159, v100
	v_pk_mul_f32 v[96:97], v[94:95], v[94:95]
	v_pk_add_f32 v[104:105], v[158:159], v[104:105]
	v_mov_b32_e32 v100, v155
	v_lshlrev_b32_e32 v2, 16, v7
	v_and_b32_e32 v3, 0xffff0000, v7
	v_pk_add_f32 v[100:101], v[100:101], v[104:105]
	v_mov_b32_e32 v104, v150
	v_mov_b32_e32 v105, v96
	v_pk_mul_f32 v[92:93], v[2:3], v[2:3]
	v_pk_add_f32 v[100:101], v[104:105], v[100:101]
	v_mov_b32_e32 v96, v151
	v_pk_add_f32 v[96:97], v[96:97], v[100:101]
	v_mov_b32_e32 v100, v134
	v_mov_b32_e32 v101, v92
	v_pk_add_f32 v[96:97], v[100:101], v[96:97]
	v_mov_b32_e32 v92, v135
	v_pk_add_f32 v[92:93], v[92:93], v[96:97]
	s_nop 1
	v_mov_b32_dpp v97, v93 quad_perm:[1,0,3,2] row_mask:0xf bank_mask:0xf
	s_nop 1
	v_mov_b32_dpp v96, v92 quad_perm:[1,0,3,2] row_mask:0xf bank_mask:0xf
	v_mov_b64_e32 v[134:135], s[0:1]
	v_and_b32_e32 v171, 0xffff0000, v52
	v_pk_fma_f32 v[240:241], v[172:173], v[172:173], v[240:241]
	v_mul_f32_e32 v242, v173, v173
	s_waitcnt lgkmcnt(0)
	v_pk_add_f32 v[92:93], v[92:93], v[96:97]
	s_nop 1
	v_mov_b32_dpp v97, v93 quad_perm:[2,3,0,1] row_mask:0xf bank_mask:0xf
	s_nop 1
	v_mov_b32_dpp v96, v92 quad_perm:[2,3,0,1] row_mask:0xf bank_mask:0xf
	ds_write_b128 v231, v[12:15] offset:36864
	v_pk_mul_f32 v[180:181], v[162:163], v[162:163]
	v_pk_mul_f32 v[238:239], v[170:171], v[170:171]
	v_pk_add_f32 v[240:241], v[242:243], v[240:241] op_sel_hi:[0,1]
	s_waitcnt lgkmcnt(1)
; #define LAS __attribute__((address_space(3)))
; __device__ __forceinline__ void attn_phase(LAS unsigned char* lds, const bf16* PROJ, const bf16* Ygate, bf16* OG0, bf16* OG1, bf16* OG2, float* LSE, const float* qnw, const float* knw, int bx, int G) {
;     ...
;             for (int jj = 0; jj < 4; ++jj) {
;                 const int key = (tid >> 3) + 64 * jj; const v4u kq = kr[half][jj];
;                 float kf[8] = {bflo(kq.x), bfhi(kq.x), bflo(kq.y), bfhi(kq.y), bflo(kq.z), bfhi(kq.z), bflo(kq.w), bfhi(kq.w)};
;                 float ss = 0.f;
; #pragma unroll
;                 for (int e = 0; e < 8; ++e) ss += kf[e] * kf[e];
;                 ss += __shfl_xor(ss, 1); ss += __shfl_xor(ss, 2); ss += __shfl_xor(ss, 4);
;                 const float rs = rsqrtf(ss * (1.f / 64.f) + EPS);
;                 v4u ko; ko.x = pk2(kf[0] * rs * kw0[0], kf[1] * rs * kw0[1]); ko.y = pk2(kf[2] * rs * kw0[2], kf[3] * rs * kw0[3]);
;                 ko.z = pk2(kf[4] * rs * kw1[0], kf[5] * rs * kw1[1]); ko.w = pk2(kf[6] * rs * kw1[2], kf[7] * rs * kw1[3]);
;                 *(LAS v4u*)(Ks + key * 72 + 8 * oct) = ko;
;                 *(LAS v4u*)(Vs + key * 80 + 8 * oct) = vr[half][jj];
;             }
;         }
;         const int qi = 16 * w + l16;
;         const size_t qrow = (size_t)bl * SEQL + (size_t)(128 * n + qi) * d + r;
;         bf16x8 qreg[2];
;         {
;             float qf[2][8]; float ss = 0.f;
; #pragma unroll
;             for (int ks = 0; ks < 2; ++ks) {
;                 const v4u qq = qr[half][ks];
;                 qf[ks][0] = bflo(qq.x); qf[ks][1] = bfhi(qq.x); qf[ks][2] = bflo(qq.y); qf[ks][3] = bfhi(qq.y); qf[ks][4] = bflo(qq.z); qf[ks][5] = bfhi(qq.z); qf[ks][6] = bflo(qq.w); qf[ks][7] = bfhi(qq.w);
; #pragma unroll
;                 for (int e = 0; e < 8; ++e) ss += qf[ks][e] * qf[ks][e];
;             }
;             ss += __shfl_xor(ss, 16); ss += __shfl_xor(ss, 32);
;             const float rs = rsqrtf(ss * (1.f / 64.f) + EPS) * 0.125f;
; #pragma unroll
;             for (int ks = 0; ks < 2; ++ks) {
;                 const f32x4 w0 = *(const f32x4*)(qnw + gi * 64 + 32 * ks + 8 * g4), w1 = *(const f32x4*)(qnw + gi * 64 + 32 * ks + 8 * g4 + 4);
;                 v4u tq; tq.x = pk2(qf[ks][0] * rs * w0[0], qf[ks][1] * rs * w0[1]); tq.y = pk2(qf[ks][2] * rs * w0[2], qf[ks][3] * rs * w0[3]);
	v_pk_add_f32 v[92:93], v[92:93], v[96:97]
	s_nop 1
	v_mov_b32_dpp v97, v93 row_half_mirror row_mask:0xf bank_mask:0xf
	s_nop 1
	v_mov_b32_dpp v96, v92 row_half_mirror row_mask:0xf bank_mask:0xf
	v_lshlrev_b32_e32 v168, 16, v53
	v_and_b32_e32 v169, 0xffff0000, v53
	v_mov_b32_e32 v242, v238
	v_mov_b32_e32 v243, v180
	s_waitcnt lgkmcnt(0)
	v_pk_add_f32 v[92:93], v[92:93], v[96:97]
	v_mov_b32_e32 v241, v181
	v_pk_fma_f32 v[96:97], v[92:93], s[26:27], v[134:135] op_sel_hi:[1,0,0]
	v_pk_mul_f32 v[236:237], v[168:169], v[168:169]
	v_mul_f32_e32 v1, 0x4b800000, v97
	v_cmp_gt_f32_e64 s[0:1], s33, v97
	v_pk_add_f32 v[180:181], v[242:243], v[240:241]
	v_cndmask_b32_e64 v1, v97, v1, s[0:1]
	v_rsq_f32_e32 v1, v1
	v_lshlrev_b32_e32 v166, 16, v54
	v_and_b32_e32 v167, 0xffff0000, v54
	v_pk_mul_f32 v[234:235], v[166:167], v[166:167]
	v_mul_f32_e32 v92, 0x45800000, v1
	v_cndmask_b32_e64 v100, v1, v92, s[0:1]
	v_mov_b32_e32 v1, v96
	v_rsq_f32_e32 v1, v1
	v_pk_mul_f32 v[94:95], v[100:101], v[94:95] op_sel_hi:[0,1]
	v_pk_mul_f32 v[2:3], v[100:101], v[2:3] op_sel_hi:[0,1]
	v_pk_mul_f32 v[92:93], v[100:101], v[102:103] op_sel_hi:[0,1]
	v_pk_mul_f32 v[98:99], v[100:101], v[98:99] op_sel_hi:[0,1]
	v_pk_mul_f32 v[94:95], v[84:85], v[94:95]
	v_pk_mul_f32 v[2:3], v[86:87], v[2:3]
	v_pk_mul_f32 v[92:93], v[88:89], v[92:93]
	v_pk_mul_f32 v[98:99], v[90:91], v[98:99]
	v_cvt_pk_bf16_f32 v94, v94, v95
	v_cvt_pk_bf16_f32 v95, v2, v3
	s_nop 0
	v_cvt_pk_bf16_f32 v92, v92, v93
	v_cvt_pk_bf16_f32 v93, v98, v99
	v_mov_b32_e32 v2, v1
	ds_write_b128 v229, v[92:95] offset:9216
	ds_write_b128 v231, v[16:19] offset:47104
	v_pk_mul_f32 v[92:93], v[2:3], v[156:157] op_sel_hi:[0,1]
	v_lshlrev_b32_e32 v156, 16, v41
	v_and_b32_e32 v157, 0xffff0000, v41
	v_pk_mul_f32 v[158:159], v[156:157], v[156:157]
	v_pk_mul_f32 v[94:95], v[2:3], v[152:153] op_sel_hi:[0,1]
	v_lshlrev_b32_e32 v152, 16, v42
	v_and_b32_e32 v153, 0xffff0000, v42
	v_pk_mov_b32 v[238:239], v[238:239], v[158:159] op_sel:[1,0]
	v_pk_mul_f32 v[92:93], v[88:89], v[92:93]
	v_pk_mul_f32 v[94:95], v[90:91], v[94:95]
	v_pk_mul_f32 v[154:155], v[152:153], v[152:153]
	v_pk_add_f32 v[180:181], v[238:239], v[180:181]
	v_mov_b32_e32 v158, v236
	v_cvt_pk_bf16_f32 v92, v92, v93
	v_cvt_pk_bf16_f32 v93, v94, v95
	v_pk_mul_f32 v[94:95], v[2:3], v[136:137] op_sel_hi:[0,1]
	v_lshlrev_b32_e32 v136, 16, v43
	v_and_b32_e32 v137, 0xffff0000, v43
	v_pk_add_f32 v[158:159], v[158:159], v[180:181]
	v_pk_mov_b32 v[180:181], v[236:237], v[154:155] op_sel:[1,0]
	v_pk_mul_f32 v[150:151], v[136:137], v[136:137]
	v_lshlrev_b32_e32 v164, 16, v55
	v_and_b32_e32 v165, 0xffff0000, v55
	v_pk_add_f32 v[158:159], v[180:181], v[158:159]
	v_mov_b32_e32 v154, v234
	v_pk_mul_f32 v[232:233], v[164:165], v[164:165]
	v_pk_add_f32 v[154:155], v[154:155], v[158:159]
	v_pk_mov_b32 v[158:159], v[234:235], v[150:151] op_sel:[1,0]
	v_mov_b32_e32 v150, v232
	v_pk_add_f32 v[154:155], v[158:159], v[154:155]
	v_pk_mul_f32 v[2:3], v[2:3], v[106:107] op_sel_hi:[0,1]
	v_pk_add_f32 v[150:151], v[150:151], v[154:155]
	s_nop 1
	v_mov_b32_dpp v155, v151 quad_perm:[1,0,3,2] row_mask:0xf bank_mask:0xf
	v_mov_b32_e32 v154, v233
	v_pk_mul_f32 v[94:95], v[84:85], v[94:95]
	v_pk_mul_f32 v[2:3], v[86:87], v[2:3]
	s_ashr_i32 s0, s21, 4
	s_waitcnt lgkmcnt(0)
	v_pk_add_f32 v[150:151], v[154:155], v[150:151]
	s_nop 1
	v_mov_b32_dpp v155, v151 quad_perm:[2,3,0,1] row_mask:0xf bank_mask:0xf
	v_mov_b32_e32 v154, v150
	s_nop 1
	v_permlane16_swap_b32_e32 v154, v150
	s_lshr_b32 s54, s20, s3
	v_cvt_pk_bf16_f32 v94, v94, v95
	v_cvt_pk_bf16_f32 v95, v2, v3
	s_ashr_i32 s1, s0, 31
	s_waitcnt lgkmcnt(0)
	v_pk_add_f32 v[150:151], v[150:151], v[154:155]
	s_nop 1
	v_mov_b32_dpp v155, v151 row_half_mirror row_mask:0xf bank_mask:0xf
	v_mov_b32_e32 v154, v150
	s_nop 1
	v_permlane32_swap_b32_e32 v154, v150
	v_lshl_add_u32 v2, s54, 7, v147
	s_and_b32 s53, s21, 15
	s_lshl_b64 s[20:21], s[0:1], 11
	v_ashrrev_i32_e32 v3, 31, v2
	s_waitcnt lgkmcnt(0)
	v_pk_add_f32 v[150:151], v[150:151], v[154:155]
	s_or_b32 s20, s20, s22
	v_pk_fma_f32 v[180:181], v[150:151], s[26:27], v[134:135] op_sel_hi:[1,0,0]
	v_lshlrev_b64 v[2:3], s3, v[2:3]
	ds_write_b128 v229, v[92:95] offset:18432
	ds_write_b128 v231, v[24:27] offset:57344
	v_mov_b32_e32 v1, v181
	v_rsq_f32_e32 v1, v1
	v_lshl_add_u64 v[96:97], v[114:115], 0, s[24:25]
	s_lshl_b32 s26, s53, 7
	global_load_dwordx4 v[100:103], v[96:97], off offset:16
	global_load_dwordx4 v[104:107], v[96:97], off
	global_load_dwordx4 v[92:95], v[96:97], off offset:144
	s_nop 0
	global_load_dwordx4 v[96:99], v[96:97], off offset:128
	s_nop 0
	v_mov_b32_e32 v134, v1
	v_pk_mul_f32 v[150:151], v[134:135], v[162:163] op_sel_hi:[0,1]
	v_pk_mul_f32 v[88:89], v[88:89], v[150:151]
	v_pk_mul_f32 v[150:151], v[134:135], v[156:157] op_sel_hi:[0,1]
	v_pk_mul_f32 v[90:91], v[90:91], v[150:151]
	v_cvt_pk_bf16_f32 v88, v88, v89
	v_cvt_pk_bf16_f32 v89, v90, v91
	v_pk_mul_f32 v[90:91], v[134:135], v[152:153] op_sel_hi:[0,1]
	v_pk_mul_f32 v[84:85], v[84:85], v[90:91]
	v_cmp_gt_f32_e64 s[0:1], s33, v180
	v_cvt_pk_bf16_f32 v90, v84, v85
	v_pk_mul_f32 v[84:85], v[134:135], v[136:137] op_sel_hi:[0,1]
	v_lshl_add_u64 v[136:137], s[20:21], 0, v[2:3]
	v_lshlrev_b64 v[162:163], 11, v[136:137]
	v_pk_mul_f32 v[84:85], v[86:87], v[84:85]
	v_lshl_add_u64 v[2:3], s[28:29], 0, v[162:163]
	v_cvt_pk_bf16_f32 v91, v84, v85
	v_lshl_add_u64 v[2:3], v[2:3], 0, s[26:27]
	v_lshlrev_b32_e32 v134, 1, v112
	v_mov_b32_e32 v135, v0
	ds_write_b128 v229, v[88:91] offset:27648
	ds_write_b128 v230, v[44:47] offset:57344
	v_lshl_add_u64 v[2:3], v[2:3], 0, v[134:135]
	global_load_dwordx4 v[88:91], v[2:3], off
	global_load_dwordx4 v[84:87], v[2:3], off offset:64
	v_readlane_b32 s20, v252, 59
	s_add_i32 s52, s51, s20
	s_waitcnt lgkmcnt(0)
	s_barrier
; __device__ __forceinline__ void attn_phase(LAS unsigned char* lds, const bf16* PROJ, const bf16* Ygate, bf16* OG0, bf16* OG1, bf16* OG2, float* LSE, const float* qnw, const float* knw, int bx, int G) {
;     ...
;         if (t + 2 * G < 3072) AT_LOAD(t + 2 * G, half);
	s_cmpk_gt_i32 s52, 0xbff
	s_cselect_b64 s[24:25], -1, 0
	s_and_b64 vcc, exec, s[24:25]
	s_cbranch_vccnz .LBB0_279
	s_ashr_i32 s21, s52, 4
	s_mul_hi_i32 s22, s21, 0x55555556
	s_lshr_b32 s23, s22, 31
	s_add_i32 s22, s22, s23
	s_mul_i32 s22, s22, 3
	s_sub_i32 s21, s21, s22
	s_mul_hi_i32 s22, s52, 0x2aaaaaab
	s_lshr_b32 s23, s22, 31
	s_ashr_i32 s22, s22, 3
	s_lshl_b32 s26, s21, 1
	s_and_b32 s20, s52, 15
	s_add_i32 s23, s22, s23
	s_lshl_b32 s30, -1, s26
	s_andn2_b32 s30, s20, s30
	s_lshr_b32 s31, s20, s26
	s_lshl_b32 s20, s23, 6
	s_ashr_i32 s22, s23, 4
	s_mulk_i32 s21, 0xc00
	s_and_b32 s20, s20, 0x3c0
	s_or_b32 s20, s21, s20
	s_ashr_i32 s23, s22, 31
	s_lshl_b64 s[22:23], s[22:23], 11
	s_ashr_i32 s21, s20, 31
	s_lshl_b32 s55, s31, 7
	s_or_b32 s22, s22, s30
	s_lshl_b64 s[30:31], s[20:21], 1
	v_mov_b32_e32 v6, v0
	v_mov_b32_e32 v7, v0
	v_add_u32_e32 v48, s55, v182
	s_add_u32 s38, s34, s30
	v_mov_b32_e32 v4, v0
	v_mov_b32_e32 v5, v0
	v_mov_b64_e32 v[10:11], v[6:7]
	v_mov_b64_e32 v[14:15], v[6:7]
	s_addc_u32 s39, s35, s31
	v_cmp_lt_i32_e32 vcc, -1, v48
	v_mov_b64_e32 v[8:9], v[4:5]
	v_mov_b64_e32 v[12:13], v[4:5]
	s_and_saveexec_b64 s[30:31], vcc
	s_cbranch_execz .LBB0_272
	v_mov_b32_e32 v49, v0
	v_lshlrev_b64 v[2:3], s26, v[48:49]
	v_lshl_add_u64 v[2:3], v[2:3], 0, s[22:23]
	v_mov_b64_e32 v[8:9], s[38:39]
	s_movk_i32 s80, 0x4800
	v_mad_u64_u32 v[8:9], vcc, v2, s80, v[8:9]
	v_mov_b32_e32 v2, v9
	v_mad_u64_u32 v[2:3], vcc, v3, s80, v[2:3]
	v_mov_b32_e32 v9, v2
	v_lshlrev_b32_e32 v2, 1, v108
	v_mov_b32_e32 v3, v0
	v_lshl_add_u64 v[2:3], v[8:9], 0, v[2:3]
	v_add_co_u32_e32 v12, vcc, 0x1000, v2
	s_nop 1
	v_addc_co_u32_e32 v13, vcc, 0, v3, vcc
	global_load_dwordx4 v[8:11], v[2:3], off offset:2048
	s_nop 0
	global_load_dwordx4 v[12:15], v[12:13], off

; #define LAS __attribute__((address_space(3)))
; __device__ __forceinline__ float bflo(unsigned u) { return __uint_as_float(u << 16); }
; __device__ __forceinline__ void attn_phase(LAS unsigned char* lds, const bf16* PROJ, const bf16* Ygate, bf16* OG0, bf16* OG1, bf16* OG2, float* LSE, const float* qnw, const float* knw, int bx, int G) {
;     ...
;         const int sub = t & 15, gi = (t >> 4) % 3, bh = t / 48, h = bh & 15, bl = bh >> 4;
;         const int sh = 2 * gi, d = 1 << sh, r = sub & (d - 1), n = sub >> sh;
;         const float ad = exp2f(-8.f * (float)(gi * 16 + h + 1) / 48.f) * (float)d;
;         bf16* OG = gi == 0 ? OG0 : (gi == 1 ? OG1 : OG2);
;         {
;             const f32x4 kw0 = *(const f32x4*)(knw + gi * 64 + 8 * oct), kw1 = *(const f32x4*)(knw + gi * 64 + 8 * oct + 4);
; #pragma unroll
;             for (int jj = 0; jj < 4; ++jj) {
;                 const int key = (tid >> 3) + 64 * jj; const v4u kq = kr[half][jj];
;                 float kf[8] = {bflo(kq.x), bfhi(kq.x), bflo(kq.y), bfhi(kq.y), bflo(kq.z), bfhi(kq.z), bflo(kq.w), bfhi(kq.w)};
;                 float ss = 0.f;
; #pragma unroll
;                 for (int e = 0; e < 8; ++e) ss += kf[e] * kf[e];
;                 ss += __shfl_xor(ss, 1); ss += __shfl_xor(ss, 2); ss += __shfl_xor(ss, 4);
;                 const float rs = rsqrtf(ss * (1.f / 64.f) + EPS);
;                 v4u ko; ko.x = pk2(kf[0] * rs * kw0[0], kf[1] * rs * kw0[1]); ko.y = pk2(kf[2] * rs * kw0[2], kf[3] * rs * kw0[3]);
;                 ko.z = pk2(kf[4] * rs * kw1[0], kf[5] * rs * kw1[1]); ko.w = pk2(kf[6] * rs * kw1[2], kf[7] * rs * kw1[3]);
;                 *(LAS v4u*)(Ks + key * 72 + 8 * oct) = ko;
;                 *(LAS v4u*)(Vs + key * 80 + 8 * oct) = vr[half][jj];
;             }
;         }
;         const int qi = 16 * w + l16;
;         const size_t qrow = (size_t)bl * SEQL + (size_t)(128 * n + qi) * d + r;
;         bf16x8 qreg[2];
;         {
;             float qf[2][8]; float ss = 0.f;
; #pragma unroll
;             for (int ks = 0; ks < 2; ++ks) {
;                 const v4u qq = qr[half][ks];
;                 qf[ks][0] = bflo(qq.x); qf[ks][1] = bfhi(qq.x); qf[ks][2] = bflo(qq.y); qf[ks][3] = bfhi(qq.y); qf[ks][4] = bflo(qq.z); qf[ks][5] = bfhi(qq.z); qf[ks][6] = bflo(qq.w); qf[ks][7] = bfhi(qq.w);
; #pragma unroll
;                 for (int e = 0; e < 8; ++e) ss += qf[ks][e] * qf[ks][e];
.LBB0_308:
	s_or_b64 exec, exec, s[0:1]
	s_waitcnt lgkmcnt(0)
	s_barrier
	s_add_i32 s0, s84, s51
	s_cmpk_gt_i32 s0, 0xbff
	s_cbranch_scc1 .LBB0_268
	s_ashr_i32 s1, s0, 4
	s_mul_hi_i32 s2, s1, 0x55555556
	s_lshr_b32 s3, s2, 31
	s_add_i32 s2, s2, s3
	s_mul_i32 s2, s2, 3
	s_sub_i32 s2, s1, s2
	s_and_b32 s22, s0, 15
	s_mul_hi_i32 s0, s0, 0x2aaaaaab
	s_lshl_b32 s3, s2, 1
	s_lshr_b32 s1, s0, 31
	s_ashr_i32 s23, s0, 3
	s_bfm_b32 s0, s3, 0
	s_and_b32 s26, s0, s22
	s_lshl_b32 s0, s2, 6
	s_add_i32 s23, s23, s1
	s_ashr_i32 s1, s0, 31
	s_lshl_b64 s[20:21], s[0:1], 2
	v_lshl_add_u64 v[2:3], v[110:111], 0, s[20:21]
	global_load_dwordx4 v[84:87], v[2:3], off offset:16
	global_load_dwordx4 v[88:91], v[2:3], off
	v_lshlrev_b32_e32 v102, 16, v32
	v_and_b32_e32 v103, 0xffff0000, v32
	v_lshlrev_b32_e32 v98, 16, v33
	v_and_b32_e32 v99, 0xffff0000, v33
	v_pk_mul_f32 v[104:105], v[102:103], v[102:103]
	v_pk_mul_f32 v[100:101], v[98:99], v[98:99]
	v_add_f32_e32 v1, v104, v105
	v_lshlrev_b32_e32 v94, 16, v34
	v_and_b32_e32 v95, 0xffff0000, v34
	v_add_f32_e32 v1, v100, v1
	v_pk_mul_f32 v[96:97], v[94:95], v[94:95]
	v_add_f32_e32 v1, v101, v1
	v_lshlrev_b32_e32 v2, 16, v35
	v_and_b32_e32 v3, 0xffff0000, v35
	v_add_f32_e32 v1, v96, v1
	v_pk_mul_f32 v[92:93], v[2:3], v[2:3]
	v_add_f32_e32 v1, v97, v1
	v_add_f32_e32 v1, v92, v1
	v_add_f32_e32 v1, v93, v1
	s_nop 1
	v_mov_b32_dpp v92, v1 quad_perm:[1,0,3,2] row_mask:0xf bank_mask:0xf
	v_lshlrev_b32_e32 v158, 16, v60
	v_and_b32_e32 v159, 0xffff0000, v60
	v_lshlrev_b32_e32 v154, 16, v61
	v_and_b32_e32 v155, 0xffff0000, v61
	s_waitcnt lgkmcnt(0)
	v_add_f32_e32 v1, v1, v92
	s_nop 1
	v_mov_b32_dpp v92, v1 quad_perm:[2,3,0,1] row_mask:0xf bank_mask:0xf
	v_pk_mul_f32 v[162:163], v[158:159], v[158:159]
	v_pk_mul_f32 v[156:157], v[154:155], v[154:155]
	v_mov_b32_e32 v164, v162
	v_lshlrev_b32_e32 v150, 16, v62
	s_waitcnt lgkmcnt(0)
	v_add_f32_e32 v1, v1, v92
	s_nop 1
	v_mov_b32_dpp v92, v1 row_half_mirror row_mask:0xf bank_mask:0xf
	v_and_b32_e32 v151, 0xffff0000, v62
	v_mov_b32_e32 v162, v156
	v_pk_mul_f32 v[152:153], v[150:151], v[150:151]
	v_lshlrev_b32_e32 v106, 16, v63
	s_waitcnt lgkmcnt(0)
	v_add_f32_e32 v1, v1, v92
	v_fmamk_f32 v1, v1, 0x3c800000, v139
	v_and_b32_e32 v107, 0xffff0000, v63
	v_rsq_f32_e32 v1, v1
	v_pk_mul_f32 v[136:137], v[106:107], v[106:107]
	s_mov_b32 s0, 0x358637bd
	s_mov_b32 s38, 0x3c800000
	s_nop 0
	v_mov_b32_e32 v96, v1
	v_pk_mul_f32 v[92:93], v[96:97], v[102:103] op_sel_hi:[0,1]
	v_pk_mul_f32 v[98:99], v[96:97], v[98:99] op_sel_hi:[0,1]
	v_pk_mul_f32 v[94:95], v[96:97], v[94:95] op_sel_hi:[0,1]
	v_pk_mul_f32 v[2:3], v[96:97], v[2:3] op_sel_hi:[0,1]
	v_lshlrev_b32_e32 v102, 16, v28
	v_and_b32_e32 v103, 0xffff0000, v28
	v_pk_mul_f32 v[104:105], v[102:103], v[102:103]
	v_and_b32_e32 v179, 0xffff0000, v76
	v_mov_b32_e32 v165, v104
	v_mov_b32_e32 v104, v163
	v_pk_add_f32 v[104:105], v[164:165], v[104:105]
	v_lshlrev_b32_e32 v178, 16, v76
	v_mul_f32_e32 v242, v179, v179
	v_lshlrev_b32_e32 v176, 16, v77
	v_and_b32_e32 v177, 0xffff0000, v77
	v_pk_fma_f32 v[242:243], v[178:179], v[178:179], v[242:243] op_sel_hi:[1,1,0]
	v_mul_f32_e32 v244, v177, v177
	v_pk_fma_f32 v[242:243], v[176:177], v[176:177], v[242:243]
	v_lshlrev_b32_e32 v174, 16, v78
	v_and_b32_e32 v175, 0xffff0000, v78
	v_pk_add_f32 v[242:243], v[244:245], v[242:243] op_sel_hi:[0,1]
	v_pk_fma_f32 v[242:243], v[174:175], v[174:175], v[242:243]
	v_mul_f32_e32 v244, v175, v175
	v_lshlrev_b32_e32 v172, 16, v79
	v_and_b32_e32 v173, 0xffff0000, v79
	v_pk_add_f32 v[242:243], v[244:245], v[242:243] op_sel_hi:[0,1]
	v_lshlrev_b32_e32 v232, 16, v68
	v_and_b32_e32 v233, 0xffff0000, v68
	v_lshlrev_b32_e32 v170, 16, v80
	v_and_b32_e32 v171, 0xffff0000, v80
	s_waitcnt vmcnt(1)
	v_pk_mul_f32 v[94:95], v[84:85], v[94:95]
	s_waitcnt vmcnt(0)
	v_pk_mul_f32 v[92:93], v[88:89], v[92:93]
	v_pk_mul_f32 v[98:99], v[90:91], v[98:99]
	v_cvt_pk_bf16_f32 v92, v92, v93
	v_cvt_pk_bf16_f32 v93, v98, v99
	v_pk_mul_f32 v[2:3], v[86:87], v[2:3]
	v_lshlrev_b32_e32 v98, 16, v29
	v_and_b32_e32 v99, 0xffff0000, v29
	v_cvt_pk_bf16_f32 v94, v94, v95
	v_cvt_pk_bf16_f32 v95, v2, v3
	v_pk_mul_f32 v[100:101], v[98:99], v[98:99]
	ds_write_b128 v229, v[92:95]
	ds_write_b128 v231, v[36:39] offset:36864
	v_lshlrev_b32_e32 v94, 16, v30
	v_and_b32_e32 v95, 0xffff0000, v30
	v_mov_b32_e32 v163, v100
	v_pk_mul_f32 v[96:97], v[94:95], v[94:95]
	v_pk_add_f32 v[104:105], v[162:163], v[104:105]
	v_mov_b32_e32 v100, v157
	v_lshlrev_b32_e32 v2, 16, v31
	v_and_b32_e32 v3, 0xffff0000, v31
	v_pk_add_f32 v[100:101], v[100:101], v[104:105]
	v_mov_b32_e32 v104, v152
	v_mov_b32_e32 v105, v96
	v_pk_mul_f32 v[92:93], v[2:3], v[2:3]
	v_pk_add_f32 v[100:101], v[104:105], v[100:101]
	v_mov_b32_e32 v96, v153
	v_pk_add_f32 v[96:97], v[96:97], v[100:101]
	v_mov_b32_e32 v100, v136
	v_mov_b32_e32 v101, v92
	v_pk_add_f32 v[96:97], v[100:101], v[96:97]
	v_mov_b32_e32 v92, v137
	v_pk_add_f32 v[92:93], v[92:93], v[96:97]
	s_nop 1
	v_mov_b32_dpp v97, v93 quad_perm:[1,0,3,2] row_mask:0xf bank_mask:0xf
	s_nop 1
	v_mov_b32_dpp v96, v92 quad_perm:[1,0,3,2] row_mask:0xf bank_mask:0xf
	v_mov_b64_e32 v[136:137], s[0:1]
	v_pk_fma_f32 v[242:243], v[172:173], v[172:173], v[242:243]
	v_mul_f32_e32 v244, v173, v173
	v_pk_mul_f32 v[180:181], v[232:233], v[232:233]
	s_waitcnt lgkmcnt(0)
	v_pk_add_f32 v[92:93], v[92:93], v[96:97]
	s_nop 1
	v_mov_b32_dpp v97, v93 quad_perm:[2,3,0,1] row_mask:0xf bank_mask:0xf
	s_nop 1
	v_mov_b32_dpp v96, v92 quad_perm:[2,3,0,1] row_mask:0xf bank_mask:0xf
	v_pk_mul_f32 v[240:241], v[170:171], v[170:171]
	v_pk_add_f32 v[242:243], v[244:245], v[242:243] op_sel_hi:[0,1]
	v_lshlrev_b32_e32 v168, 16, v81
	v_and_b32_e32 v169, 0xffff0000, v81
	s_waitcnt lgkmcnt(0)
; #define LAS __attribute__((address_space(3)))
; __device__ __forceinline__ void attn_phase(LAS unsigned char* lds, const bf16* PROJ, const bf16* Ygate, bf16* OG0, bf16* OG1, bf16* OG2, float* LSE, const float* qnw, const float* knw, int bx, int G) {
;     ...
;             for (int jj = 0; jj < 4; ++jj) {
;                 const int key = (tid >> 3) + 64 * jj; const v4u kq = kr[half][jj];
;                 float kf[8] = {bflo(kq.x), bfhi(kq.x), bflo(kq.y), bfhi(kq.y), bflo(kq.z), bfhi(kq.z), bflo(kq.w), bfhi(kq.w)};
;                 float ss = 0.f;
; #pragma unroll
;                 for (int e = 0; e < 8; ++e) ss += kf[e] * kf[e];
;                 ss += __shfl_xor(ss, 1); ss += __shfl_xor(ss, 2); ss += __shfl_xor(ss, 4);
;                 const float rs = rsqrtf(ss * (1.f / 64.f) + EPS);
;                 v4u ko; ko.x = pk2(kf[0] * rs * kw0[0], kf[1] * rs * kw0[1]); ko.y = pk2(kf[2] * rs * kw0[2], kf[3] * rs * kw0[3]);
;                 ko.z = pk2(kf[4] * rs * kw1[0], kf[5] * rs * kw1[1]); ko.w = pk2(kf[6] * rs * kw1[2], kf[7] * rs * kw1[3]);
;                 *(LAS v4u*)(Ks + key * 72 + 8 * oct) = ko;
;                 *(LAS v4u*)(Vs + key * 80 + 8 * oct) = vr[half][jj];
;             }
;         }
;         const int qi = 16 * w + l16;
;         const size_t qrow = (size_t)bl * SEQL + (size_t)(128 * n + qi) * d + r;
;         bf16x8 qreg[2];
;         {
;             float qf[2][8]; float ss = 0.f;
; #pragma unroll
;             for (int ks = 0; ks < 2; ++ks) {
;                 const v4u qq = qr[half][ks];
;                 qf[ks][0] = bflo(qq.x); qf[ks][1] = bfhi(qq.x); qf[ks][2] = bflo(qq.y); qf[ks][3] = bfhi(qq.y); qf[ks][4] = bflo(qq.z); qf[ks][5] = bfhi(qq.z); qf[ks][6] = bflo(qq.w); qf[ks][7] = bfhi(qq.w);
; #pragma unroll
;                 for (int e = 0; e < 8; ++e) ss += qf[ks][e] * qf[ks][e];
;             }
;             ss += __shfl_xor(ss, 16); ss += __shfl_xor(ss, 32);
;             const float rs = rsqrtf(ss * (1.f / 64.f) + EPS) * 0.125f;
; #pragma unroll
;             for (int ks = 0; ks < 2; ++ks) {
;                 const f32x4 w0 = *(const f32x4*)(qnw + gi * 64 + 32 * ks + 8 * g4), w1 = *(const f32x4*)(qnw + gi * 64 + 32 * ks + 8 * g4 + 4);
;                 v4u tq; tq.x = pk2(qf[ks][0] * rs * w0[0], qf[ks][1] * rs * w0[1]); tq.y = pk2(qf[ks][2] * rs * w0[2], qf[ks][3] * rs * w0[3]);
	v_pk_add_f32 v[92:93], v[92:93], v[96:97]
	s_nop 1
	v_mov_b32_dpp v97, v93 row_half_mirror row_mask:0xf bank_mask:0xf
	s_nop 1
	v_mov_b32_dpp v96, v92 row_half_mirror row_mask:0xf bank_mask:0xf
	v_mov_b32_e32 v244, v240
	v_mov_b32_e32 v245, v180
	v_mov_b32_e32 v243, v181
	v_pk_mul_f32 v[238:239], v[168:169], v[168:169]
	s_waitcnt lgkmcnt(0)
	v_pk_add_f32 v[92:93], v[92:93], v[96:97]
	v_pk_add_f32 v[180:181], v[244:245], v[242:243]
	v_pk_fma_f32 v[96:97], v[92:93], s[38:39], v[136:137] op_sel_hi:[1,0,0]
	v_lshlrev_b32_e32 v166, 16, v82
	v_mul_f32_e32 v1, 0x4b800000, v97
	v_cmp_gt_f32_e64 s[0:1], s33, v97
	v_and_b32_e32 v167, 0xffff0000, v82
	v_cndmask_b32_e64 v1, v97, v1, s[0:1]
	v_rsq_f32_e32 v1, v1
	v_pk_mul_f32 v[236:237], v[166:167], v[166:167]
	v_lshlrev_b32_e32 v164, 16, v83
	v_and_b32_e32 v165, 0xffff0000, v83
	v_mul_f32_e32 v92, 0x45800000, v1
	v_cndmask_b32_e64 v100, v1, v92, s[0:1]
	v_mov_b32_e32 v1, v96
	v_rsq_f32_e32 v1, v1
	v_pk_mul_f32 v[94:95], v[100:101], v[94:95] op_sel_hi:[0,1]
	v_pk_mul_f32 v[2:3], v[100:101], v[2:3] op_sel_hi:[0,1]
	v_pk_mul_f32 v[92:93], v[100:101], v[102:103] op_sel_hi:[0,1]
	v_pk_mul_f32 v[98:99], v[100:101], v[98:99] op_sel_hi:[0,1]
	v_pk_mul_f32 v[94:95], v[84:85], v[94:95]
	v_pk_mul_f32 v[2:3], v[86:87], v[2:3]
	v_pk_mul_f32 v[92:93], v[88:89], v[92:93]
	v_pk_mul_f32 v[98:99], v[90:91], v[98:99]
	v_cvt_pk_bf16_f32 v94, v94, v95
	v_cvt_pk_bf16_f32 v95, v2, v3
	s_nop 0
	v_cvt_pk_bf16_f32 v92, v92, v93
	v_cvt_pk_bf16_f32 v93, v98, v99
	v_mov_b32_e32 v2, v1
	ds_write_b128 v229, v[92:95] offset:9216
	ds_write_b128 v231, v[56:59] offset:47104
	v_pk_mul_f32 v[92:93], v[2:3], v[158:159] op_sel_hi:[0,1]
	v_lshlrev_b32_e32 v158, 16, v69
	v_and_b32_e32 v159, 0xffff0000, v69
	v_pk_mul_f32 v[162:163], v[158:159], v[158:159]
	v_pk_mul_f32 v[94:95], v[2:3], v[154:155] op_sel_hi:[0,1]
	v_lshlrev_b32_e32 v154, 16, v70
	v_and_b32_e32 v155, 0xffff0000, v70
	v_pk_mov_b32 v[240:241], v[240:241], v[162:163] op_sel:[1,0]
	v_pk_mul_f32 v[92:93], v[88:89], v[92:93]
	v_pk_mul_f32 v[94:95], v[90:91], v[94:95]
	v_pk_mul_f32 v[156:157], v[154:155], v[154:155]
	v_pk_add_f32 v[180:181], v[240:241], v[180:181]
	v_mov_b32_e32 v162, v238
	v_cvt_pk_bf16_f32 v92, v92, v93
	v_cvt_pk_bf16_f32 v93, v94, v95
	v_pk_mul_f32 v[94:95], v[2:3], v[150:151] op_sel_hi:[0,1]
	v_lshlrev_b32_e32 v150, 16, v71
	v_and_b32_e32 v151, 0xffff0000, v71
	v_pk_add_f32 v[162:163], v[162:163], v[180:181]
	v_pk_mov_b32 v[180:181], v[238:239], v[156:157] op_sel:[1,0]
	v_pk_mul_f32 v[152:153], v[150:151], v[150:151]
	v_pk_add_f32 v[162:163], v[180:181], v[162:163]
	v_mov_b32_e32 v156, v236
	v_pk_mul_f32 v[234:235], v[164:165], v[164:165]
	v_pk_add_f32 v[156:157], v[156:157], v[162:163]
	v_pk_mov_b32 v[162:163], v[236:237], v[152:153] op_sel:[1,0]
	v_mov_b32_e32 v152, v234
	v_pk_add_f32 v[156:157], v[162:163], v[156:157]
	v_pk_mul_f32 v[2:3], v[2:3], v[106:107] op_sel_hi:[0,1]
	v_pk_add_f32 v[152:153], v[152:153], v[156:157]
	s_nop 1
	v_mov_b32_dpp v157, v153 quad_perm:[1,0,3,2] row_mask:0xf bank_mask:0xf
	v_mov_b32_e32 v156, v235
	v_pk_mul_f32 v[94:95], v[84:85], v[94:95]
	v_pk_mul_f32 v[2:3], v[86:87], v[2:3]
	s_ashr_i32 s0, s23, 4
	s_waitcnt lgkmcnt(0)
	v_pk_add_f32 v[152:153], v[156:157], v[152:153]
	s_nop 1
	v_mov_b32_dpp v157, v153 quad_perm:[2,3,0,1] row_mask:0xf bank_mask:0xf
	v_mov_b32_e32 v156, v152
	s_nop 1
	v_permlane16_swap_b32_e32 v156, v152
	s_lshr_b32 s54, s22, s3
	v_cvt_pk_bf16_f32 v94, v94, v95
	v_cvt_pk_bf16_f32 v95, v2, v3
	s_ashr_i32 s1, s0, 31
	s_waitcnt lgkmcnt(0)
	v_pk_add_f32 v[152:153], v[152:153], v[156:157]
	s_nop 1
	v_mov_b32_dpp v157, v153 row_half_mirror row_mask:0xf bank_mask:0xf
	v_mov_b32_e32 v156, v152
	s_nop 1
	v_permlane32_swap_b32_e32 v156, v152
	v_lshl_add_u32 v2, s54, 7, v147
	s_and_b32 s53, s23, 15
	s_lshl_b64 s[22:23], s[0:1], 11
	v_ashrrev_i32_e32 v3, 31, v2
	s_waitcnt lgkmcnt(0)
	v_pk_add_f32 v[152:153], v[152:153], v[156:157]
	s_or_b32 s22, s22, s26
	v_pk_fma_f32 v[180:181], v[152:153], s[38:39], v[136:137] op_sel_hi:[1,0,0]
	v_lshlrev_b64 v[2:3], s3, v[2:3]
	ds_write_b128 v229, v[92:95] offset:18432
	ds_write_b128 v231, v[64:67] offset:57344
	v_mov_b32_e32 v1, v181
	v_rsq_f32_e32 v1, v1
	v_lshl_add_u64 v[96:97], v[114:115], 0, s[20:21]
	s_lshl_b32 s26, s53, 7
	global_load_dwordx4 v[100:103], v[96:97], off offset:16
	global_load_dwordx4 v[104:107], v[96:97], off
	global_load_dwordx4 v[92:95], v[96:97], off offset:144
	s_nop 0
	global_load_dwordx4 v[96:99], v[96:97], off offset:128
	s_nop 0
	v_mov_b32_e32 v136, v1
	v_pk_mul_f32 v[152:153], v[136:137], v[232:233] op_sel_hi:[0,1]
	v_pk_mul_f32 v[88:89], v[88:89], v[152:153]
	v_pk_mul_f32 v[152:153], v[136:137], v[158:159] op_sel_hi:[0,1]
	v_pk_mul_f32 v[90:91], v[90:91], v[152:153]
	v_cvt_pk_bf16_f32 v88, v88, v89
	v_cvt_pk_bf16_f32 v89, v90, v91
	v_pk_mul_f32 v[90:91], v[136:137], v[154:155] op_sel_hi:[0,1]
	v_pk_mul_f32 v[84:85], v[84:85], v[90:91]
	v_mov_b32_e32 v135, v0
	v_cvt_pk_bf16_f32 v90, v84, v85
	v_pk_mul_f32 v[84:85], v[136:137], v[150:151] op_sel_hi:[0,1]
	v_lshl_add_u64 v[136:137], s[22:23], 0, v[2:3]
	v_lshlrev_b64 v[162:163], 11, v[136:137]
	v_pk_mul_f32 v[84:85], v[86:87], v[84:85]
	v_lshl_add_u64 v[2:3], s[28:29], 0, v[162:163]
	v_cvt_pk_bf16_f32 v91, v84, v85
	v_lshl_add_u64 v[2:3], v[2:3], 0, s[26:27]
	ds_write_b128 v229, v[88:91] offset:27648
	ds_write_b128 v230, v[72:75] offset:57344
	v_lshl_add_u64 v[2:3], v[2:3], 0, v[134:135]
	global_load_dwordx4 v[88:91], v[2:3], off
	global_load_dwordx4 v[84:87], v[2:3], off offset:64
	s_waitcnt lgkmcnt(0)
	s_barrier
; __device__ __forceinline__ void attn_phase(LAS unsigned char* lds, const bf16* PROJ, const bf16* Ygate, bf16* OG0, bf16* OG1, bf16* OG2, float* LSE, const float* qnw, const float* knw, int bx, int G) {
;     ...
;         if (t + 2 * G < 3072) AT_LOAD(t + 2 * G, half);
	s_mul_i32 s20, s84, 3
	s_add_i32 s20, s20, s51
	v_cmp_gt_f32_e64 s[0:1], s33, v180
	s_cmpk_gt_i32 s20, 0xbff
	s_cbranch_scc1 .LBB0_319
	s_ashr_i32 s22, s20, 4
	s_mul_hi_i32 s23, s22, 0x55555556
	s_lshr_b32 s26, s23, 31
	s_add_i32 s23, s23, s26
	s_and_b32 s21, s20, 15
	s_mul_i32 s23, s23, 3
	s_mul_hi_i32 s20, s20, 0x2aaaaaab
	s_sub_i32 s23, s22, s23
	s_lshr_b32 s22, s20, 31
	s_ashr_i32 s20, s20, 3
	s_add_i32 s20, s20, s22
	s_ashr_i32 s22, s20, 4
	s_lshl_b32 s26, s23, 1
	s_lshl_b32 s20, s20, 6
	s_lshl_b32 s30, -1, s26
	s_mulk_i32 s23, 0xc00
	s_and_b32 s20, s20, 0x3c0
	s_andn2_b32 s30, s21, s30
	s_lshr_b32 s21, s21, s26
	s_or_b32 s20, s23, s20
	s_ashr_i32 s23, s22, 31
	s_lshl_b32 s51, s21, 7
	s_lshl_b64 s[22:23], s[22:23], 11
	s_ashr_i32 s21, s20, 31
	s_or_b32 s22, s22, s30
	s_lshl_b64 s[30:31], s[20:21], 1
	v_mov_b32_e32 v30, v0
	v_mov_b32_e32 v31, v0
	v_add_u32_e32 v76, s51, v182
	s_add_u32 s38, s34, s30
	v_mov_b32_e32 v28, v0
	v_mov_b32_e32 v29, v0
	v_mov_b64_e32 v[34:35], v[30:31]
	v_mov_b64_e32 v[38:39], v[30:31]
	s_addc_u32 s39, s35, s31
	v_cmp_lt_i32_e32 vcc, -1, v76
	v_lshlrev_b32_e32 v78, 1, v108
	v_mov_b64_e32 v[32:33], v[28:29]
	v_mov_b64_e32 v[36:37], v[28:29]
	s_and_saveexec_b64 s[30:31], vcc
	s_cbranch_execz .LBB0_312
	v_mov_b32_e32 v77, v0
	v_lshlrev_b64 v[2:3], s26, v[76:77]
	v_lshl_add_u64 v[2:3], v[2:3], 0, s[22:23]
	v_mov_b64_e32 v[32:33], s[38:39]
	s_movk_i32 s55, 0x4800
	v_mad_u64_u32 v[32:33], vcc, v2, s55, v[32:33]
	v_mov_b32_e32 v2, v33
	v_mad_u64_u32 v[2:3], vcc, v3, s55, v[2:3]
	v_mov_b32_e32 v33, v2
	v_mov_b32_e32 v79, v0
	v_lshl_add_u64 v[2:3], v[32:33], 0, v[78:79]
	v_add_co_u32_e32 v36, vcc, 0x1000, v2
	s_nop 1
	v_addc_co_u32_e32 v37, vcc, 0, v3, vcc
	global_load_dwordx4 v[32:35], v[2:3], off offset:2048
	s_nop 0
	global_load_dwordx4 v[36:39], v[36:37], off

; __device__ __forceinline__ float silu_f(float x) { return x * __builtin_amdgcn_rcpf(1.f + __expf(-x)); }
; __device__ __forceinline__ v4u pack8(const float (&y)[8]) { return (v4u){pk2(y[0], y[1]), pk2(y[2], y[3]), pk2(y[4], y[5]), pk2(y[6], y[7])}; }
;     __device__ __forceinline__ void operator()(const f32x4 (&acc)[2][2][4][2], const pg8::Unit& u, int wr, int wc, int fr, int fq) const {
;     ...
;                 for (int m = 0; m < 4; ++m) rs[ai][m] = rsqrtf(ssq[lrow0 + ai * 128 + m * 16] * (1.f / 1024.f) + EPS);
; #pragma unroll
;             for (int bj = 0; bj < 2; ++bj) {
;                 const int c = c0 + bj * 128;
;                 float lb[8] = {0.f, 0.f, 0.f, 0.f, 0.f, 0.f, 0.f, 0.f};
;                 if (region == 1 && idx != 0) {
;                     const f32x4 a00 = *(const f32x4*)(lbsrc + c), a01 = *(const f32x4*)(lbsrc + c + 4), a10 = *(const f32x4*)(lbsrc + 1024 + c), a11 = *(const f32x4*)(lbsrc + 1024 + c + 4);
; #pragma unroll
;                     for (int j = 0; j < 4; ++j) { lb[j] = __builtin_amdgcn_rcpf(1.f + __expf(a00[j] - a10[j])); lb[4 + j] = __builtin_amdgcn_rcpf(1.f + __expf(a01[j] - a11[j])); }
;                 }
; #pragma unroll
;                 for (int ai = 0; ai < 2; ++ai)
; #pragma unroll
;                     for (int m = 0; m < 4; ++m) {
;                         const int row = lrow0 + ai * 128 + m * 16; const size_t off = (size_t)row * 1024 + c;
;                         const f32x4 v0 = acc[ai][bj][m][0] * rs[ai][m], v1 = acc[ai][bj][m][1] * rs[ai][m];
;                         const float v[8] = {v0[0], v0[1], v0[2], v0[3], v1[0], v1[1], v1[2], v1[3]};
;                         float y[8];
;                         if (region == 0) {
; #pragma unroll
;                             for (int j = 0; j < 8; ++j) y[j] = silu_f(v[j]);
;                             *(v4u*)(o0 + off) = pack8(y);
.LBB0_547:
	v_lshl_add_u32 v166, s20, 8, v147
	v_readlane_b32 s20, v252, 60
	v_ashrrev_i32_e32 v167, 31, v166
	v_readlane_b32 s21, v252, 61
	s_cmp_gt_u32 s31, 3
	s_cselect_b64 s[2:3], -1, 0
	v_lshl_add_u64 v[168:169], v[166:167], 2, s[20:21]
	global_load_dword v196, v[168:169], off offset:64
	global_load_dword v197, v[168:169], off offset:128
	global_load_dword v198, v[168:169], off offset:192
	global_load_dword v199, v[168:169], off offset:512
	global_load_dword v200, v[168:169], off offset:576
	global_load_dword v201, v[168:169], off offset:640
	global_load_dword v202, v[168:169], off offset:704
	global_load_dword v1, v[168:169], off
	s_and_b32 s9, s31, -4
	s_cmp_eq_u32 s9, 4
	s_cselect_b64 s[0:1], -1, 0
	s_cmp_lg_u32 s9, 4
	s_cselect_b64 s[18:19], -1, 0
	s_mov_b64 s[20:21], -1
	s_waitcnt vmcnt(0)
	v_fmamk_f32 v1, v1, 0x3a800000, v139
	s_nop 0
	v_rsq_f32_e32 v1, v1
	s_nop 0
	s_nop 0
	v_mov_b32_e32 v170, v1
	v_cndmask_b32_e64 v1, 0, 1, s[18:19]
	v_pk_mul_f32 v[128:129], v[128:129], v[170:171] op_sel_hi:[1,0]
	v_pk_mul_f32 v[172:173], v[126:127], v[170:171] op_sel_hi:[1,0]
	v_pk_mul_f32 v[126:127], v[124:125], v[170:171] op_sel_hi:[1,0]
	v_pk_mul_f32 v[122:123], v[122:123], v[170:171] op_sel_hi:[1,0]
	s_and_b64 vcc, exec, s[2:3]
	v_cmp_ne_u32_e64 s[46:47], 1, v1
	s_cbranch_vccz .LBB0_552
	s_and_b64 vcc, exec, s[46:47]
	s_mov_b64 s[18:19], -1
	s_cbranch_vccnz .LBB0_550
	v_mul_f32_e32 v1, 0xbfb8aa3b, v172
	v_exp_f32_e32 v1, v1
	v_mul_f32_e32 v124, 0xbfb8aa3b, v173
	v_exp_f32_e32 v124, v124
	v_mul_f32_e32 v150, 0xbfb8aa3b, v129
	v_add_f32_e32 v1, 1.0, v1
	v_exp_f32_e32 v151, v150
	v_add_f32_e32 v125, 1.0, v124
	v_rcp_f32_e32 v124, v1
	v_mul_f32_e32 v1, 0xbfb8aa3b, v128
	v_exp_f32_e32 v1, v1
	v_rcp_f32_e32 v125, v125
	s_mov_b64 s[18:19], 0
	v_add_f32_e32 v1, 1.0, v1
	v_rcp_f32_e32 v150, v1
	v_add_f32_e32 v1, 1.0, v151
	v_mul_f32_e32 v151, 0xbfb8aa3b, v122
	v_exp_f32_e32 v152, v151
	v_mul_f32_e32 v151, 0xbfb8aa3b, v123
	v_exp_f32_e32 v153, v151
	v_rcp_f32_e32 v151, v1
	v_add_f32_e32 v1, 1.0, v152
	v_rcp_f32_e32 v152, v1
	v_add_f32_e32 v1, 1.0, v153
	v_mul_f32_e32 v153, 0xbfb8aa3b, v126
	v_exp_f32_e32 v154, v153
	v_mul_f32_e32 v153, 0xbfb8aa3b, v127
	v_exp_f32_e32 v155, v153
	v_rcp_f32_e32 v153, v1
	v_add_f32_e32 v1, 1.0, v154
	v_rcp_f32_e32 v154, v1
	v_add_f32_e32 v1, 1.0, v155
	v_rcp_f32_e32 v155, v1
	v_pk_mul_f32 v[174:175], v[172:173], v[124:125]
	v_pk_mul_f32 v[176:177], v[128:129], v[150:151]
	v_pk_mul_f32 v[178:179], v[122:123], v[152:153]
	v_pk_mul_f32 v[180:181], v[126:127], v[154:155]

; __device__ __forceinline__ float silu_f(float x) { return x * __builtin_amdgcn_rcpf(1.f + __expf(-x)); }
;     __device__ __forceinline__ void operator()(const f32x4 (&acc)[2][2][4][2], const pg8::Unit& u, int wr, int wc, int fr, int fq) const {
;     ...
;                 for (int m = 0; m < 4; ++m) rs[ai][m] = rsqrtf(ssq[lrow0 + ai * 128 + m * 16] * (1.f / 1024.f) + EPS);
; #pragma unroll
;             for (int bj = 0; bj < 2; ++bj) {
;                 const int c = c0 + bj * 128;
;                 float lb[8] = {0.f, 0.f, 0.f, 0.f, 0.f, 0.f, 0.f, 0.f};
;                 if (region == 1 && idx != 0) {
;                     const f32x4 a00 = *(const f32x4*)(lbsrc + c), a01 = *(const f32x4*)(lbsrc + c + 4), a10 = *(const f32x4*)(lbsrc + 1024 + c), a11 = *(const f32x4*)(lbsrc + 1024 + c + 4);
; #pragma unroll
;                     for (int j = 0; j < 4; ++j) { lb[j] = __builtin_amdgcn_rcpf(1.f + __expf(a00[j] - a10[j])); lb[4 + j] = __builtin_amdgcn_rcpf(1.f + __expf(a01[j] - a11[j])); }
;                 }
; #pragma unroll
;                 for (int ai = 0; ai < 2; ++ai)
; #pragma unroll
;                     for (int m = 0; m < 4; ++m) {
;                         const int row = lrow0 + ai * 128 + m * 16; const size_t off = (size_t)row * 1024 + c;
;                         const f32x4 v0 = acc[ai][bj][m][0] * rs[ai][m], v1 = acc[ai][bj][m][1] * rs[ai][m];
;                         const float v[8] = {v0[0], v0[1], v0[2], v0[3], v1[0], v1[1], v1[2], v1[3]};
;                         float y[8];
;                         if (region == 0) {
; #pragma unroll
;                             for (int j = 0; j < 8; ++j) y[j] = silu_f(v[j]);
;                             *(v4u*)(o0 + off) = pack8(y);
;                         } else if (region == 1) {
;                             float lf[8];
; #pragma unroll
;                             for (int j = 0; j < 8; ++j) {
;                                 const float om = 1.f - lb[j];
;                                 const float fc = fminf(fmaxf(v[j], -80.f), 80.f);
;                                 const float e = __expf(-fc), sg = __builtin_amdgcn_rcpf(1.f + e);
;                                 y[j] = om * e * sg;
;                                 lf[j] = __logf(fmaxf(lb[j] + om * sg, 1e-30f));
;                             }
;                             *(v4u*)(o1 + off) = pack8(y);
.LBB0_918:
	s_waitcnt vmcnt(0)
	v_fmamk_f32 v150, v154, 0x3a800000, v139
	s_cmp_gt_u32 s39, 3
	s_cselect_b64 s[2:3], -1, 0
	v_rsq_f32_e32 v150, v150
	s_cmp_lg_u32 s13, 2
	v_lshlrev_b64 v[166:167], 10, v[178:179]
	s_cselect_b64 s[46:47], -1, 0
	s_nop 0
	v_mov_b32_e32 v168, v150
	v_pk_mul_f32 v[182:183], v[128:129], v[168:169] op_sel_hi:[1,0]
	v_pk_mul_f32 v[128:129], v[122:123], v[168:169] op_sel_hi:[1,0]
	v_cndmask_b32_e64 v122, 0, 1, s[0:1]
	v_or_b32_e32 v180, v166, v198
	v_mov_b32_e32 v181, v167
	v_pk_mul_f32 v[184:185], v[126:127], v[168:169] op_sel_hi:[1,0]
	v_pk_mul_f32 v[126:127], v[124:125], v[168:169] op_sel_hi:[1,0]
	s_mov_b64 s[20:21], -1
	s_and_b64 vcc, exec, s[2:3]
	v_cmp_ne_u32_e64 s[42:43], 1, v122
	s_cbranch_vccz .LBB0_927
	s_and_b64 vcc, exec, s[42:43]
	s_mov_b64 s[0:1], -1
	s_cbranch_vccnz .LBB0_921
	v_max_f32_e32 v122, v184, v184
	s_mov_b32 s20, 0xc2a00000
	v_med3_f32 v122, v122, s20, v195
	v_mul_f32_e32 v122, 0xbfb8aa3b, v122
	v_exp_f32_e32 v122, v122
	v_pk_add_f32 v[150:151], v[176:177], 1.0 op_sel_hi:[1,0] neg_lo:[1,0] neg_hi:[1,0]
	s_mov_b32 s13, 0x3f317217
	s_mov_b32 s15, 0x7f800000
	v_add_f32_e32 v123, 1.0, v122
	v_rcp_f32_e32 v124, v123
	v_max_f32_e32 v123, v185, v185
	v_med3_f32 v123, v123, s20, v195
	v_mul_f32_e32 v123, 0xbfb8aa3b, v123
	v_exp_f32_e32 v123, v123
	v_pk_add_f32 v[152:153], v[174:175], 1.0 op_sel_hi:[1,0] neg_lo:[1,0] neg_hi:[1,0]
	v_pk_add_f32 v[154:155], v[172:173], 1.0 op_sel_hi:[1,0] neg_lo:[1,0] neg_hi:[1,0]
	v_pk_add_f32 v[158:159], v[170:171], 1.0 op_sel_hi:[1,0] neg_lo:[1,0] neg_hi:[1,0]
	v_add_f32_e32 v125, 1.0, v123
	v_rcp_f32_e32 v125, v125
	v_pk_mul_f32 v[122:123], v[122:123], v[150:151]
	s_nop 0
	v_pk_mul_f32 v[186:187], v[124:125], v[122:123]
	v_fma_f32 v122, v124, v150, v176
	v_max_f32_e32 v122, 0xda24260, v122
	v_cmp_gt_f32_e32 vcc, s33, v122
	s_nop 1
	v_cndmask_b32_e64 v123, 0, 32, vcc
	v_ldexp_f32 v122, v122, v123
	v_log_f32_e32 v122, v122
	s_nop 0
	v_mul_f32_e32 v123, 0x3f317217, v122
	v_fma_f32 v123, v122, s13, -v123
	v_fmac_f32_e32 v123, 0x3377d1cf, v122
	v_fmac_f32_e32 v123, 0x3f317217, v122
	v_cmp_lt_f32_e64 s[0:1], |v122|, s15
	s_nop 1
	v_cndmask_b32_e64 v122, v122, v123, s[0:1]
	v_cndmask_b32_e32 v123, 0, v194, vcc
	v_sub_f32_e32 v122, v122, v123
	v_fma_f32 v123, v125, v151, v177
	v_max_f32_e32 v123, 0xda24260, v123
	v_cmp_gt_f32_e32 vcc, s33, v123
	s_nop 1
	v_cndmask_b32_e64 v124, 0, 32, vcc
	v_ldexp_f32 v123, v123, v124
	v_log_f32_e32 v123, v123
	s_nop 0
	v_mul_f32_e32 v124, 0x3f317217, v123
	v_fma_f32 v124, v123, s13, -v124
	v_fmac_f32_e32 v124, 0x3377d1cf, v123
	v_fmac_f32_e32 v124, 0x3f317217, v123
	v_cmp_lt_f32_e64 s[0:1], |v123|, s15
	s_nop 1
	v_cndmask_b32_e64 v123, v123, v124, s[0:1]
	v_cndmask_b32_e32 v124, 0, v194, vcc
	v_sub_f32_e32 v123, v123, v124
	v_max_f32_e32 v124, v182, v182
	v_med3_f32 v124, v124, s20, v195
	v_mul_f32_e32 v124, 0xbfb8aa3b, v124
	v_exp_f32_e32 v124, v124
	s_nop 0
	v_add_f32_e32 v125, 1.0, v124
	v_rcp_f32_e32 v150, v125
	v_max_f32_e32 v125, v183, v183
	v_med3_f32 v125, v125, s20, v195
	v_mul_f32_e32 v125, 0xbfb8aa3b, v125
	v_exp_f32_e32 v125, v125
	s_nop 0
	v_add_f32_e32 v151, 1.0, v125
	v_rcp_f32_e32 v151, v151
	v_pk_mul_f32 v[124:125], v[124:125], v[152:153]
	s_nop 0
	v_pk_mul_f32 v[188:189], v[150:151], v[124:125]
	v_fma_f32 v124, v150, v152, v174
	v_max_f32_e32 v124, 0xda24260, v124
	v_cmp_gt_f32_e32 vcc, s33, v124
	s_nop 1
	v_cndmask_b32_e64 v125, 0, 32, vcc
	v_ldexp_f32 v124, v124, v125
	v_log_f32_e32 v124, v124
	s_nop 0
	v_mul_f32_e32 v125, 0x3f317217, v124
	v_fma_f32 v125, v124, s13, -v125
	v_fmac_f32_e32 v125, 0x3377d1cf, v124
	v_fmac_f32_e32 v125, 0x3f317217, v124
	v_cmp_lt_f32_e64 s[0:1], |v124|, s15
	s_nop 1
	v_cndmask_b32_e64 v124, v124, v125, s[0:1]
	v_cndmask_b32_e32 v125, 0, v194, vcc
	v_sub_f32_e32 v124, v124, v125
	v_fma_f32 v125, v151, v153, v175
	v_max_f32_e32 v125, 0xda24260, v125
	v_cmp_gt_f32_e32 vcc, s33, v125
	s_nop 1
	v_cndmask_b32_e64 v150, 0, 32, vcc
	v_ldexp_f32 v125, v125, v150
; __device__ __forceinline__ v4u pack8(const float (&y)[8]) { return (v4u){pk2(y[0], y[1]), pk2(y[2], y[3]), pk2(y[4], y[5]), pk2(y[6], y[7])}; }
;     __device__ __forceinline__ void operator()(const f32x4 (&acc)[2][2][4][2], const pg8::Unit& u, int wr, int wc, int fr, int fq) const {
;     ...
;                         } else if (region == 1) {
;                             float lf[8];
; #pragma unroll
;                             for (int j = 0; j < 8; ++j) {
;                                 const float om = 1.f - lb[j];
;                                 const float fc = fminf(fmaxf(v[j], -80.f), 80.f);
;                                 const float e = __expf(-fc), sg = __builtin_amdgcn_rcpf(1.f + e);
;                                 y[j] = om * e * sg;
;                                 lf[j] = __logf(fmaxf(lb[j] + om * sg, 1e-30f));
;                             }
;                             *(v4u*)(o1 + off) = pack8(y);
;                             *(f32x4*)(of + off) = (f32x4){lf[0], lf[1], lf[2], lf[3]}; *(f32x4*)(of + off + 4) = (f32x4){lf[4], lf[5], lf[6], lf[7]};
	v_log_f32_e32 v125, v125
	s_nop 0
	v_mul_f32_e32 v150, 0x3f317217, v125
	v_fma_f32 v150, v125, s13, -v150
	v_fmac_f32_e32 v150, 0x3377d1cf, v125
	v_fmac_f32_e32 v150, 0x3f317217, v125
	v_cmp_lt_f32_e64 s[0:1], |v125|, s15
	s_nop 1
	v_cndmask_b32_e64 v125, v125, v150, s[0:1]
	v_cndmask_b32_e32 v150, 0, v194, vcc
	v_sub_f32_e32 v125, v125, v150
	v_max_f32_e32 v150, v128, v128
	v_med3_f32 v150, v150, s20, v195
	v_mul_f32_e32 v150, 0xbfb8aa3b, v150
	v_exp_f32_e32 v150, v150
	s_nop 0
	v_add_f32_e32 v151, 1.0, v150
	v_rcp_f32_e32 v152, v151
	v_max_f32_e32 v151, v129, v129
	v_med3_f32 v151, v151, s20, v195
	v_mul_f32_e32 v151, 0xbfb8aa3b, v151
	v_exp_f32_e32 v151, v151
	s_nop 0
	v_add_f32_e32 v153, 1.0, v151
	v_rcp_f32_e32 v153, v153
	v_pk_mul_f32 v[150:151], v[150:151], v[154:155]
	s_nop 0
	v_pk_mul_f32 v[156:157], v[152:153], v[150:151]
	v_fma_f32 v150, v152, v154, v172
	v_max_f32_e32 v150, 0xda24260, v150
	v_cmp_gt_f32_e32 vcc, s33, v150
	v_cvt_pk_bf16_f32 v156, v156, v157
	s_nop 0
	v_cndmask_b32_e64 v151, 0, 32, vcc
	v_ldexp_f32 v150, v150, v151
	v_log_f32_e32 v150, v150
	s_nop 0
	v_mul_f32_e32 v151, 0x3f317217, v150
	v_fma_f32 v151, v150, s13, -v151
	v_fmac_f32_e32 v151, 0x3377d1cf, v150
	v_fmac_f32_e32 v151, 0x3f317217, v150
	v_cmp_lt_f32_e64 s[0:1], |v150|, s15
	s_nop 1
	v_cndmask_b32_e64 v150, v150, v151, s[0:1]
	v_cndmask_b32_e32 v151, 0, v194, vcc
	v_sub_f32_e32 v150, v150, v151
	v_fma_f32 v151, v153, v155, v173
	v_max_f32_e32 v151, 0xda24260, v151
	v_cmp_gt_f32_e32 vcc, s33, v151
	s_nop 1
	v_cndmask_b32_e64 v152, 0, 32, vcc
	v_ldexp_f32 v151, v151, v152
	v_log_f32_e32 v151, v151
	s_nop 0
	v_mul_f32_e32 v152, 0x3f317217, v151
	v_fma_f32 v152, v151, s13, -v152
	v_fmac_f32_e32 v152, 0x3377d1cf, v151
	v_fmac_f32_e32 v152, 0x3f317217, v151
	v_cmp_lt_f32_e64 s[0:1], |v151|, s15
	s_nop 1
	v_cndmask_b32_e64 v151, v151, v152, s[0:1]
	v_cndmask_b32_e32 v152, 0, v194, vcc
	v_sub_f32_e32 v151, v151, v152
	v_max_f32_e32 v152, v126, v126
	v_med3_f32 v152, v152, s20, v195
	v_mul_f32_e32 v152, 0xbfb8aa3b, v152
	v_exp_f32_e32 v152, v152
	s_nop 0
	v_add_f32_e32 v153, 1.0, v152
	v_rcp_f32_e32 v154, v153
	v_max_f32_e32 v153, v127, v127
	v_med3_f32 v153, v153, s20, v195
	v_mul_f32_e32 v153, 0xbfb8aa3b, v153
	v_exp_f32_e32 v153, v153
	s_nop 0
	v_add_f32_e32 v155, 1.0, v153
	v_rcp_f32_e32 v155, v155
	v_pk_mul_f32 v[152:153], v[152:153], v[158:159]
	s_nop 0
	v_pk_mul_f32 v[206:207], v[154:155], v[152:153]
	v_fma_f32 v152, v154, v158, v170
	v_max_f32_e32 v152, 0xda24260, v152
	v_cmp_gt_f32_e32 vcc, s33, v152
	v_cvt_pk_bf16_f32 v157, v206, v207
	s_nop 0
	v_cndmask_b32_e64 v153, 0, 32, vcc
	v_ldexp_f32 v152, v152, v153
	v_log_f32_e32 v152, v152
	s_nop 0
	v_mul_f32_e32 v153, 0x3f317217, v152
	v_fma_f32 v153, v152, s13, -v153
	v_fmac_f32_e32 v153, 0x3377d1cf, v152
	v_fmac_f32_e32 v153, 0x3f317217, v152
	v_cmp_lt_f32_e64 s[0:1], |v152|, s15
	s_nop 1
	v_cndmask_b32_e64 v152, v152, v153, s[0:1]
	v_cndmask_b32_e32 v153, 0, v194, vcc
	v_sub_f32_e32 v152, v152, v153
	v_fma_f32 v153, v155, v159, v171
	v_max_f32_e32 v153, 0xda24260, v153
	v_cmp_gt_f32_e32 vcc, s33, v153
	v_cvt_pk_bf16_f32 v155, v188, v189
	s_nop 0
	v_cndmask_b32_e64 v154, 0, 32, vcc
	v_ldexp_f32 v153, v153, v154
	v_log_f32_e32 v153, v153
	s_nop 0
	v_mul_f32_e32 v154, 0x3f317217, v153
	v_fma_f32 v154, v153, s13, -v154
	v_fmac_f32_e32 v154, 0x3377d1cf, v153
	v_fmac_f32_e32 v154, 0x3f317217, v153
	v_cmp_lt_f32_e64 s[0:1], |v153|, s15
	s_nop 1
	v_cndmask_b32_e64 v153, v153, v154, s[0:1]
	v_readlane_b32 s0, v253, 0
	v_readlane_b32 s1, v253, 1
	v_cndmask_b32_e32 v154, 0, v194, vcc
	v_sub_f32_e32 v153, v153, v154
	v_lshl_add_u64 v[158:159], v[180:181], 1, s[0:1]
	v_readlane_b32 s0, v253, 15
	v_cvt_pk_bf16_f32 v154, v186, v187
	v_readlane_b32 s1, v253, 16
	global_store_dwordx4 v[158:159], v[154:157], off
	s_nop 1
	v_lshl_add_u64 v[154:155], v[180:181], 2, s[0:1]
	s_mov_b64 s[0:1], 0
	global_store_dwordx4 v[154:155], v[122:125], off
	global_store_dwordx4 v[154:155], v[150:153], off offset:16

;     __device__ __forceinline__ void operator()(const f32x4 (&acc)[2][2][4][2], const pg8::Unit& u, int wr, int wc, int fr, int fq) const {
;     ...
;                 for (int m = 0; m < 4; ++m) rs[ai][m] = rsqrtf(ssq[lrow0 + ai * 128 + m * 16] * (1.f / 1024.f) + EPS);
; #pragma unroll
;             for (int bj = 0; bj < 2; ++bj) {
;                 const int c = c0 + bj * 128;
;                 float lb[8] = {0.f, 0.f, 0.f, 0.f, 0.f, 0.f, 0.f, 0.f};
;                 if (region == 1 && idx != 0) {
;                     const f32x4 a00 = *(const f32x4*)(lbsrc + c), a01 = *(const f32x4*)(lbsrc + c + 4), a10 = *(const f32x4*)(lbsrc + 1024 + c), a11 = *(const f32x4*)(lbsrc + 1024 + c + 4);
; #pragma unroll
;                     for (int j = 0; j < 4; ++j) { lb[j] = __builtin_amdgcn_rcpf(1.f + __expf(a00[j] - a10[j])); lb[4 + j] = __builtin_amdgcn_rcpf(1.f + __expf(a01[j] - a11[j])); }
;                 }
; #pragma unroll
;                 for (int ai = 0; ai < 2; ++ai)
; #pragma unroll
;                     for (int m = 0; m < 4; ++m) {
;                         const int row = lrow0 + ai * 128 + m * 16; const size_t off = (size_t)row * 1024 + c;
;                         const f32x4 v0 = acc[ai][bj][m][0] * rs[ai][m], v1 = acc[ai][bj][m][1] * rs[ai][m];
.LBB0_929:
	s_nop 1
	v_fmamk_f32 v122, v205, 0x3a800000, v139
	s_mov_b64 s[0:1], -1
	s_mov_b32 s20, s85
	v_rsq_f32_e32 v124, v122
	v_or_b32_e32 v122, 16, v178
	v_ashrrev_i32_e32 v123, 31, v122
	v_lshlrev_b64 v[122:123], 10, v[122:123]
	s_nop 0
	v_pk_mul_f32 v[128:129], v[120:121], v[124:125] op_sel_hi:[1,0]
	v_pk_mul_f32 v[120:121], v[114:115], v[124:125] op_sel_hi:[1,0]
	v_cndmask_b32_e64 v114, 0, 1, s[2:3]
	s_andn2_b64 vcc, exec, s[2:3]
	v_readlane_b32 s2, v253, 15
	v_or_b32_e32 v126, v122, v198
	v_mov_b32_e32 v127, v123
	v_pk_mul_f32 v[180:181], v[118:119], v[124:125] op_sel_hi:[1,0]
	v_pk_mul_f32 v[118:119], v[116:117], v[124:125] op_sel_hi:[1,0]
	v_cmp_ne_u32_e64 s[44:45], 1, v114
	v_readlane_b32 s3, v253, 16
	s_mov_b32 s21, 0x100000
	s_cbranch_vccnz .LBB0_938
	s_and_b64 vcc, exec, s[42:43]
	s_cbranch_vccnz .LBB0_932
; __device__ __forceinline__ v4u pack8(const float (&y)[8]) { return (v4u){pk2(y[0], y[1]), pk2(y[2], y[3]), pk2(y[4], y[5]), pk2(y[6], y[7])}; }
;     __device__ __forceinline__ void operator()(const f32x4 (&acc)[2][2][4][2], const pg8::Unit& u, int wr, int wc, int fr, int fq) const {
;     ...
;                         } else if (region == 1) {
;                             float lf[8];
; #pragma unroll
;                             for (int j = 0; j < 8; ++j) {
;                                 const float om = 1.f - lb[j];
;                                 const float fc = fminf(fmaxf(v[j], -80.f), 80.f);
;                                 const float e = __expf(-fc), sg = __builtin_amdgcn_rcpf(1.f + e);
;                                 y[j] = om * e * sg;
;                                 lf[j] = __logf(fmaxf(lb[j] + om * sg, 1e-30f));
;                             }
;                             *(v4u*)(o1 + off) = pack8(y);
;                             *(f32x4*)(of + off) = (f32x4){lf[0], lf[1], lf[2], lf[3]}; *(f32x4*)(of + off + 4) = (f32x4){lf[4], lf[5], lf[6], lf[7]};
	v_max_f32_e32 v114, v180, v180
	s_mov_b32 s39, 0xc2a00000
	v_med3_f32 v114, v114, s39, v195
	v_mul_f32_e32 v114, 0xbfb8aa3b, v114
	v_exp_f32_e32 v114, v114
	v_pk_add_f32 v[150:151], v[176:177], 1.0 op_sel_hi:[1,0] neg_lo:[1,0] neg_hi:[1,0]
	s_mov_b32 s13, 0x3f317217
	s_mov_b32 s15, 0x7f800000
	v_add_f32_e32 v115, 1.0, v114
	v_rcp_f32_e32 v116, v115
	v_max_f32_e32 v115, v181, v181
	v_med3_f32 v115, v115, s39, v195
	v_mul_f32_e32 v115, 0xbfb8aa3b, v115
	v_exp_f32_e32 v115, v115
	v_pk_add_f32 v[152:153], v[174:175], 1.0 op_sel_hi:[1,0] neg_lo:[1,0] neg_hi:[1,0]
	v_pk_add_f32 v[154:155], v[172:173], 1.0 op_sel_hi:[1,0] neg_lo:[1,0] neg_hi:[1,0]
	v_pk_add_f32 v[158:159], v[170:171], 1.0 op_sel_hi:[1,0] neg_lo:[1,0] neg_hi:[1,0]
	v_add_f32_e32 v117, 1.0, v115
	v_rcp_f32_e32 v117, v117
	v_pk_mul_f32 v[114:115], v[114:115], v[150:151]
	s_nop 0
	v_pk_mul_f32 v[182:183], v[116:117], v[114:115]
	v_fma_f32 v114, v116, v150, v176
	v_max_f32_e32 v114, 0xda24260, v114
	v_cmp_gt_f32_e32 vcc, s33, v114
	s_nop 1
	v_cndmask_b32_e64 v115, 0, 32, vcc
	v_ldexp_f32 v114, v114, v115
	v_log_f32_e32 v114, v114
	s_nop 0
	v_mul_f32_e32 v115, 0x3f317217, v114
	v_fma_f32 v115, v114, s13, -v115
	v_fmac_f32_e32 v115, 0x3377d1cf, v114
	v_fmac_f32_e32 v115, 0x3f317217, v114
	v_cmp_lt_f32_e64 s[0:1], |v114|, s15
	s_nop 1
	v_cndmask_b32_e64 v114, v114, v115, s[0:1]
	v_cndmask_b32_e32 v115, 0, v194, vcc
	v_sub_f32_e32 v114, v114, v115
	v_fma_f32 v115, v117, v151, v177
	v_max_f32_e32 v115, 0xda24260, v115
	v_cmp_gt_f32_e32 vcc, s33, v115
	s_nop 1
	v_cndmask_b32_e64 v116, 0, 32, vcc
	v_ldexp_f32 v115, v115, v116
	v_log_f32_e32 v115, v115
	s_nop 0
	v_mul_f32_e32 v116, 0x3f317217, v115
	v_fma_f32 v116, v115, s13, -v116
	v_fmac_f32_e32 v116, 0x3377d1cf, v115
	v_fmac_f32_e32 v116, 0x3f317217, v115
	v_cmp_lt_f32_e64 s[0:1], |v115|, s15
	s_nop 1
	v_cndmask_b32_e64 v115, v115, v116, s[0:1]
	v_cndmask_b32_e32 v116, 0, v194, vcc
	v_sub_f32_e32 v115, v115, v116
	v_max_f32_e32 v116, v128, v128
	v_med3_f32 v116, v116, s39, v195
	v_mul_f32_e32 v116, 0xbfb8aa3b, v116
	v_exp_f32_e32 v116, v116
	s_nop 0
	v_add_f32_e32 v117, 1.0, v116
	v_rcp_f32_e32 v150, v117
	v_max_f32_e32 v117, v129, v129
	v_med3_f32 v117, v117, s39, v195
	v_mul_f32_e32 v117, 0xbfb8aa3b, v117
	v_exp_f32_e32 v117, v117
	s_nop 0
	v_add_f32_e32 v125, 1.0, v117
	v_rcp_f32_e32 v151, v125
	v_pk_mul_f32 v[116:117], v[116:117], v[152:153]
	s_nop 0
	v_pk_mul_f32 v[184:185], v[150:151], v[116:117]
	v_fma_f32 v116, v150, v152, v174
	v_max_f32_e32 v116, 0xda24260, v116
	v_cmp_gt_f32_e32 vcc, s33, v116
	s_nop 1
	v_cndmask_b32_e64 v117, 0, 32, vcc
	v_ldexp_f32 v116, v116, v117
	v_log_f32_e32 v116, v116
	s_nop 0
	v_mul_f32_e32 v117, 0x3f317217, v116
	v_fma_f32 v117, v116, s13, -v117
	v_fmac_f32_e32 v117, 0x3377d1cf, v116
	v_fmac_f32_e32 v117, 0x3f317217, v116
	v_cmp_lt_f32_e64 s[0:1], |v116|, s15
	s_nop 1
	v_cndmask_b32_e64 v116, v116, v117, s[0:1]
	v_cndmask_b32_e32 v117, 0, v194, vcc
	v_sub_f32_e32 v116, v116, v117
	v_fma_f32 v117, v151, v153, v175
	v_max_f32_e32 v117, 0xda24260, v117
	v_cmp_gt_f32_e32 vcc, s33, v117
	s_nop 1
	v_cndmask_b32_e64 v125, 0, 32, vcc
	v_ldexp_f32 v117, v117, v125
	v_log_f32_e32 v117, v117
	s_nop 0
	v_mul_f32_e32 v125, 0x3f317217, v117
	v_fma_f32 v125, v117, s13, -v125
	v_fmac_f32_e32 v125, 0x3377d1cf, v117
	v_fmac_f32_e32 v125, 0x3f317217, v117
	v_cmp_lt_f32_e64 s[0:1], |v117|, s15
	s_nop 1
	v_cndmask_b32_e64 v117, v117, v125, s[0:1]
	v_cndmask_b32_e32 v125, 0, v194, vcc
	v_sub_f32_e32 v117, v117, v125
	v_max_f32_e32 v125, v120, v120
	v_med3_f32 v125, v125, s39, v195
	v_mul_f32_e32 v125, 0xbfb8aa3b, v125
	v_exp_f32_e32 v150, v125
	s_nop 0
	v_add_f32_e32 v125, 1.0, v150
	v_rcp_f32_e32 v152, v125
	v_max_f32_e32 v125, v121, v121
	v_med3_f32 v125, v125, s39, v195
	v_mul_f32_e32 v125, 0xbfb8aa3b, v125
	v_exp_f32_e32 v151, v125
	s_nop 0
	v_add_f32_e32 v125, 1.0, v151
	v_rcp_f32_e32 v153, v125
	v_fma_f32 v125, v152, v154, v172
	v_max_f32_e32 v125, 0xda24260, v125
	v_pk_mul_f32 v[150:151], v[150:151], v[154:155]
	v_cmp_gt_f32_e32 vcc, s33, v125
	v_pk_mul_f32 v[156:157], v[152:153], v[150:151]
	s_nop 0
	v_cndmask_b32_e64 v150, 0, 32, vcc
	v_ldexp_f32 v125, v125, v150
	v_log_f32_e32 v125, v125
	v_cvt_pk_bf16_f32 v156, v156, v157
	v_mul_f32_e32 v150, 0x3f317217, v125
	v_fma_f32 v150, v125, s13, -v150
	v_fmac_f32_e32 v150, 0x3377d1cf, v125
	v_fmac_f32_e32 v150, 0x3f317217, v125
	v_cmp_lt_f32_e64 s[0:1], |v125|, s15
	s_nop 1
	v_cndmask_b32_e64 v125, v125, v150, s[0:1]
	v_cndmask_b32_e32 v150, 0, v194, vcc
	v_sub_f32_e32 v150, v125, v150
	v_fma_f32 v125, v153, v155, v173
	v_max_f32_e32 v125, 0xda24260, v125
	v_cmp_gt_f32_e32 vcc, s33, v125
	s_nop 1
	v_cndmask_b32_e64 v151, 0, 32, vcc
	v_ldexp_f32 v125, v125, v151
	v_log_f32_e32 v125, v125
	s_nop 0
	v_mul_f32_e32 v151, 0x3f317217, v125
	v_fma_f32 v151, v125, s13, -v151
	v_fmac_f32_e32 v151, 0x3377d1cf, v125
	v_fmac_f32_e32 v151, 0x3f317217, v125
	v_cmp_lt_f32_e64 s[0:1], |v125|, s15
	s_nop 1
	v_cndmask_b32_e64 v125, v125, v151, s[0:1]
	v_cndmask_b32_e32 v151, 0, v194, vcc
	v_sub_f32_e32 v151, v125, v151
	v_max_f32_e32 v125, v118, v118
	v_med3_f32 v125, v125, s39, v195
	v_mul_f32_e32 v125, 0xbfb8aa3b, v125
	v_exp_f32_e32 v152, v125
	s_nop 0
	v_add_f32_e32 v125, 1.0, v152
	v_rcp_f32_e32 v154, v125
	v_max_f32_e32 v125, v119, v119
	v_med3_f32 v125, v125, s39, v195
	v_mul_f32_e32 v125, 0xbfb8aa3b, v125
	v_exp_f32_e32 v153, v125
	s_nop 0
	v_add_f32_e32 v125, 1.0, v153
	v_rcp_f32_e32 v155, v125
	v_fma_f32 v125, v154, v158, v170
	v_max_f32_e32 v125, 0xda24260, v125
	v_pk_mul_f32 v[152:153], v[152:153], v[158:159]
	v_cmp_gt_f32_e32 vcc, s33, v125
	v_pk_mul_f32 v[186:187], v[154:155], v[152:153]
	v_cvt_pk_bf16_f32 v154, v182, v183
	v_cndmask_b32_e64 v152, 0, 32, vcc
	v_ldexp_f32 v125, v125, v152
	v_log_f32_e32 v125, v125
	v_cvt_pk_bf16_f32 v157, v186, v187
	v_mul_f32_e32 v152, 0x3f317217, v125
	v_fma_f32 v152, v125, s13, -v152
	v_fmac_f32_e32 v152, 0x3377d1cf, v125
	v_fmac_f32_e32 v152, 0x3f317217, v125
	v_cmp_lt_f32_e64 s[0:1], |v125|, s15
	s_nop 1
	v_cndmask_b32_e64 v125, v125, v152, s[0:1]
	v_cndmask_b32_e32 v152, 0, v194, vcc
	v_sub_f32_e32 v152, v125, v152
	v_fma_f32 v125, v155, v159, v171
	v_max_f32_e32 v125, 0xda24260, v125
	v_cmp_gt_f32_e32 vcc, s33, v125
	v_cvt_pk_bf16_f32 v155, v184, v185
	s_nop 0
	v_cndmask_b32_e64 v153, 0, 32, vcc
	v_ldexp_f32 v125, v125, v153
	v_log_f32_e32 v125, v125
	s_nop 0
	v_mul_f32_e32 v153, 0x3f317217, v125
	v_fma_f32 v153, v125, s13, -v153
	v_fmac_f32_e32 v153, 0x3377d1cf, v125
	v_fmac_f32_e32 v153, 0x3f317217, v125
	v_cmp_lt_f32_e64 s[0:1], |v125|, s15
	s_nop 1
	v_cndmask_b32_e64 v125, v125, v153, s[0:1]
	v_readlane_b32 s0, v253, 0
	v_readlane_b32 s1, v253, 1
	v_cndmask_b32_e32 v153, 0, v194, vcc
	v_sub_f32_e32 v153, v125, v153
	v_lshl_add_u64 v[158:159], v[126:127], 1, s[0:1]
	global_store_dwordx4 v[158:159], v[154:157], off
	s_mov_b64 s[0:1], 0
	s_nop 0
	v_lshl_add_u64 v[154:155], v[126:127], 2, s[2:3]
	global_store_dwordx4 v[154:155], v[114:117], off
	global_store_dwordx4 v[154:155], v[150:153], off offset:16

;     __device__ __forceinline__ void operator()(const f32x4 (&acc)[2][2][4][2], const pg8::Unit& u, int wr, int wc, int fr, int fq) const {
;     ...
;                 for (int m = 0; m < 4; ++m) rs[ai][m] = rsqrtf(ssq[lrow0 + ai * 128 + m * 16] * (1.f / 1024.f) + EPS);
; #pragma unroll
;             for (int bj = 0; bj < 2; ++bj) {
;                 const int c = c0 + bj * 128;
;                 float lb[8] = {0.f, 0.f, 0.f, 0.f, 0.f, 0.f, 0.f, 0.f};
;                 if (region == 1 && idx != 0) {
;                     const f32x4 a00 = *(const f32x4*)(lbsrc + c), a01 = *(const f32x4*)(lbsrc + c + 4), a10 = *(const f32x4*)(lbsrc + 1024 + c), a11 = *(const f32x4*)(lbsrc + 1024 + c + 4);
; #pragma unroll
;                     for (int j = 0; j < 4; ++j) { lb[j] = __builtin_amdgcn_rcpf(1.f + __expf(a00[j] - a10[j])); lb[4 + j] = __builtin_amdgcn_rcpf(1.f + __expf(a01[j] - a11[j])); }
;                 }
; #pragma unroll
;                 for (int ai = 0; ai < 2; ++ai)
; #pragma unroll
;                     for (int m = 0; m < 4; ++m) {
;                         const int row = lrow0 + ai * 128 + m * 16; const size_t off = (size_t)row * 1024 + c;
;                         const f32x4 v0 = acc[ai][bj][m][0] * rs[ai][m], v1 = acc[ai][bj][m][1] * rs[ai][m];
.LBB0_940:
	s_nop 1
	v_fmamk_f32 v114, v204, 0x3a800000, v139
	s_mov_b64 s[0:1], -1
	s_nop 0
	v_rsq_f32_e32 v116, v114
	v_or_b32_e32 v114, 32, v178
	v_ashrrev_i32_e32 v115, 31, v114
	v_lshlrev_b64 v[114:115], 10, v[114:115]
	s_nop 0
	v_or_b32_e32 v118, v114, v198
	v_mov_b32_e32 v119, v115
	v_pk_mul_f32 v[120:121], v[112:113], v[116:117] op_sel_hi:[1,0]
	v_pk_mul_f32 v[126:127], v[110:111], v[116:117] op_sel_hi:[1,0]
	v_pk_mul_f32 v[110:111], v[108:109], v[116:117] op_sel_hi:[1,0]
	v_pk_mul_f32 v[112:113], v[106:107], v[116:117] op_sel_hi:[1,0]
	s_and_b64 vcc, exec, s[44:45]
	s_cbranch_vccnz .LBB0_949
	s_and_b64 vcc, exec, s[42:43]
	s_cbranch_vccnz .LBB0_943
; __device__ __forceinline__ v4u pack8(const float (&y)[8]) { return (v4u){pk2(y[0], y[1]), pk2(y[2], y[3]), pk2(y[4], y[5]), pk2(y[6], y[7])}; }
;     __device__ __forceinline__ void operator()(const f32x4 (&acc)[2][2][4][2], const pg8::Unit& u, int wr, int wc, int fr, int fq) const {
;     ...
;                         } else if (region == 1) {
;                             float lf[8];
; #pragma unroll
;                             for (int j = 0; j < 8; ++j) {
;                                 const float om = 1.f - lb[j];
;                                 const float fc = fminf(fmaxf(v[j], -80.f), 80.f);
;                                 const float e = __expf(-fc), sg = __builtin_amdgcn_rcpf(1.f + e);
;                                 y[j] = om * e * sg;
;                                 lf[j] = __logf(fmaxf(lb[j] + om * sg, 1e-30f));
;                             }
;                             *(v4u*)(o1 + off) = pack8(y);
;                             *(f32x4*)(of + off) = (f32x4){lf[0], lf[1], lf[2], lf[3]}; *(f32x4*)(of + off + 4) = (f32x4){lf[4], lf[5], lf[6], lf[7]};
	v_max_f32_e32 v106, v126, v126
	s_mov_b32 s39, 0xc2a00000
	v_med3_f32 v106, v106, s39, v195
	v_mul_f32_e32 v106, 0xbfb8aa3b, v106
	v_exp_f32_e32 v106, v106
	v_pk_add_f32 v[150:151], v[176:177], 1.0 op_sel_hi:[1,0] neg_lo:[1,0] neg_hi:[1,0]
	s_mov_b32 s13, 0x3f317217
	s_mov_b32 s15, 0x7f800000
	v_add_f32_e32 v107, 1.0, v106
	v_rcp_f32_e32 v108, v107
	v_max_f32_e32 v107, v127, v127
	v_med3_f32 v107, v107, s39, v195
	v_mul_f32_e32 v107, 0xbfb8aa3b, v107
	v_exp_f32_e32 v107, v107
	v_pk_add_f32 v[152:153], v[174:175], 1.0 op_sel_hi:[1,0] neg_lo:[1,0] neg_hi:[1,0]
	v_pk_add_f32 v[154:155], v[172:173], 1.0 op_sel_hi:[1,0] neg_lo:[1,0] neg_hi:[1,0]
	v_pk_add_f32 v[158:159], v[170:171], 1.0 op_sel_hi:[1,0] neg_lo:[1,0] neg_hi:[1,0]
	v_add_f32_e32 v109, 1.0, v107
	v_rcp_f32_e32 v109, v109
	v_pk_mul_f32 v[106:107], v[106:107], v[150:151]
	s_nop 0
	v_pk_mul_f32 v[128:129], v[108:109], v[106:107]
	v_fma_f32 v106, v108, v150, v176
	v_max_f32_e32 v106, 0xda24260, v106
	v_cmp_gt_f32_e32 vcc, s33, v106
	s_nop 1
	v_cndmask_b32_e64 v107, 0, 32, vcc
	v_ldexp_f32 v106, v106, v107
	v_log_f32_e32 v106, v106
	s_nop 0
	v_mul_f32_e32 v107, 0x3f317217, v106
	v_fma_f32 v107, v106, s13, -v107
	v_fmac_f32_e32 v107, 0x3377d1cf, v106
	v_fmac_f32_e32 v107, 0x3f317217, v106
	v_cmp_lt_f32_e64 s[0:1], |v106|, s15
	s_nop 1
	v_cndmask_b32_e64 v106, v106, v107, s[0:1]
	v_cndmask_b32_e32 v107, 0, v194, vcc
	v_sub_f32_e32 v106, v106, v107
	v_fma_f32 v107, v109, v151, v177
	v_max_f32_e32 v107, 0xda24260, v107
	v_cmp_gt_f32_e32 vcc, s33, v107
	s_nop 1
	v_cndmask_b32_e64 v108, 0, 32, vcc
	v_ldexp_f32 v107, v107, v108
	v_log_f32_e32 v107, v107
	s_nop 0
	v_mul_f32_e32 v108, 0x3f317217, v107
	v_fma_f32 v108, v107, s13, -v108
	v_fmac_f32_e32 v108, 0x3377d1cf, v107
	v_fmac_f32_e32 v108, 0x3f317217, v107
	v_cmp_lt_f32_e64 s[0:1], |v107|, s15
	s_nop 1
	v_cndmask_b32_e64 v107, v107, v108, s[0:1]
	v_cndmask_b32_e32 v108, 0, v194, vcc
	v_sub_f32_e32 v107, v107, v108
	v_max_f32_e32 v108, v120, v120
	v_med3_f32 v108, v108, s39, v195
	v_mul_f32_e32 v108, 0xbfb8aa3b, v108
	v_exp_f32_e32 v108, v108
	s_nop 0
	v_add_f32_e32 v109, 1.0, v108
	v_rcp_f32_e32 v150, v109
	v_max_f32_e32 v109, v121, v121
	v_med3_f32 v109, v109, s39, v195
	v_mul_f32_e32 v109, 0xbfb8aa3b, v109
	v_exp_f32_e32 v109, v109
	s_nop 0
	v_add_f32_e32 v117, 1.0, v109
	v_rcp_f32_e32 v151, v117
	v_pk_mul_f32 v[108:109], v[108:109], v[152:153]
	s_nop 0
	v_pk_mul_f32 v[180:181], v[150:151], v[108:109]
	v_fma_f32 v108, v150, v152, v174
	v_max_f32_e32 v108, 0xda24260, v108
	v_cmp_gt_f32_e32 vcc, s33, v108
	s_nop 1
	v_cndmask_b32_e64 v109, 0, 32, vcc
	v_ldexp_f32 v108, v108, v109
	v_log_f32_e32 v108, v108
	s_nop 0
	v_mul_f32_e32 v109, 0x3f317217, v108
	v_fma_f32 v109, v108, s13, -v109
	v_fmac_f32_e32 v109, 0x3377d1cf, v108
	v_fmac_f32_e32 v109, 0x3f317217, v108
	v_cmp_lt_f32_e64 s[0:1], |v108|, s15
	s_nop 1
	v_cndmask_b32_e64 v108, v108, v109, s[0:1]
	v_cndmask_b32_e32 v109, 0, v194, vcc
	v_sub_f32_e32 v108, v108, v109
	v_fma_f32 v109, v151, v153, v175
	v_max_f32_e32 v109, 0xda24260, v109
	v_cmp_gt_f32_e32 vcc, s33, v109
	s_nop 1
	v_cndmask_b32_e64 v117, 0, 32, vcc
	v_ldexp_f32 v109, v109, v117
	v_log_f32_e32 v109, v109
	s_nop 0
	v_mul_f32_e32 v117, 0x3f317217, v109
	v_fma_f32 v117, v109, s13, -v117
	v_fmac_f32_e32 v117, 0x3377d1cf, v109
	v_fmac_f32_e32 v117, 0x3f317217, v109
	v_cmp_lt_f32_e64 s[0:1], |v109|, s15
	s_nop 1
	v_cndmask_b32_e64 v109, v109, v117, s[0:1]
	v_cndmask_b32_e32 v117, 0, v194, vcc
	v_sub_f32_e32 v109, v109, v117
	v_max_f32_e32 v117, v112, v112
	v_med3_f32 v117, v117, s39, v195
	v_mul_f32_e32 v117, 0xbfb8aa3b, v117
	v_exp_f32_e32 v150, v117
	s_nop 0
	v_add_f32_e32 v117, 1.0, v150
	v_rcp_f32_e32 v152, v117
	v_max_f32_e32 v117, v113, v113
	v_med3_f32 v117, v117, s39, v195
	v_mul_f32_e32 v117, 0xbfb8aa3b, v117
	v_exp_f32_e32 v151, v117
	s_nop 0
	v_add_f32_e32 v117, 1.0, v151
	v_rcp_f32_e32 v153, v117
	v_fma_f32 v117, v152, v154, v172
	v_max_f32_e32 v117, 0xda24260, v117
	v_cmp_gt_f32_e32 vcc, s33, v117
	v_pk_mul_f32 v[150:151], v[150:151], v[154:155]
	s_nop 0
	v_cndmask_b32_e64 v125, 0, 32, vcc
	v_ldexp_f32 v117, v117, v125
	v_log_f32_e32 v117, v117
	v_pk_mul_f32 v[156:157], v[152:153], v[150:151]
	v_mul_f32_e32 v125, 0x3f317217, v117
	v_fma_f32 v125, v117, s13, -v125
	v_fmac_f32_e32 v125, 0x3377d1cf, v117
	v_fmac_f32_e32 v125, 0x3f317217, v117
	v_cmp_lt_f32_e64 s[0:1], |v117|, s15
	v_cvt_pk_bf16_f32 v156, v156, v157
	s_nop 0
	v_cndmask_b32_e64 v117, v117, v125, s[0:1]
	v_cndmask_b32_e32 v125, 0, v194, vcc
	v_sub_f32_e32 v150, v117, v125
	v_fma_f32 v117, v153, v155, v173
	v_max_f32_e32 v117, 0xda24260, v117
	v_cmp_gt_f32_e32 vcc, s33, v117
	s_nop 1
	v_cndmask_b32_e64 v125, 0, 32, vcc
	v_ldexp_f32 v117, v117, v125
	v_log_f32_e32 v117, v117
	s_nop 0
	v_mul_f32_e32 v125, 0x3f317217, v117
	v_fma_f32 v125, v117, s13, -v125
	v_fmac_f32_e32 v125, 0x3377d1cf, v117
	v_fmac_f32_e32 v125, 0x3f317217, v117
	v_cmp_lt_f32_e64 s[0:1], |v117|, s15
	s_nop 1
	v_cndmask_b32_e64 v117, v117, v125, s[0:1]
	v_cndmask_b32_e32 v125, 0, v194, vcc
	v_sub_f32_e32 v151, v117, v125
	v_max_f32_e32 v117, v110, v110
	v_med3_f32 v117, v117, s39, v195
	v_mul_f32_e32 v117, 0xbfb8aa3b, v117
	v_exp_f32_e32 v152, v117
	s_nop 0
	v_add_f32_e32 v117, 1.0, v152
	v_rcp_f32_e32 v154, v117
	v_max_f32_e32 v117, v111, v111
	v_med3_f32 v117, v117, s39, v195
	v_mul_f32_e32 v117, 0xbfb8aa3b, v117
	v_exp_f32_e32 v153, v117
	s_nop 0
	v_add_f32_e32 v117, 1.0, v153
	v_rcp_f32_e32 v155, v117
	v_fma_f32 v117, v154, v158, v170
	v_max_f32_e32 v117, 0xda24260, v117
	v_cmp_gt_f32_e32 vcc, s33, v117
	v_pk_mul_f32 v[152:153], v[152:153], v[158:159]
	s_nop 0
	v_cndmask_b32_e64 v125, 0, 32, vcc
	v_ldexp_f32 v117, v117, v125
	v_log_f32_e32 v117, v117
	v_pk_mul_f32 v[182:183], v[154:155], v[152:153]
	v_cvt_pk_bf16_f32 v154, v128, v129
	v_cvt_pk_bf16_f32 v157, v182, v183
	v_mul_f32_e32 v125, 0x3f317217, v117
	v_fma_f32 v125, v117, s13, -v125
	v_fmac_f32_e32 v125, 0x3377d1cf, v117
	v_fmac_f32_e32 v125, 0x3f317217, v117
	v_cmp_lt_f32_e64 s[0:1], |v117|, s15
	s_nop 1
	v_cndmask_b32_e64 v117, v117, v125, s[0:1]
	v_cndmask_b32_e32 v125, 0, v194, vcc
	v_sub_f32_e32 v152, v117, v125
	v_fma_f32 v117, v155, v159, v171
	v_max_f32_e32 v117, 0xda24260, v117
	v_cmp_gt_f32_e32 vcc, s33, v117
	v_cvt_pk_bf16_f32 v155, v180, v181
	s_nop 0
	v_cndmask_b32_e64 v125, 0, 32, vcc
	v_ldexp_f32 v117, v117, v125
	v_log_f32_e32 v117, v117
	s_nop 0
	v_mul_f32_e32 v125, 0x3f317217, v117
	v_fma_f32 v125, v117, s13, -v125
	v_fmac_f32_e32 v125, 0x3377d1cf, v117
	v_fmac_f32_e32 v125, 0x3f317217, v117
	v_cmp_lt_f32_e64 s[0:1], |v117|, s15
	s_nop 1
	v_cndmask_b32_e64 v117, v117, v125, s[0:1]
	v_readlane_b32 s0, v253, 0
	v_readlane_b32 s1, v253, 1
	v_cndmask_b32_e32 v125, 0, v194, vcc
	v_sub_f32_e32 v153, v117, v125
	v_lshl_add_u64 v[128:129], v[118:119], 1, s[0:1]
	global_store_dwordx4 v[128:129], v[154:157], off
	v_lshl_add_u64 v[128:129], v[118:119], 2, s[2:3]
	s_mov_b64 s[0:1], 0
	global_store_dwordx4 v[128:129], v[106:109], off
	global_store_dwordx4 v[128:129], v[150:153], off offset:16

;     __device__ __forceinline__ void operator()(const f32x4 (&acc)[2][2][4][2], const pg8::Unit& u, int wr, int wc, int fr, int fq) const {
;     ...
;                 for (int m = 0; m < 4; ++m) rs[ai][m] = rsqrtf(ssq[lrow0 + ai * 128 + m * 16] * (1.f / 1024.f) + EPS);
; #pragma unroll
;             for (int bj = 0; bj < 2; ++bj) {
;                 const int c = c0 + bj * 128;
;                 float lb[8] = {0.f, 0.f, 0.f, 0.f, 0.f, 0.f, 0.f, 0.f};
;                 if (region == 1 && idx != 0) {
;                     const f32x4 a00 = *(const f32x4*)(lbsrc + c), a01 = *(const f32x4*)(lbsrc + c + 4), a10 = *(const f32x4*)(lbsrc + 1024 + c), a11 = *(const f32x4*)(lbsrc + 1024 + c + 4);
; #pragma unroll
;                     for (int j = 0; j < 4; ++j) { lb[j] = __builtin_amdgcn_rcpf(1.f + __expf(a00[j] - a10[j])); lb[4 + j] = __builtin_amdgcn_rcpf(1.f + __expf(a01[j] - a11[j])); }
;                 }
; #pragma unroll
;                 for (int ai = 0; ai < 2; ++ai)
; #pragma unroll
;                     for (int m = 0; m < 4; ++m) {
;                         const int row = lrow0 + ai * 128 + m * 16; const size_t off = (size_t)row * 1024 + c;
;                         const f32x4 v0 = acc[ai][bj][m][0] * rs[ai][m], v1 = acc[ai][bj][m][1] * rs[ai][m];
.LBB0_951:
	s_nop 1
	v_fmamk_f32 v106, v203, 0x3a800000, v139
	s_mov_b64 s[0:1], -1
	s_nop 0
	v_rsq_f32_e32 v108, v106
	v_or_b32_e32 v106, 48, v178
	v_ashrrev_i32_e32 v107, 31, v106
	v_lshlrev_b64 v[106:107], 10, v[106:107]
	s_nop 0
	v_or_b32_e32 v110, v106, v198
	v_mov_b32_e32 v111, v107
	v_pk_mul_f32 v[112:113], v[104:105], v[108:109] op_sel_hi:[1,0]
	v_pk_mul_f32 v[118:119], v[102:103], v[108:109] op_sel_hi:[1,0]
	v_pk_mul_f32 v[102:103], v[100:101], v[108:109] op_sel_hi:[1,0]
	v_pk_mul_f32 v[104:105], v[98:99], v[108:109] op_sel_hi:[1,0]
	s_and_b64 vcc, exec, s[44:45]
	s_cbranch_vccnz .LBB0_960
	s_and_b64 vcc, exec, s[42:43]
	s_cbranch_vccnz .LBB0_954
; __device__ __forceinline__ v4u pack8(const float (&y)[8]) { return (v4u){pk2(y[0], y[1]), pk2(y[2], y[3]), pk2(y[4], y[5]), pk2(y[6], y[7])}; }
;     __device__ __forceinline__ void operator()(const f32x4 (&acc)[2][2][4][2], const pg8::Unit& u, int wr, int wc, int fr, int fq) const {
;     ...
;                         } else if (region == 1) {
;                             float lf[8];
; #pragma unroll
;                             for (int j = 0; j < 8; ++j) {
;                                 const float om = 1.f - lb[j];
;                                 const float fc = fminf(fmaxf(v[j], -80.f), 80.f);
;                                 const float e = __expf(-fc), sg = __builtin_amdgcn_rcpf(1.f + e);
;                                 y[j] = om * e * sg;
;                                 lf[j] = __logf(fmaxf(lb[j] + om * sg, 1e-30f));
;                             }
;                             *(v4u*)(o1 + off) = pack8(y);
;                             *(f32x4*)(of + off) = (f32x4){lf[0], lf[1], lf[2], lf[3]}; *(f32x4*)(of + off + 4) = (f32x4){lf[4], lf[5], lf[6], lf[7]};
	v_max_f32_e32 v98, v118, v118
	s_mov_b32 s39, 0xc2a00000
	v_med3_f32 v98, v98, s39, v195
	v_mul_f32_e32 v98, 0xbfb8aa3b, v98
	v_exp_f32_e32 v98, v98
	v_pk_add_f32 v[126:127], v[176:177], 1.0 op_sel_hi:[1,0] neg_lo:[1,0] neg_hi:[1,0]
	s_mov_b32 s13, 0x3f317217
	s_mov_b32 s15, 0x7f800000
	v_add_f32_e32 v99, 1.0, v98
	v_rcp_f32_e32 v100, v99
	v_max_f32_e32 v99, v119, v119
	v_med3_f32 v99, v99, s39, v195
	v_mul_f32_e32 v99, 0xbfb8aa3b, v99
	v_exp_f32_e32 v99, v99
	v_pk_add_f32 v[150:151], v[174:175], 1.0 op_sel_hi:[1,0] neg_lo:[1,0] neg_hi:[1,0]
	v_pk_add_f32 v[152:153], v[172:173], 1.0 op_sel_hi:[1,0] neg_lo:[1,0] neg_hi:[1,0]
	v_pk_add_f32 v[156:157], v[170:171], 1.0 op_sel_hi:[1,0] neg_lo:[1,0] neg_hi:[1,0]
	v_add_f32_e32 v101, 1.0, v99
	v_rcp_f32_e32 v101, v101
	v_pk_mul_f32 v[98:99], v[98:99], v[126:127]
	s_nop 0
	v_pk_mul_f32 v[120:121], v[100:101], v[98:99]
	v_fma_f32 v98, v100, v126, v176
	v_max_f32_e32 v98, 0xda24260, v98
	v_cmp_gt_f32_e32 vcc, s33, v98
	s_nop 1
	v_cndmask_b32_e64 v99, 0, 32, vcc
	v_ldexp_f32 v98, v98, v99
	v_log_f32_e32 v98, v98
	s_nop 0
	v_mul_f32_e32 v99, 0x3f317217, v98
	v_fma_f32 v99, v98, s13, -v99
	v_fmac_f32_e32 v99, 0x3377d1cf, v98
	v_fmac_f32_e32 v99, 0x3f317217, v98
	v_cmp_lt_f32_e64 s[0:1], |v98|, s15
	s_nop 1
	v_cndmask_b32_e64 v98, v98, v99, s[0:1]
	v_cndmask_b32_e32 v99, 0, v194, vcc
	v_sub_f32_e32 v98, v98, v99
	v_fma_f32 v99, v101, v127, v177
	v_max_f32_e32 v99, 0xda24260, v99
	v_cmp_gt_f32_e32 vcc, s33, v99
	s_nop 1
	v_cndmask_b32_e64 v100, 0, 32, vcc
	v_ldexp_f32 v99, v99, v100
	v_log_f32_e32 v99, v99
	s_nop 0
	v_mul_f32_e32 v100, 0x3f317217, v99
	v_fma_f32 v100, v99, s13, -v100
	v_fmac_f32_e32 v100, 0x3377d1cf, v99
	v_fmac_f32_e32 v100, 0x3f317217, v99
	v_cmp_lt_f32_e64 s[0:1], |v99|, s15
	s_nop 1
	v_cndmask_b32_e64 v99, v99, v100, s[0:1]
	v_cndmask_b32_e32 v100, 0, v194, vcc
	v_sub_f32_e32 v99, v99, v100
	v_max_f32_e32 v100, v112, v112
	v_med3_f32 v100, v100, s39, v195
	v_mul_f32_e32 v100, 0xbfb8aa3b, v100
	v_exp_f32_e32 v100, v100
	s_nop 0
	v_add_f32_e32 v101, 1.0, v100
	v_rcp_f32_e32 v128, v101
	v_max_f32_e32 v101, v113, v113
	v_med3_f32 v101, v101, s39, v195
	v_mul_f32_e32 v101, 0xbfb8aa3b, v101
	v_exp_f32_e32 v101, v101
	s_nop 0
	v_add_f32_e32 v109, 1.0, v101
	v_rcp_f32_e32 v129, v109
	v_pk_mul_f32 v[100:101], v[100:101], v[150:151]
	s_nop 0
	v_pk_mul_f32 v[126:127], v[128:129], v[100:101]
	v_fma_f32 v100, v128, v150, v174
	v_max_f32_e32 v100, 0xda24260, v100
	v_cmp_gt_f32_e32 vcc, s33, v100
	s_nop 1
	v_cndmask_b32_e64 v101, 0, 32, vcc
	v_ldexp_f32 v100, v100, v101
	v_log_f32_e32 v100, v100
	s_nop 0
	v_mul_f32_e32 v101, 0x3f317217, v100
	v_fma_f32 v101, v100, s13, -v101
	v_fmac_f32_e32 v101, 0x3377d1cf, v100
	v_fmac_f32_e32 v101, 0x3f317217, v100
	v_cmp_lt_f32_e64 s[0:1], |v100|, s15
	s_nop 1
	v_cndmask_b32_e64 v100, v100, v101, s[0:1]
	v_cndmask_b32_e32 v101, 0, v194, vcc
	v_sub_f32_e32 v100, v100, v101
	v_fma_f32 v101, v129, v151, v175
	v_max_f32_e32 v101, 0xda24260, v101
	v_cmp_gt_f32_e32 vcc, s33, v101
	s_nop 1
	v_cndmask_b32_e64 v109, 0, 32, vcc
	v_ldexp_f32 v101, v101, v109
	v_log_f32_e32 v101, v101
	s_nop 0
	v_mul_f32_e32 v109, 0x3f317217, v101
	v_fma_f32 v109, v101, s13, -v109
	v_fmac_f32_e32 v109, 0x3377d1cf, v101
	v_fmac_f32_e32 v109, 0x3f317217, v101
	v_cmp_lt_f32_e64 s[0:1], |v101|, s15
	s_nop 1
	v_cndmask_b32_e64 v101, v101, v109, s[0:1]
	v_cndmask_b32_e32 v109, 0, v194, vcc
	v_sub_f32_e32 v101, v101, v109
	v_max_f32_e32 v109, v104, v104
	v_med3_f32 v109, v109, s39, v195
	v_mul_f32_e32 v109, 0xbfb8aa3b, v109
	v_exp_f32_e32 v128, v109
	s_nop 0
	v_add_f32_e32 v109, 1.0, v128
	v_rcp_f32_e32 v150, v109
	v_max_f32_e32 v109, v105, v105
	v_med3_f32 v109, v109, s39, v195
	v_mul_f32_e32 v109, 0xbfb8aa3b, v109
	v_exp_f32_e32 v129, v109
	s_nop 0
	v_add_f32_e32 v109, 1.0, v129
	v_rcp_f32_e32 v151, v109
	v_fma_f32 v109, v150, v152, v172
	v_max_f32_e32 v109, 0xda24260, v109
	v_cmp_gt_f32_e32 vcc, s33, v109
	v_pk_mul_f32 v[128:129], v[128:129], v[152:153]
	s_nop 0
	v_cndmask_b32_e64 v117, 0, 32, vcc
	v_ldexp_f32 v109, v109, v117
	v_log_f32_e32 v109, v109
	v_pk_mul_f32 v[128:129], v[150:151], v[128:129]
	v_mul_f32_e32 v117, 0x3f317217, v109
	v_fma_f32 v117, v109, s13, -v117
	v_fmac_f32_e32 v117, 0x3377d1cf, v109
	v_fmac_f32_e32 v117, 0x3f317217, v109
	v_cmp_lt_f32_e64 s[0:1], |v109|, s15
	s_nop 1
	v_cndmask_b32_e64 v109, v109, v117, s[0:1]
	v_cndmask_b32_e32 v117, 0, v194, vcc
	v_sub_f32_e32 v150, v109, v117
	v_fma_f32 v109, v151, v153, v173
	v_max_f32_e32 v109, 0xda24260, v109
	v_cmp_gt_f32_e32 vcc, s33, v109
	s_nop 1
	v_cndmask_b32_e64 v117, 0, 32, vcc
	v_ldexp_f32 v109, v109, v117
	v_log_f32_e32 v109, v109
	s_nop 0
	v_mul_f32_e32 v117, 0x3f317217, v109
	v_fma_f32 v117, v109, s13, -v117
	v_fmac_f32_e32 v117, 0x3377d1cf, v109
	v_fmac_f32_e32 v117, 0x3f317217, v109
	v_cmp_lt_f32_e64 s[0:1], |v109|, s15
	s_nop 1
	v_cndmask_b32_e64 v109, v109, v117, s[0:1]
	v_cndmask_b32_e32 v117, 0, v194, vcc
	v_sub_f32_e32 v151, v109, v117
	v_max_f32_e32 v109, v102, v102
	v_med3_f32 v109, v109, s39, v195
	v_mul_f32_e32 v109, 0xbfb8aa3b, v109
	v_exp_f32_e32 v152, v109
	s_nop 0
	v_add_f32_e32 v109, 1.0, v152
	v_rcp_f32_e32 v154, v109
	v_max_f32_e32 v109, v103, v103
	v_med3_f32 v109, v109, s39, v195
	v_mul_f32_e32 v109, 0xbfb8aa3b, v109
	v_exp_f32_e32 v153, v109
	s_nop 0
	v_add_f32_e32 v109, 1.0, v153
	v_rcp_f32_e32 v155, v109
	v_fma_f32 v109, v154, v156, v170
	v_max_f32_e32 v109, 0xda24260, v109
	v_cmp_gt_f32_e32 vcc, s33, v109
	v_pk_mul_f32 v[152:153], v[152:153], v[156:157]
	v_cvt_pk_bf16_f32 v156, v128, v129
	v_cndmask_b32_e64 v117, 0, 32, vcc
	v_ldexp_f32 v109, v109, v117
	v_log_f32_e32 v109, v109
	v_pk_mul_f32 v[158:159], v[154:155], v[152:153]
	v_cvt_pk_bf16_f32 v154, v120, v121
	v_mul_f32_e32 v117, 0x3f317217, v109
	v_fma_f32 v117, v109, s13, -v117
	v_fmac_f32_e32 v117, 0x3377d1cf, v109
	v_fmac_f32_e32 v117, 0x3f317217, v109
	v_cmp_lt_f32_e64 s[0:1], |v109|, s15
	s_nop 1
	v_cndmask_b32_e64 v109, v109, v117, s[0:1]
	v_cndmask_b32_e32 v117, 0, v194, vcc
	v_sub_f32_e32 v152, v109, v117
	v_fma_f32 v109, v155, v157, v171
	v_max_f32_e32 v109, 0xda24260, v109
	v_cmp_gt_f32_e32 vcc, s33, v109
	v_cvt_pk_bf16_f32 v155, v126, v127
	v_cvt_pk_bf16_f32 v157, v158, v159
	v_cndmask_b32_e64 v117, 0, 32, vcc
	v_ldexp_f32 v109, v109, v117
	v_log_f32_e32 v109, v109
	s_nop 0
	v_mul_f32_e32 v117, 0x3f317217, v109
	v_fma_f32 v117, v109, s13, -v117
	v_fmac_f32_e32 v117, 0x3377d1cf, v109
	v_fmac_f32_e32 v117, 0x3f317217, v109
	v_cmp_lt_f32_e64 s[0:1], |v109|, s15
	s_nop 1
	v_cndmask_b32_e64 v109, v109, v117, s[0:1]
	v_readlane_b32 s0, v253, 0
	v_readlane_b32 s1, v253, 1
	v_cndmask_b32_e32 v117, 0, v194, vcc
	v_sub_f32_e32 v153, v109, v117
	v_lshl_add_u64 v[120:121], v[110:111], 1, s[0:1]
	global_store_dwordx4 v[120:121], v[154:157], off
	v_lshl_add_u64 v[120:121], v[110:111], 2, s[2:3]
	s_mov_b64 s[0:1], 0
	global_store_dwordx4 v[120:121], v[98:101], off
	global_store_dwordx4 v[120:121], v[150:153], off offset:16

;     __device__ __forceinline__ void operator()(const f32x4 (&acc)[2][2][4][2], const pg8::Unit& u, int wr, int wc, int fr, int fq) const {
;     ...
;                 for (int m = 0; m < 4; ++m) rs[ai][m] = rsqrtf(ssq[lrow0 + ai * 128 + m * 16] * (1.f / 1024.f) + EPS);
;     ...
;                         const int row = lrow0 + ai * 128 + m * 16; const size_t off = (size_t)row * 1024 + c;
;                         const f32x4 v0 = acc[ai][bj][m][0] * rs[ai][m], v1 = acc[ai][bj][m][1] * rs[ai][m];
.LBB0_962:
	s_nop 1
	v_fmamk_f32 v98, v202, 0x3a800000, v139
	s_mov_b64 s[0:1], 0x20000
	s_nop 0
	v_rsq_f32_e32 v100, v98
	v_lshlrev_b64 v[98:99], 10, v[178:179]
	v_lshl_add_u64 v[98:99], v[98:99], 0, s[0:1]
	v_or_b32_e32 v102, v98, v198
	s_nop 0
	v_mov_b32_e32 v103, v99
	v_pk_mul_f32 v[104:105], v[96:97], v[100:101] op_sel_hi:[1,0]
	v_pk_mul_f32 v[110:111], v[94:95], v[100:101] op_sel_hi:[1,0]
	v_pk_mul_f32 v[94:95], v[92:93], v[100:101] op_sel_hi:[1,0]
	v_pk_mul_f32 v[96:97], v[90:91], v[100:101] op_sel_hi:[1,0]
	s_and_b64 vcc, exec, s[44:45]
	s_mov_b64 s[0:1], -1
	s_cbranch_vccnz .LBB0_971
	s_and_b64 vcc, exec, s[42:43]
	s_cbranch_vccnz .LBB0_965
; __device__ __forceinline__ v4u pack8(const float (&y)[8]) { return (v4u){pk2(y[0], y[1]), pk2(y[2], y[3]), pk2(y[4], y[5]), pk2(y[6], y[7])}; }
;     __device__ __forceinline__ void operator()(const f32x4 (&acc)[2][2][4][2], const pg8::Unit& u, int wr, int wc, int fr, int fq) const {
;     ...
;                         } else if (region == 1) {
;                             float lf[8];
; #pragma unroll
;                             for (int j = 0; j < 8; ++j) {
;                                 const float om = 1.f - lb[j];
;                                 const float fc = fminf(fmaxf(v[j], -80.f), 80.f);
;                                 const float e = __expf(-fc), sg = __builtin_amdgcn_rcpf(1.f + e);
;                                 y[j] = om * e * sg;
;                                 lf[j] = __logf(fmaxf(lb[j] + om * sg, 1e-30f));
;                             }
;                             *(v4u*)(o1 + off) = pack8(y);
;                             *(f32x4*)(of + off) = (f32x4){lf[0], lf[1], lf[2], lf[3]}; *(f32x4*)(of + off + 4) = (f32x4){lf[4], lf[5], lf[6], lf[7]};
	v_max_f32_e32 v90, v110, v110
	s_mov_b32 s39, 0xc2a00000
	v_med3_f32 v90, v90, s39, v195
	v_mul_f32_e32 v90, 0xbfb8aa3b, v90
	v_exp_f32_e32 v90, v90
	v_pk_add_f32 v[118:119], v[176:177], 1.0 op_sel_hi:[1,0] neg_lo:[1,0] neg_hi:[1,0]
	s_mov_b32 s13, 0x3f317217
	s_mov_b32 s15, 0x7f800000
	v_add_f32_e32 v91, 1.0, v90
	v_rcp_f32_e32 v92, v91
	v_max_f32_e32 v91, v111, v111
	v_med3_f32 v91, v91, s39, v195
	v_mul_f32_e32 v91, 0xbfb8aa3b, v91
	v_exp_f32_e32 v91, v91
	v_pk_add_f32 v[126:127], v[174:175], 1.0 op_sel_hi:[1,0] neg_lo:[1,0] neg_hi:[1,0]
	v_pk_add_f32 v[128:129], v[172:173], 1.0 op_sel_hi:[1,0] neg_lo:[1,0] neg_hi:[1,0]
	v_pk_add_f32 v[152:153], v[170:171], 1.0 op_sel_hi:[1,0] neg_lo:[1,0] neg_hi:[1,0]
	v_add_f32_e32 v93, 1.0, v91
	v_rcp_f32_e32 v93, v93
	v_pk_mul_f32 v[90:91], v[90:91], v[118:119]
	s_nop 0
	v_pk_mul_f32 v[112:113], v[92:93], v[90:91]
	v_fma_f32 v90, v92, v118, v176
	v_max_f32_e32 v90, 0xda24260, v90
	v_cmp_gt_f32_e32 vcc, s33, v90
	s_nop 1
	v_cndmask_b32_e64 v91, 0, 32, vcc
	v_ldexp_f32 v90, v90, v91
	v_log_f32_e32 v90, v90
	s_nop 0
	v_mul_f32_e32 v91, 0x3f317217, v90
	v_fma_f32 v91, v90, s13, -v91
	v_fmac_f32_e32 v91, 0x3377d1cf, v90
	v_fmac_f32_e32 v91, 0x3f317217, v90
	v_cmp_lt_f32_e64 s[0:1], |v90|, s15
	s_nop 1
	v_cndmask_b32_e64 v90, v90, v91, s[0:1]
	v_cndmask_b32_e32 v91, 0, v194, vcc
	v_sub_f32_e32 v90, v90, v91
	v_fma_f32 v91, v93, v119, v177
	v_max_f32_e32 v91, 0xda24260, v91
	v_cmp_gt_f32_e32 vcc, s33, v91
	s_nop 1
	v_cndmask_b32_e64 v92, 0, 32, vcc
	v_ldexp_f32 v91, v91, v92
	v_log_f32_e32 v91, v91
	s_nop 0
	v_mul_f32_e32 v92, 0x3f317217, v91
	v_fma_f32 v92, v91, s13, -v92
	v_fmac_f32_e32 v92, 0x3377d1cf, v91
	v_fmac_f32_e32 v92, 0x3f317217, v91
	v_cmp_lt_f32_e64 s[0:1], |v91|, s15
	s_nop 1
	v_cndmask_b32_e64 v91, v91, v92, s[0:1]
	v_cndmask_b32_e32 v92, 0, v194, vcc
	v_sub_f32_e32 v91, v91, v92
	v_max_f32_e32 v92, v104, v104
	v_med3_f32 v92, v92, s39, v195
	v_mul_f32_e32 v92, 0xbfb8aa3b, v92
	v_exp_f32_e32 v92, v92
	s_nop 0
	v_add_f32_e32 v93, 1.0, v92
	v_rcp_f32_e32 v120, v93
	v_max_f32_e32 v93, v105, v105
	v_med3_f32 v93, v93, s39, v195
	v_mul_f32_e32 v93, 0xbfb8aa3b, v93
	v_exp_f32_e32 v93, v93
	s_nop 0
	v_add_f32_e32 v101, 1.0, v93
	v_rcp_f32_e32 v121, v101
	v_pk_mul_f32 v[92:93], v[92:93], v[126:127]
	s_nop 0
	v_pk_mul_f32 v[118:119], v[120:121], v[92:93]
	v_fma_f32 v92, v120, v126, v174
	v_max_f32_e32 v92, 0xda24260, v92
	v_cmp_gt_f32_e32 vcc, s33, v92
	s_nop 1
	v_cndmask_b32_e64 v93, 0, 32, vcc
	v_ldexp_f32 v92, v92, v93
	v_log_f32_e32 v92, v92
	s_nop 0
	v_mul_f32_e32 v93, 0x3f317217, v92
	v_fma_f32 v93, v92, s13, -v93
	v_fmac_f32_e32 v93, 0x3377d1cf, v92
	v_fmac_f32_e32 v93, 0x3f317217, v92
	v_cmp_lt_f32_e64 s[0:1], |v92|, s15
	s_nop 1
	v_cndmask_b32_e64 v92, v92, v93, s[0:1]
	v_cndmask_b32_e32 v93, 0, v194, vcc
	v_sub_f32_e32 v92, v92, v93
	v_fma_f32 v93, v121, v127, v175
	v_max_f32_e32 v93, 0xda24260, v93
	v_cmp_gt_f32_e32 vcc, s33, v93
	s_nop 1
	v_cndmask_b32_e64 v101, 0, 32, vcc
	v_ldexp_f32 v93, v93, v101
	v_log_f32_e32 v93, v93
	s_nop 0
	v_mul_f32_e32 v101, 0x3f317217, v93
	v_fma_f32 v101, v93, s13, -v101
	v_fmac_f32_e32 v101, 0x3377d1cf, v93
	v_fmac_f32_e32 v101, 0x3f317217, v93
	v_cmp_lt_f32_e64 s[0:1], |v93|, s15
	s_nop 1
	v_cndmask_b32_e64 v93, v93, v101, s[0:1]
	v_cndmask_b32_e32 v101, 0, v194, vcc
	v_sub_f32_e32 v93, v93, v101
	v_max_f32_e32 v101, v96, v96
	v_med3_f32 v101, v101, s39, v195
	v_mul_f32_e32 v101, 0xbfb8aa3b, v101
	v_exp_f32_e32 v120, v101
	s_nop 0
	v_add_f32_e32 v101, 1.0, v120
	v_rcp_f32_e32 v126, v101
	v_max_f32_e32 v101, v97, v97
	v_med3_f32 v101, v101, s39, v195
	v_mul_f32_e32 v101, 0xbfb8aa3b, v101
	v_exp_f32_e32 v121, v101
	s_nop 0
	v_add_f32_e32 v101, 1.0, v121
	v_rcp_f32_e32 v127, v101
	v_fma_f32 v101, v126, v128, v172
	v_max_f32_e32 v101, 0xda24260, v101
	v_cmp_gt_f32_e32 vcc, s33, v101
	v_pk_mul_f32 v[120:121], v[120:121], v[128:129]
	s_nop 0
	v_cndmask_b32_e64 v109, 0, 32, vcc
	v_ldexp_f32 v101, v101, v109
	v_log_f32_e32 v101, v101
	v_pk_mul_f32 v[120:121], v[126:127], v[120:121]
	v_mul_f32_e32 v109, 0x3f317217, v101
	v_fma_f32 v109, v101, s13, -v109
	v_fmac_f32_e32 v109, 0x3377d1cf, v101
	v_fmac_f32_e32 v109, 0x3f317217, v101
	v_cmp_lt_f32_e64 s[0:1], |v101|, s15
	s_nop 1
	v_cndmask_b32_e64 v101, v101, v109, s[0:1]
	v_cndmask_b32_e32 v109, 0, v194, vcc
	v_sub_f32_e32 v126, v101, v109
	v_fma_f32 v101, v127, v129, v173
	v_max_f32_e32 v101, 0xda24260, v101
	v_cmp_gt_f32_e32 vcc, s33, v101
	s_nop 1
	v_cndmask_b32_e64 v109, 0, 32, vcc
	v_ldexp_f32 v101, v101, v109
	v_log_f32_e32 v101, v101
	s_nop 0
	v_mul_f32_e32 v109, 0x3f317217, v101
	v_fma_f32 v109, v101, s13, -v109
	v_fmac_f32_e32 v109, 0x3377d1cf, v101
	v_fmac_f32_e32 v109, 0x3f317217, v101
	v_cmp_lt_f32_e64 s[0:1], |v101|, s15
	s_nop 1
	v_cndmask_b32_e64 v101, v101, v109, s[0:1]
	v_cndmask_b32_e32 v109, 0, v194, vcc
	v_sub_f32_e32 v127, v101, v109
	v_max_f32_e32 v101, v94, v94
	v_med3_f32 v101, v101, s39, v195
	v_mul_f32_e32 v101, 0xbfb8aa3b, v101
	v_exp_f32_e32 v128, v101
	s_nop 0
	v_add_f32_e32 v101, 1.0, v128
	v_rcp_f32_e32 v150, v101
	v_max_f32_e32 v101, v95, v95
	v_med3_f32 v101, v101, s39, v195
	v_mul_f32_e32 v101, 0xbfb8aa3b, v101
	v_exp_f32_e32 v129, v101
	s_nop 0
	v_add_f32_e32 v101, 1.0, v129
	v_rcp_f32_e32 v151, v101
	v_fma_f32 v101, v150, v152, v170
	v_max_f32_e32 v101, 0xda24260, v101
	v_cmp_gt_f32_e32 vcc, s33, v101
	v_pk_mul_f32 v[128:129], v[128:129], v[152:153]
	v_cvt_pk_bf16_f32 v152, v120, v121
	v_cndmask_b32_e64 v109, 0, 32, vcc
	v_ldexp_f32 v101, v101, v109
	v_log_f32_e32 v101, v101
	v_pk_mul_f32 v[154:155], v[150:151], v[128:129]
	v_cvt_pk_bf16_f32 v150, v112, v113
	v_mul_f32_e32 v109, 0x3f317217, v101
	v_fma_f32 v109, v101, s13, -v109
	v_fmac_f32_e32 v109, 0x3377d1cf, v101
	v_fmac_f32_e32 v109, 0x3f317217, v101
	v_cmp_lt_f32_e64 s[0:1], |v101|, s15
	s_nop 1
	v_cndmask_b32_e64 v101, v101, v109, s[0:1]
	v_cndmask_b32_e32 v109, 0, v194, vcc
	v_sub_f32_e32 v128, v101, v109
	v_fma_f32 v101, v151, v153, v171
	v_max_f32_e32 v101, 0xda24260, v101
	v_cmp_gt_f32_e32 vcc, s33, v101
	v_cvt_pk_bf16_f32 v151, v118, v119
	v_cvt_pk_bf16_f32 v153, v154, v155
	v_cndmask_b32_e64 v109, 0, 32, vcc
	v_ldexp_f32 v101, v101, v109
	v_log_f32_e32 v101, v101
	s_nop 0
	v_mul_f32_e32 v109, 0x3f317217, v101
	v_fma_f32 v109, v101, s13, -v109
	v_fmac_f32_e32 v109, 0x3377d1cf, v101
	v_fmac_f32_e32 v109, 0x3f317217, v101
	v_cmp_lt_f32_e64 s[0:1], |v101|, s15
	s_nop 1
	v_cndmask_b32_e64 v101, v101, v109, s[0:1]
	v_readlane_b32 s0, v253, 0
	v_readlane_b32 s1, v253, 1
	v_cndmask_b32_e32 v109, 0, v194, vcc
	v_sub_f32_e32 v129, v101, v109
	v_lshl_add_u64 v[112:113], v[102:103], 1, s[0:1]
	global_store_dwordx4 v[112:113], v[150:153], off
	v_lshl_add_u64 v[112:113], v[102:103], 2, s[2:3]
	s_mov_b64 s[0:1], 0
	global_store_dwordx4 v[112:113], v[90:93], off
	global_store_dwordx4 v[112:113], v[126:129], off offset:16

;     __device__ __forceinline__ void operator()(const f32x4 (&acc)[2][2][4][2], const pg8::Unit& u, int wr, int wc, int fr, int fq) const {
;     ...
;                 for (int m = 0; m < 4; ++m) rs[ai][m] = rsqrtf(ssq[lrow0 + ai * 128 + m * 16] * (1.f / 1024.f) + EPS);
;     ...
;                         const int row = lrow0 + ai * 128 + m * 16; const size_t off = (size_t)row * 1024 + c;
;                         const f32x4 v0 = acc[ai][bj][m][0] * rs[ai][m], v1 = acc[ai][bj][m][1] * rs[ai][m];
.LBB0_973:
	s_nop 1
	v_fmamk_f32 v90, v201, 0x3a800000, v139
	s_mov_b64 s[0:1], 0x24000
	s_nop 0
	v_rsq_f32_e32 v92, v90
	v_lshlrev_b64 v[90:91], 10, v[178:179]
	v_lshl_add_u64 v[90:91], v[90:91], 0, s[0:1]
	v_or_b32_e32 v94, v90, v198
	s_nop 0
	v_mov_b32_e32 v95, v91
	v_pk_mul_f32 v[96:97], v[88:89], v[92:93] op_sel_hi:[1,0]
	v_pk_mul_f32 v[102:103], v[86:87], v[92:93] op_sel_hi:[1,0]
	v_pk_mul_f32 v[86:87], v[84:85], v[92:93] op_sel_hi:[1,0]
	v_pk_mul_f32 v[88:89], v[82:83], v[92:93] op_sel_hi:[1,0]
	s_and_b64 vcc, exec, s[44:45]
	s_mov_b64 s[0:1], -1
	s_cbranch_vccnz .LBB0_982
	s_and_b64 vcc, exec, s[42:43]
	s_cbranch_vccnz .LBB0_976
; __device__ __forceinline__ v4u pack8(const float (&y)[8]) { return (v4u){pk2(y[0], y[1]), pk2(y[2], y[3]), pk2(y[4], y[5]), pk2(y[6], y[7])}; }
;     __device__ __forceinline__ void operator()(const f32x4 (&acc)[2][2][4][2], const pg8::Unit& u, int wr, int wc, int fr, int fq) const {
;     ...
;                         } else if (region == 1) {
;                             float lf[8];
; #pragma unroll
;                             for (int j = 0; j < 8; ++j) {
;                                 const float om = 1.f - lb[j];
;                                 const float fc = fminf(fmaxf(v[j], -80.f), 80.f);
;                                 const float e = __expf(-fc), sg = __builtin_amdgcn_rcpf(1.f + e);
;                                 y[j] = om * e * sg;
;                                 lf[j] = __logf(fmaxf(lb[j] + om * sg, 1e-30f));
;                             }
;                             *(v4u*)(o1 + off) = pack8(y);
;                             *(f32x4*)(of + off) = (f32x4){lf[0], lf[1], lf[2], lf[3]}; *(f32x4*)(of + off + 4) = (f32x4){lf[4], lf[5], lf[6], lf[7]};
	v_max_f32_e32 v82, v102, v102
	s_mov_b32 s39, 0xc2a00000
	v_med3_f32 v82, v82, s39, v195
	v_mul_f32_e32 v82, 0xbfb8aa3b, v82
	v_exp_f32_e32 v82, v82
	v_pk_add_f32 v[110:111], v[176:177], 1.0 op_sel_hi:[1,0] neg_lo:[1,0] neg_hi:[1,0]
	s_mov_b32 s13, 0x3f317217
	s_mov_b32 s15, 0x7f800000
	v_add_f32_e32 v83, 1.0, v82
	v_rcp_f32_e32 v84, v83
	v_max_f32_e32 v83, v103, v103
	v_med3_f32 v83, v83, s39, v195
	v_mul_f32_e32 v83, 0xbfb8aa3b, v83
	v_exp_f32_e32 v83, v83
	v_pk_add_f32 v[118:119], v[174:175], 1.0 op_sel_hi:[1,0] neg_lo:[1,0] neg_hi:[1,0]
	v_pk_add_f32 v[120:121], v[172:173], 1.0 op_sel_hi:[1,0] neg_lo:[1,0] neg_hi:[1,0]
	v_pk_add_f32 v[128:129], v[170:171], 1.0 op_sel_hi:[1,0] neg_lo:[1,0] neg_hi:[1,0]
	v_add_f32_e32 v85, 1.0, v83
	v_rcp_f32_e32 v85, v85
	v_pk_mul_f32 v[82:83], v[82:83], v[110:111]
	s_nop 0
	v_pk_mul_f32 v[104:105], v[84:85], v[82:83]
	v_fma_f32 v82, v84, v110, v176
	v_max_f32_e32 v82, 0xda24260, v82
	v_cmp_gt_f32_e32 vcc, s33, v82
	s_nop 1
	v_cndmask_b32_e64 v83, 0, 32, vcc
	v_ldexp_f32 v82, v82, v83
	v_log_f32_e32 v82, v82
	s_nop 0
	v_mul_f32_e32 v83, 0x3f317217, v82
	v_fma_f32 v83, v82, s13, -v83
	v_fmac_f32_e32 v83, 0x3377d1cf, v82
	v_fmac_f32_e32 v83, 0x3f317217, v82
	v_cmp_lt_f32_e64 s[0:1], |v82|, s15
	s_nop 1
	v_cndmask_b32_e64 v82, v82, v83, s[0:1]
	v_cndmask_b32_e32 v83, 0, v194, vcc
	v_sub_f32_e32 v82, v82, v83
	v_fma_f32 v83, v85, v111, v177
	v_max_f32_e32 v83, 0xda24260, v83
	v_cmp_gt_f32_e32 vcc, s33, v83
	s_nop 1
	v_cndmask_b32_e64 v84, 0, 32, vcc
	v_ldexp_f32 v83, v83, v84
	v_log_f32_e32 v83, v83
	s_nop 0
	v_mul_f32_e32 v84, 0x3f317217, v83
	v_fma_f32 v84, v83, s13, -v84
	v_fmac_f32_e32 v84, 0x3377d1cf, v83
	v_fmac_f32_e32 v84, 0x3f317217, v83
	v_cmp_lt_f32_e64 s[0:1], |v83|, s15
	s_nop 1
	v_cndmask_b32_e64 v83, v83, v84, s[0:1]
	v_cndmask_b32_e32 v84, 0, v194, vcc
	v_sub_f32_e32 v83, v83, v84
	v_max_f32_e32 v84, v96, v96
	v_med3_f32 v84, v84, s39, v195
	v_mul_f32_e32 v84, 0xbfb8aa3b, v84
	v_exp_f32_e32 v84, v84
	s_nop 0
	v_add_f32_e32 v85, 1.0, v84
	v_rcp_f32_e32 v112, v85
	v_max_f32_e32 v85, v97, v97
	v_med3_f32 v85, v85, s39, v195
	v_mul_f32_e32 v85, 0xbfb8aa3b, v85
	v_exp_f32_e32 v85, v85
	s_nop 0
	v_add_f32_e32 v93, 1.0, v85
	v_rcp_f32_e32 v113, v93
	v_pk_mul_f32 v[84:85], v[84:85], v[118:119]
	s_nop 0
	v_pk_mul_f32 v[110:111], v[112:113], v[84:85]
	v_fma_f32 v84, v112, v118, v174
	v_max_f32_e32 v84, 0xda24260, v84
	v_cmp_gt_f32_e32 vcc, s33, v84
	s_nop 1
	v_cndmask_b32_e64 v85, 0, 32, vcc
	v_ldexp_f32 v84, v84, v85
	v_log_f32_e32 v84, v84
	s_nop 0
	v_mul_f32_e32 v85, 0x3f317217, v84
	v_fma_f32 v85, v84, s13, -v85
	v_fmac_f32_e32 v85, 0x3377d1cf, v84
	v_fmac_f32_e32 v85, 0x3f317217, v84
	v_cmp_lt_f32_e64 s[0:1], |v84|, s15
	s_nop 1
	v_cndmask_b32_e64 v84, v84, v85, s[0:1]
	v_cndmask_b32_e32 v85, 0, v194, vcc
	v_sub_f32_e32 v84, v84, v85
	v_fma_f32 v85, v113, v119, v175
	v_max_f32_e32 v85, 0xda24260, v85
	v_cmp_gt_f32_e32 vcc, s33, v85
	s_nop 1
	v_cndmask_b32_e64 v93, 0, 32, vcc
	v_ldexp_f32 v85, v85, v93
	v_log_f32_e32 v85, v85
	s_nop 0
	v_mul_f32_e32 v93, 0x3f317217, v85
	v_fma_f32 v93, v85, s13, -v93
	v_fmac_f32_e32 v93, 0x3377d1cf, v85
	v_fmac_f32_e32 v93, 0x3f317217, v85
	v_cmp_lt_f32_e64 s[0:1], |v85|, s15
	s_nop 1
	v_cndmask_b32_e64 v85, v85, v93, s[0:1]
	v_cndmask_b32_e32 v93, 0, v194, vcc
	v_sub_f32_e32 v85, v85, v93
	v_max_f32_e32 v93, v88, v88
	v_med3_f32 v93, v93, s39, v195
	v_mul_f32_e32 v93, 0xbfb8aa3b, v93
	v_exp_f32_e32 v112, v93
	s_nop 0
	v_add_f32_e32 v93, 1.0, v112
	v_rcp_f32_e32 v118, v93
	v_max_f32_e32 v93, v89, v89
	v_med3_f32 v93, v93, s39, v195
	v_mul_f32_e32 v93, 0xbfb8aa3b, v93
	v_exp_f32_e32 v113, v93
	s_nop 0
	v_add_f32_e32 v93, 1.0, v113
	v_rcp_f32_e32 v119, v93
	v_fma_f32 v93, v118, v120, v172
	v_max_f32_e32 v93, 0xda24260, v93
	v_cmp_gt_f32_e32 vcc, s33, v93
	v_pk_mul_f32 v[112:113], v[112:113], v[120:121]
	s_nop 0
	v_cndmask_b32_e64 v101, 0, 32, vcc
	v_ldexp_f32 v93, v93, v101
	v_log_f32_e32 v93, v93
	v_pk_mul_f32 v[112:113], v[118:119], v[112:113]
	v_mul_f32_e32 v101, 0x3f317217, v93
	v_fma_f32 v101, v93, s13, -v101
	v_fmac_f32_e32 v101, 0x3377d1cf, v93
	v_fmac_f32_e32 v101, 0x3f317217, v93
	v_cmp_lt_f32_e64 s[0:1], |v93|, s15
	s_nop 1
	v_cndmask_b32_e64 v93, v93, v101, s[0:1]
	v_cndmask_b32_e32 v101, 0, v194, vcc
	v_sub_f32_e32 v118, v93, v101
	v_fma_f32 v93, v119, v121, v173
	v_max_f32_e32 v93, 0xda24260, v93
	v_cmp_gt_f32_e32 vcc, s33, v93
	s_nop 1
	v_cndmask_b32_e64 v101, 0, 32, vcc
	v_ldexp_f32 v93, v93, v101
	v_log_f32_e32 v93, v93
	s_nop 0
	v_mul_f32_e32 v101, 0x3f317217, v93
	v_fma_f32 v101, v93, s13, -v101
	v_fmac_f32_e32 v101, 0x3377d1cf, v93
	v_fmac_f32_e32 v101, 0x3f317217, v93
	v_cmp_lt_f32_e64 s[0:1], |v93|, s15
	s_nop 1
	v_cndmask_b32_e64 v93, v93, v101, s[0:1]
	v_cndmask_b32_e32 v101, 0, v194, vcc
	v_sub_f32_e32 v119, v93, v101
	v_max_f32_e32 v93, v86, v86
	v_med3_f32 v93, v93, s39, v195
	v_mul_f32_e32 v93, 0xbfb8aa3b, v93
	v_exp_f32_e32 v120, v93
	s_nop 0
	v_add_f32_e32 v93, 1.0, v120
	v_rcp_f32_e32 v126, v93
	v_max_f32_e32 v93, v87, v87
	v_med3_f32 v93, v93, s39, v195
	v_mul_f32_e32 v93, 0xbfb8aa3b, v93
	v_exp_f32_e32 v121, v93
	s_nop 0
	v_add_f32_e32 v93, 1.0, v121
	v_rcp_f32_e32 v127, v93
	v_fma_f32 v93, v126, v128, v170
	v_max_f32_e32 v93, 0xda24260, v93
	v_cmp_gt_f32_e32 vcc, s33, v93
	v_pk_mul_f32 v[120:121], v[120:121], v[128:129]
	v_cvt_pk_bf16_f32 v128, v112, v113
	v_cndmask_b32_e64 v101, 0, 32, vcc
	v_ldexp_f32 v93, v93, v101
	v_log_f32_e32 v93, v93
	v_pk_mul_f32 v[150:151], v[126:127], v[120:121]
	v_cvt_pk_bf16_f32 v126, v104, v105
	v_mul_f32_e32 v101, 0x3f317217, v93
	v_fma_f32 v101, v93, s13, -v101
	v_fmac_f32_e32 v101, 0x3377d1cf, v93
	v_fmac_f32_e32 v101, 0x3f317217, v93
	v_cmp_lt_f32_e64 s[0:1], |v93|, s15
	s_nop 1
	v_cndmask_b32_e64 v93, v93, v101, s[0:1]
	v_cndmask_b32_e32 v101, 0, v194, vcc
	v_sub_f32_e32 v120, v93, v101
	v_fma_f32 v93, v127, v129, v171
	v_max_f32_e32 v93, 0xda24260, v93
	v_cmp_gt_f32_e32 vcc, s33, v93
	v_cvt_pk_bf16_f32 v127, v110, v111
	v_cvt_pk_bf16_f32 v129, v150, v151
	v_cndmask_b32_e64 v101, 0, 32, vcc
	v_ldexp_f32 v93, v93, v101
	v_log_f32_e32 v93, v93
	s_nop 0
	v_mul_f32_e32 v101, 0x3f317217, v93
	v_fma_f32 v101, v93, s13, -v101
	v_fmac_f32_e32 v101, 0x3377d1cf, v93
	v_fmac_f32_e32 v101, 0x3f317217, v93
	v_cmp_lt_f32_e64 s[0:1], |v93|, s15
	s_nop 1
	v_cndmask_b32_e64 v93, v93, v101, s[0:1]
	v_readlane_b32 s0, v253, 0
	v_readlane_b32 s1, v253, 1
	v_cndmask_b32_e32 v101, 0, v194, vcc
	v_sub_f32_e32 v121, v93, v101
	v_lshl_add_u64 v[104:105], v[94:95], 1, s[0:1]
	global_store_dwordx4 v[104:105], v[126:129], off
	v_lshl_add_u64 v[104:105], v[94:95], 2, s[2:3]
	s_mov_b64 s[0:1], 0
	global_store_dwordx4 v[104:105], v[82:85], off
	global_store_dwordx4 v[104:105], v[118:121], off offset:16

;     __device__ __forceinline__ void operator()(const f32x4 (&acc)[2][2][4][2], const pg8::Unit& u, int wr, int wc, int fr, int fq) const {
;     ...
;                 for (int m = 0; m < 4; ++m) rs[ai][m] = rsqrtf(ssq[lrow0 + ai * 128 + m * 16] * (1.f / 1024.f) + EPS);
;     ...
;                         const int row = lrow0 + ai * 128 + m * 16; const size_t off = (size_t)row * 1024 + c;
;                         const f32x4 v0 = acc[ai][bj][m][0] * rs[ai][m], v1 = acc[ai][bj][m][1] * rs[ai][m];
.LBB0_984:
	s_nop 1
	v_fmamk_f32 v82, v200, 0x3a800000, v139
	s_mov_b64 s[0:1], 0x28000
	s_nop 0
	v_rsq_f32_e32 v84, v82
	v_lshlrev_b64 v[82:83], 10, v[178:179]
	v_lshl_add_u64 v[82:83], v[82:83], 0, s[0:1]
	v_or_b32_e32 v86, v82, v198
	s_nop 0
	v_mov_b32_e32 v87, v83
	v_pk_mul_f32 v[88:89], v[80:81], v[84:85] op_sel_hi:[1,0]
	v_pk_mul_f32 v[94:95], v[78:79], v[84:85] op_sel_hi:[1,0]
	v_pk_mul_f32 v[78:79], v[76:77], v[84:85] op_sel_hi:[1,0]
	v_pk_mul_f32 v[80:81], v[74:75], v[84:85] op_sel_hi:[1,0]
	s_and_b64 vcc, exec, s[44:45]
	s_mov_b64 s[0:1], -1
	s_cbranch_vccnz .LBB0_993
	s_and_b64 vcc, exec, s[42:43]
	s_cbranch_vccnz .LBB0_987
; __device__ __forceinline__ v4u pack8(const float (&y)[8]) { return (v4u){pk2(y[0], y[1]), pk2(y[2], y[3]), pk2(y[4], y[5]), pk2(y[6], y[7])}; }
;     __device__ __forceinline__ void operator()(const f32x4 (&acc)[2][2][4][2], const pg8::Unit& u, int wr, int wc, int fr, int fq) const {
;     ...
;                         } else if (region == 1) {
;                             float lf[8];
; #pragma unroll
;                             for (int j = 0; j < 8; ++j) {
;                                 const float om = 1.f - lb[j];
;                                 const float fc = fminf(fmaxf(v[j], -80.f), 80.f);
;                                 const float e = __expf(-fc), sg = __builtin_amdgcn_rcpf(1.f + e);
;                                 y[j] = om * e * sg;
;                                 lf[j] = __logf(fmaxf(lb[j] + om * sg, 1e-30f));
;                             }
;                             *(v4u*)(o1 + off) = pack8(y);
;                             *(f32x4*)(of + off) = (f32x4){lf[0], lf[1], lf[2], lf[3]}; *(f32x4*)(of + off + 4) = (f32x4){lf[4], lf[5], lf[6], lf[7]};
	v_max_f32_e32 v74, v94, v94
	s_mov_b32 s39, 0xc2a00000
	v_med3_f32 v74, v74, s39, v195
	v_mul_f32_e32 v74, 0xbfb8aa3b, v74
	v_exp_f32_e32 v74, v74
	v_pk_add_f32 v[102:103], v[176:177], 1.0 op_sel_hi:[1,0] neg_lo:[1,0] neg_hi:[1,0]
	s_mov_b32 s13, 0x3f317217
	s_mov_b32 s15, 0x7f800000
	v_add_f32_e32 v75, 1.0, v74
	v_rcp_f32_e32 v76, v75
	v_max_f32_e32 v75, v95, v95
	v_med3_f32 v75, v75, s39, v195
	v_mul_f32_e32 v75, 0xbfb8aa3b, v75
	v_exp_f32_e32 v75, v75
	v_pk_add_f32 v[110:111], v[174:175], 1.0 op_sel_hi:[1,0] neg_lo:[1,0] neg_hi:[1,0]
	v_pk_add_f32 v[112:113], v[172:173], 1.0 op_sel_hi:[1,0] neg_lo:[1,0] neg_hi:[1,0]
	v_pk_add_f32 v[120:121], v[170:171], 1.0 op_sel_hi:[1,0] neg_lo:[1,0] neg_hi:[1,0]
	v_add_f32_e32 v77, 1.0, v75
	v_rcp_f32_e32 v77, v77
	v_pk_mul_f32 v[74:75], v[74:75], v[102:103]
	s_nop 0
	v_pk_mul_f32 v[96:97], v[76:77], v[74:75]
	v_fma_f32 v74, v76, v102, v176
	v_max_f32_e32 v74, 0xda24260, v74
	v_cmp_gt_f32_e32 vcc, s33, v74
	s_nop 1
	v_cndmask_b32_e64 v75, 0, 32, vcc
	v_ldexp_f32 v74, v74, v75
	v_log_f32_e32 v74, v74
	s_nop 0
	v_mul_f32_e32 v75, 0x3f317217, v74
	v_fma_f32 v75, v74, s13, -v75
	v_fmac_f32_e32 v75, 0x3377d1cf, v74
	v_fmac_f32_e32 v75, 0x3f317217, v74
	v_cmp_lt_f32_e64 s[0:1], |v74|, s15
	s_nop 1
	v_cndmask_b32_e64 v74, v74, v75, s[0:1]
	v_cndmask_b32_e32 v75, 0, v194, vcc
	v_sub_f32_e32 v74, v74, v75
	v_fma_f32 v75, v77, v103, v177
	v_max_f32_e32 v75, 0xda24260, v75
	v_cmp_gt_f32_e32 vcc, s33, v75
	s_nop 1
	v_cndmask_b32_e64 v76, 0, 32, vcc
	v_ldexp_f32 v75, v75, v76
	v_log_f32_e32 v75, v75
	s_nop 0
	v_mul_f32_e32 v76, 0x3f317217, v75
	v_fma_f32 v76, v75, s13, -v76
	v_fmac_f32_e32 v76, 0x3377d1cf, v75
	v_fmac_f32_e32 v76, 0x3f317217, v75
	v_cmp_lt_f32_e64 s[0:1], |v75|, s15
	s_nop 1
	v_cndmask_b32_e64 v75, v75, v76, s[0:1]
	v_cndmask_b32_e32 v76, 0, v194, vcc
	v_sub_f32_e32 v75, v75, v76
	v_max_f32_e32 v76, v88, v88
	v_med3_f32 v76, v76, s39, v195
	v_mul_f32_e32 v76, 0xbfb8aa3b, v76
	v_exp_f32_e32 v76, v76
	s_nop 0
	v_add_f32_e32 v77, 1.0, v76
	v_rcp_f32_e32 v104, v77
	v_max_f32_e32 v77, v89, v89
	v_med3_f32 v77, v77, s39, v195
	v_mul_f32_e32 v77, 0xbfb8aa3b, v77
	v_exp_f32_e32 v77, v77
	s_nop 0
	v_add_f32_e32 v85, 1.0, v77
	v_rcp_f32_e32 v105, v85
	v_pk_mul_f32 v[76:77], v[76:77], v[110:111]
	s_nop 0
	v_pk_mul_f32 v[102:103], v[104:105], v[76:77]
	v_fma_f32 v76, v104, v110, v174
	v_max_f32_e32 v76, 0xda24260, v76
	v_cmp_gt_f32_e32 vcc, s33, v76
	s_nop 1
	v_cndmask_b32_e64 v77, 0, 32, vcc
	v_ldexp_f32 v76, v76, v77
	v_log_f32_e32 v76, v76
	s_nop 0
	v_mul_f32_e32 v77, 0x3f317217, v76
	v_fma_f32 v77, v76, s13, -v77
	v_fmac_f32_e32 v77, 0x3377d1cf, v76
	v_fmac_f32_e32 v77, 0x3f317217, v76
	v_cmp_lt_f32_e64 s[0:1], |v76|, s15
	s_nop 1
	v_cndmask_b32_e64 v76, v76, v77, s[0:1]
	v_cndmask_b32_e32 v77, 0, v194, vcc
	v_sub_f32_e32 v76, v76, v77
	v_fma_f32 v77, v105, v111, v175
	v_max_f32_e32 v77, 0xda24260, v77
	v_cmp_gt_f32_e32 vcc, s33, v77
	s_nop 1
	v_cndmask_b32_e64 v85, 0, 32, vcc
	v_ldexp_f32 v77, v77, v85
	v_log_f32_e32 v77, v77
	s_nop 0
	v_mul_f32_e32 v85, 0x3f317217, v77
	v_fma_f32 v85, v77, s13, -v85
	v_fmac_f32_e32 v85, 0x3377d1cf, v77
	v_fmac_f32_e32 v85, 0x3f317217, v77
	v_cmp_lt_f32_e64 s[0:1], |v77|, s15
	s_nop 1
	v_cndmask_b32_e64 v77, v77, v85, s[0:1]
	v_cndmask_b32_e32 v85, 0, v194, vcc
	v_sub_f32_e32 v77, v77, v85
	v_max_f32_e32 v85, v80, v80
	v_med3_f32 v85, v85, s39, v195
	v_mul_f32_e32 v85, 0xbfb8aa3b, v85
	v_exp_f32_e32 v104, v85
	s_nop 0
	v_add_f32_e32 v85, 1.0, v104
	v_rcp_f32_e32 v110, v85
	v_max_f32_e32 v85, v81, v81
	v_med3_f32 v85, v85, s39, v195
	v_mul_f32_e32 v85, 0xbfb8aa3b, v85
	v_exp_f32_e32 v105, v85
	s_nop 0
	v_add_f32_e32 v85, 1.0, v105
	v_rcp_f32_e32 v111, v85
	v_fma_f32 v85, v110, v112, v172
	v_max_f32_e32 v85, 0xda24260, v85
	v_cmp_gt_f32_e32 vcc, s33, v85
	v_pk_mul_f32 v[104:105], v[104:105], v[112:113]
	s_nop 0
	v_cndmask_b32_e64 v93, 0, 32, vcc
	v_ldexp_f32 v85, v85, v93
	v_log_f32_e32 v85, v85
	v_pk_mul_f32 v[104:105], v[110:111], v[104:105]
	v_mul_f32_e32 v93, 0x3f317217, v85
	v_fma_f32 v93, v85, s13, -v93
	v_fmac_f32_e32 v93, 0x3377d1cf, v85
	v_fmac_f32_e32 v93, 0x3f317217, v85
	v_cmp_lt_f32_e64 s[0:1], |v85|, s15
	s_nop 1
	v_cndmask_b32_e64 v85, v85, v93, s[0:1]
	v_cndmask_b32_e32 v93, 0, v194, vcc
	v_sub_f32_e32 v110, v85, v93
	v_fma_f32 v85, v111, v113, v173
	v_max_f32_e32 v85, 0xda24260, v85
	v_cmp_gt_f32_e32 vcc, s33, v85
	s_nop 1
	v_cndmask_b32_e64 v93, 0, 32, vcc
	v_ldexp_f32 v85, v85, v93
	v_log_f32_e32 v85, v85
	s_nop 0
	v_mul_f32_e32 v93, 0x3f317217, v85
	v_fma_f32 v93, v85, s13, -v93
	v_fmac_f32_e32 v93, 0x3377d1cf, v85
	v_fmac_f32_e32 v93, 0x3f317217, v85
	v_cmp_lt_f32_e64 s[0:1], |v85|, s15
	s_nop 1
	v_cndmask_b32_e64 v85, v85, v93, s[0:1]
	v_cndmask_b32_e32 v93, 0, v194, vcc
	v_sub_f32_e32 v111, v85, v93
	v_max_f32_e32 v85, v78, v78
	v_med3_f32 v85, v85, s39, v195
	v_mul_f32_e32 v85, 0xbfb8aa3b, v85
	v_exp_f32_e32 v112, v85
	s_nop 0
	v_add_f32_e32 v85, 1.0, v112
	v_rcp_f32_e32 v118, v85
	v_max_f32_e32 v85, v79, v79
	v_med3_f32 v85, v85, s39, v195
	v_mul_f32_e32 v85, 0xbfb8aa3b, v85
	v_exp_f32_e32 v113, v85
	s_nop 0
	v_add_f32_e32 v85, 1.0, v113
	v_rcp_f32_e32 v119, v85
	v_fma_f32 v85, v118, v120, v170
	v_max_f32_e32 v85, 0xda24260, v85
	v_cmp_gt_f32_e32 vcc, s33, v85
	v_pk_mul_f32 v[112:113], v[112:113], v[120:121]
	v_cvt_pk_bf16_f32 v120, v104, v105
	v_cndmask_b32_e64 v93, 0, 32, vcc
	v_ldexp_f32 v85, v85, v93
	v_log_f32_e32 v85, v85
	v_pk_mul_f32 v[126:127], v[118:119], v[112:113]
	v_cvt_pk_bf16_f32 v118, v96, v97
	v_mul_f32_e32 v93, 0x3f317217, v85
	v_fma_f32 v93, v85, s13, -v93
	v_fmac_f32_e32 v93, 0x3377d1cf, v85
	v_fmac_f32_e32 v93, 0x3f317217, v85
	v_cmp_lt_f32_e64 s[0:1], |v85|, s15
	s_nop 1
	v_cndmask_b32_e64 v85, v85, v93, s[0:1]
	v_cndmask_b32_e32 v93, 0, v194, vcc
	v_sub_f32_e32 v112, v85, v93
	v_fma_f32 v85, v119, v121, v171
	v_max_f32_e32 v85, 0xda24260, v85
	v_cmp_gt_f32_e32 vcc, s33, v85
	v_cvt_pk_bf16_f32 v119, v102, v103
	v_cvt_pk_bf16_f32 v121, v126, v127
	v_cndmask_b32_e64 v93, 0, 32, vcc
	v_ldexp_f32 v85, v85, v93
	v_log_f32_e32 v85, v85
	s_nop 0
	v_mul_f32_e32 v93, 0x3f317217, v85
	v_fma_f32 v93, v85, s13, -v93
	v_fmac_f32_e32 v93, 0x3377d1cf, v85
	v_fmac_f32_e32 v93, 0x3f317217, v85
	v_cmp_lt_f32_e64 s[0:1], |v85|, s15
	s_nop 1
	v_cndmask_b32_e64 v85, v85, v93, s[0:1]
	v_readlane_b32 s0, v253, 0
	v_readlane_b32 s1, v253, 1
	v_cndmask_b32_e32 v93, 0, v194, vcc
	v_sub_f32_e32 v113, v85, v93
	v_lshl_add_u64 v[96:97], v[86:87], 1, s[0:1]
	global_store_dwordx4 v[96:97], v[118:121], off
	v_lshl_add_u64 v[96:97], v[86:87], 2, s[2:3]
	s_mov_b64 s[0:1], 0
	global_store_dwordx4 v[96:97], v[74:77], off
	global_store_dwordx4 v[96:97], v[110:113], off offset:16

;     __device__ __forceinline__ void operator()(const f32x4 (&acc)[2][2][4][2], const pg8::Unit& u, int wr, int wc, int fr, int fq) const {
;     ...
;                 for (int m = 0; m < 4; ++m) rs[ai][m] = rsqrtf(ssq[lrow0 + ai * 128 + m * 16] * (1.f / 1024.f) + EPS);
;     ...
;                         const int row = lrow0 + ai * 128 + m * 16; const size_t off = (size_t)row * 1024 + c;
;                         const f32x4 v0 = acc[ai][bj][m][0] * rs[ai][m], v1 = acc[ai][bj][m][1] * rs[ai][m];
.LBB0_995:
	s_nop 1
	v_fmamk_f32 v74, v199, 0x3a800000, v139
	s_mov_b64 s[0:1], 0x2c000
	s_nop 0
	v_rsq_f32_e32 v76, v74
	v_lshlrev_b64 v[74:75], 10, v[178:179]
	v_lshl_add_u64 v[74:75], v[74:75], 0, s[0:1]
	v_or_b32_e32 v78, v74, v198
	s_nop 0
	v_mov_b32_e32 v79, v75
	v_pk_mul_f32 v[80:81], v[72:73], v[76:77] op_sel_hi:[1,0]
	v_pk_mul_f32 v[86:87], v[70:71], v[76:77] op_sel_hi:[1,0]
	v_pk_mul_f32 v[70:71], v[68:69], v[76:77] op_sel_hi:[1,0]
	v_pk_mul_f32 v[72:73], v[66:67], v[76:77] op_sel_hi:[1,0]
	s_and_b64 vcc, exec, s[44:45]
	s_mov_b64 s[0:1], -1
	s_cbranch_vccnz .LBB0_1004
	s_and_b64 vcc, exec, s[42:43]
	s_cbranch_vccnz .LBB0_998
; __device__ __forceinline__ v4u pack8(const float (&y)[8]) { return (v4u){pk2(y[0], y[1]), pk2(y[2], y[3]), pk2(y[4], y[5]), pk2(y[6], y[7])}; }
;     __device__ __forceinline__ void operator()(const f32x4 (&acc)[2][2][4][2], const pg8::Unit& u, int wr, int wc, int fr, int fq) const {
;     ...
;                         } else if (region == 1) {
;                             float lf[8];
; #pragma unroll
;                             for (int j = 0; j < 8; ++j) {
;                                 const float om = 1.f - lb[j];
;                                 const float fc = fminf(fmaxf(v[j], -80.f), 80.f);
;                                 const float e = __expf(-fc), sg = __builtin_amdgcn_rcpf(1.f + e);
;                                 y[j] = om * e * sg;
;                                 lf[j] = __logf(fmaxf(lb[j] + om * sg, 1e-30f));
;                             }
;                             *(v4u*)(o1 + off) = pack8(y);
;                             *(f32x4*)(of + off) = (f32x4){lf[0], lf[1], lf[2], lf[3]}; *(f32x4*)(of + off + 4) = (f32x4){lf[4], lf[5], lf[6], lf[7]};
	v_max_f32_e32 v66, v86, v86
	s_mov_b32 s39, 0xc2a00000
	v_med3_f32 v66, v66, s39, v195
	v_mul_f32_e32 v66, 0xbfb8aa3b, v66
	v_exp_f32_e32 v66, v66
	v_pk_add_f32 v[94:95], v[176:177], 1.0 op_sel_hi:[1,0] neg_lo:[1,0] neg_hi:[1,0]
	s_mov_b32 s13, 0x3f317217
	s_mov_b32 s15, 0x7f800000
	v_add_f32_e32 v67, 1.0, v66
	v_rcp_f32_e32 v68, v67
	v_max_f32_e32 v67, v87, v87
	v_med3_f32 v67, v67, s39, v195
	v_mul_f32_e32 v67, 0xbfb8aa3b, v67
	v_exp_f32_e32 v67, v67
	v_fmac_f32_e32 v176, v68, v94
	v_pk_add_f32 v[102:103], v[174:175], 1.0 op_sel_hi:[1,0] neg_lo:[1,0] neg_hi:[1,0]
	v_pk_add_f32 v[104:105], v[172:173], 1.0 op_sel_hi:[1,0] neg_lo:[1,0] neg_hi:[1,0]
	v_add_f32_e32 v69, 1.0, v67
	v_rcp_f32_e32 v69, v69
	v_pk_mul_f32 v[66:67], v[66:67], v[94:95]
	v_pk_add_f32 v[112:113], v[170:171], 1.0 op_sel_hi:[1,0] neg_lo:[1,0] neg_hi:[1,0]
	v_pk_mul_f32 v[88:89], v[68:69], v[66:67]
	v_max_f32_e32 v66, 0xda24260, v176
	v_cmp_gt_f32_e32 vcc, s33, v66
	v_fmac_f32_e32 v177, v69, v95
	s_nop 0
	v_cndmask_b32_e64 v67, 0, 32, vcc
	v_ldexp_f32 v66, v66, v67
	v_log_f32_e32 v66, v66
	s_nop 0
	v_mul_f32_e32 v67, 0x3f317217, v66
	v_fma_f32 v67, v66, s13, -v67
	v_fmac_f32_e32 v67, 0x3377d1cf, v66
	v_fmac_f32_e32 v67, 0x3f317217, v66
	v_cmp_lt_f32_e64 s[0:1], |v66|, s15
	s_nop 1
	v_cndmask_b32_e64 v66, v66, v67, s[0:1]
	v_cndmask_b32_e32 v67, 0, v194, vcc
	v_sub_f32_e32 v66, v66, v67
	v_max_f32_e32 v67, 0xda24260, v177
	v_cmp_gt_f32_e32 vcc, s33, v67
	s_nop 1
	v_cndmask_b32_e64 v68, 0, 32, vcc
	v_ldexp_f32 v67, v67, v68
	v_log_f32_e32 v67, v67
	s_nop 0
	v_mul_f32_e32 v68, 0x3f317217, v67
	v_fma_f32 v68, v67, s13, -v68
	v_fmac_f32_e32 v68, 0x3377d1cf, v67
	v_fmac_f32_e32 v68, 0x3f317217, v67
	v_cmp_lt_f32_e64 s[0:1], |v67|, s15
	s_nop 1
	v_cndmask_b32_e64 v67, v67, v68, s[0:1]
	v_cndmask_b32_e32 v68, 0, v194, vcc
	v_sub_f32_e32 v67, v67, v68
	v_max_f32_e32 v68, v80, v80
	v_med3_f32 v68, v68, s39, v195
	v_mul_f32_e32 v68, 0xbfb8aa3b, v68
	v_exp_f32_e32 v68, v68
	s_nop 0
	v_add_f32_e32 v69, 1.0, v68
	v_rcp_f32_e32 v96, v69
	v_max_f32_e32 v69, v81, v81
	v_med3_f32 v69, v69, s39, v195
	v_mul_f32_e32 v69, 0xbfb8aa3b, v69
	v_exp_f32_e32 v69, v69
	v_fmac_f32_e32 v174, v96, v102
	v_add_f32_e32 v77, 1.0, v69
	v_rcp_f32_e32 v97, v77
	v_pk_mul_f32 v[68:69], v[68:69], v[102:103]
	v_fmac_f32_e32 v175, v97, v103
	v_pk_mul_f32 v[94:95], v[96:97], v[68:69]
	v_max_f32_e32 v68, 0xda24260, v174
	v_cmp_gt_f32_e32 vcc, s33, v68
	s_nop 1
	v_cndmask_b32_e64 v69, 0, 32, vcc
	v_ldexp_f32 v68, v68, v69
	v_log_f32_e32 v68, v68
	s_nop 0
	v_mul_f32_e32 v69, 0x3f317217, v68
	v_fma_f32 v69, v68, s13, -v69
	v_fmac_f32_e32 v69, 0x3377d1cf, v68
	v_fmac_f32_e32 v69, 0x3f317217, v68
	v_cmp_lt_f32_e64 s[0:1], |v68|, s15
	s_nop 1
	v_cndmask_b32_e64 v68, v68, v69, s[0:1]
	v_cndmask_b32_e32 v69, 0, v194, vcc
	v_sub_f32_e32 v68, v68, v69
	v_max_f32_e32 v69, 0xda24260, v175
	v_cmp_gt_f32_e32 vcc, s33, v69
	s_nop 1
	v_cndmask_b32_e64 v77, 0, 32, vcc
	v_ldexp_f32 v69, v69, v77
	v_log_f32_e32 v69, v69
	s_nop 0
	v_mul_f32_e32 v77, 0x3f317217, v69
	v_fma_f32 v77, v69, s13, -v77
	v_fmac_f32_e32 v77, 0x3377d1cf, v69
	v_fmac_f32_e32 v77, 0x3f317217, v69
	v_cmp_lt_f32_e64 s[0:1], |v69|, s15
	s_nop 1
	v_cndmask_b32_e64 v69, v69, v77, s[0:1]
	v_cndmask_b32_e32 v77, 0, v194, vcc
	v_sub_f32_e32 v69, v69, v77
	v_max_f32_e32 v77, v72, v72
	v_med3_f32 v77, v77, s39, v195
	v_mul_f32_e32 v77, 0xbfb8aa3b, v77
	v_exp_f32_e32 v96, v77
	s_nop 0
	v_add_f32_e32 v77, 1.0, v96
	v_rcp_f32_e32 v102, v77
	v_max_f32_e32 v77, v73, v73
	v_med3_f32 v77, v77, s39, v195
	v_mul_f32_e32 v77, 0xbfb8aa3b, v77
	v_exp_f32_e32 v97, v77
	v_fmac_f32_e32 v172, v102, v104
	v_add_f32_e32 v77, 1.0, v97
	v_rcp_f32_e32 v103, v77
	v_max_f32_e32 v77, 0xda24260, v172
	v_cmp_gt_f32_e32 vcc, s33, v77
	v_pk_mul_f32 v[96:97], v[96:97], v[104:105]
	v_fmac_f32_e32 v173, v103, v105
	v_cndmask_b32_e64 v85, 0, 32, vcc
	v_ldexp_f32 v77, v77, v85
	v_log_f32_e32 v77, v77
	v_pk_mul_f32 v[96:97], v[102:103], v[96:97]
	v_mul_f32_e32 v85, 0x3f317217, v77
	v_fma_f32 v85, v77, s13, -v85
	v_fmac_f32_e32 v85, 0x3377d1cf, v77
	v_fmac_f32_e32 v85, 0x3f317217, v77
	v_cmp_lt_f32_e64 s[0:1], |v77|, s15
	s_nop 1
	v_cndmask_b32_e64 v77, v77, v85, s[0:1]
	v_cndmask_b32_e32 v85, 0, v194, vcc
	v_sub_f32_e32 v102, v77, v85
	v_max_f32_e32 v77, 0xda24260, v173
	v_cmp_gt_f32_e32 vcc, s33, v77
	s_nop 1
	v_cndmask_b32_e64 v85, 0, 32, vcc
	v_ldexp_f32 v77, v77, v85
	v_log_f32_e32 v77, v77
	s_nop 0
	v_mul_f32_e32 v85, 0x3f317217, v77
	v_fma_f32 v85, v77, s13, -v85
	v_fmac_f32_e32 v85, 0x3377d1cf, v77
	v_fmac_f32_e32 v85, 0x3f317217, v77
	v_cmp_lt_f32_e64 s[0:1], |v77|, s15
	s_nop 1
	v_cndmask_b32_e64 v77, v77, v85, s[0:1]
	v_cndmask_b32_e32 v85, 0, v194, vcc
	v_sub_f32_e32 v103, v77, v85
	v_max_f32_e32 v77, v70, v70
	v_med3_f32 v77, v77, s39, v195
	v_mul_f32_e32 v77, 0xbfb8aa3b, v77
	v_exp_f32_e32 v104, v77
	s_nop 0
	v_add_f32_e32 v77, 1.0, v104
	v_rcp_f32_e32 v110, v77
	v_max_f32_e32 v77, v71, v71
	v_med3_f32 v77, v77, s39, v195
	v_mul_f32_e32 v77, 0xbfb8aa3b, v77
	v_exp_f32_e32 v105, v77
	v_fmac_f32_e32 v170, v110, v112
	v_add_f32_e32 v77, 1.0, v105
	v_rcp_f32_e32 v111, v77
	v_max_f32_e32 v77, 0xda24260, v170
	v_cmp_gt_f32_e32 vcc, s33, v77
	v_pk_mul_f32 v[104:105], v[104:105], v[112:113]
	v_fmac_f32_e32 v171, v111, v113
	v_cndmask_b32_e64 v85, 0, 32, vcc
	v_ldexp_f32 v77, v77, v85
	v_log_f32_e32 v77, v77
	v_pk_mul_f32 v[118:119], v[110:111], v[104:105]
	v_cvt_pk_bf16_f32 v110, v88, v89
	v_cvt_pk_bf16_f32 v111, v94, v95
	v_mul_f32_e32 v85, 0x3f317217, v77
	v_fma_f32 v85, v77, s13, -v85
	v_fmac_f32_e32 v85, 0x3377d1cf, v77
	v_fmac_f32_e32 v85, 0x3f317217, v77
	v_cmp_lt_f32_e64 s[0:1], |v77|, s15
	v_cvt_pk_bf16_f32 v112, v96, v97
	v_cvt_pk_bf16_f32 v113, v118, v119
	v_cndmask_b32_e64 v77, v77, v85, s[0:1]
	v_cndmask_b32_e32 v85, 0, v194, vcc
	v_sub_f32_e32 v104, v77, v85
	v_max_f32_e32 v77, 0xda24260, v171
	v_cmp_gt_f32_e32 vcc, s33, v77
	s_nop 1
	v_cndmask_b32_e64 v85, 0, 32, vcc
	v_ldexp_f32 v77, v77, v85
	v_log_f32_e32 v77, v77
	s_nop 0
	v_mul_f32_e32 v85, 0x3f317217, v77
	v_fma_f32 v85, v77, s13, -v85
	v_fmac_f32_e32 v85, 0x3377d1cf, v77
	v_fmac_f32_e32 v85, 0x3f317217, v77
	v_cmp_lt_f32_e64 s[0:1], |v77|, s15
	s_nop 1
	v_cndmask_b32_e64 v77, v77, v85, s[0:1]
	v_readlane_b32 s0, v253, 0
	v_readlane_b32 s1, v253, 1
	v_cndmask_b32_e32 v85, 0, v194, vcc
	v_sub_f32_e32 v105, v77, v85
	v_lshl_add_u64 v[88:89], v[78:79], 1, s[0:1]
	global_store_dwordx4 v[88:89], v[110:113], off
	v_lshl_add_u64 v[88:89], v[78:79], 2, s[2:3]
	s_mov_b64 s[0:1], 0
	global_store_dwordx4 v[88:89], v[66:69], off
	global_store_dwordx4 v[88:89], v[102:105], off offset:16

.LBB0_1293:
	s_add_i32 s8, s10, -1
	s_and_b32 s8, s8, 1
	s_lshl_b32 s9, s8, 11
	s_add_i32 s11, s9, 0
	s_add_i32 s11, s11, 0x1e400
	v_add_u32_e32 v147, s11, v136
	ds_read_b128 v[150:153], v147
	ds_read_b128 v[154:157], v147 offset:16
	s_mulk_i32 s8, 0x4400
	v_add_u32_e32 v147, s8, v135
	v_add_u32_e32 v177, s11, v133
	s_waitcnt lgkmcnt(1)
	v_mov_b32_e32 v158, v150
	s_waitcnt lgkmcnt(0)
	v_mov_b32_e32 v159, v154
	v_mov_b32_e32 v154, v151
	v_add_u32_e32 v150, v147, v134
	v_pk_add_f32 v[154:155], v[158:159], v[154:155]
	v_mov_b32_e32 v158, v152
	v_mov_b32_e32 v159, v156
	v_mov_b32_e32 v156, v153
	ds_read_b128 v[150:153], v150
	v_pk_add_f32 v[156:157], v[158:159], v[156:157]
	s_mov_b32 s22, 0x358637bd
	v_pk_add_f32 v[158:159], v[154:155], v[156:157]
	ds_read_b128 v[154:157], v177
	s_waitcnt lgkmcnt(1)
	v_lshlrev_b32_e32 v162, 16, v150
	v_and_b32_e32 v163, 0xffff0000, v150
	v_lshlrev_b32_e32 v166, 16, v151
	v_and_b32_e32 v167, 0xffff0000, v151
	v_lshlrev_b32_e32 v170, 16, v152
	v_and_b32_e32 v171, 0xffff0000, v152
	v_lshlrev_b32_e32 v174, 16, v153
	v_and_b32_e32 v175, 0xffff0000, v153
	ds_read_b128 v[150:153], v177 offset:16
	s_waitcnt lgkmcnt(1)
	v_mov_b32_e32 v178, v154
	v_mov_b32_e32 v154, v156
	s_add_u32 s8, s2, s18
	s_addc_u32 s9, s3, 0
	s_waitcnt lgkmcnt(0)
	v_mov_b32_e32 v179, v150
	v_mov_b32_e32 v150, v155
	v_mov_b32_e32 v155, v152
	v_mov_b32_e32 v152, v157
	v_pk_add_f32 v[150:151], v[178:179], v[150:151]
	v_pk_add_f32 v[152:153], v[154:155], v[152:153]
	v_mov_b64_e32 v[154:155], s[22:23]
	v_pk_add_f32 v[150:151], v[150:151], v[152:153]
	v_mov_b32_e32 v153, v158
	v_mov_b32_e32 v152, v150
	v_mov_b32_e32 v158, v151
	v_pk_add_f32 v[150:151], v[152:153], v[158:159]
	s_brev_b32 s22, 60
	v_pk_fma_f32 v[156:157], v[150:151], s[22:23], v[154:155] op_sel_hi:[1,0,0]
	s_waitcnt vmcnt(17)
	v_lshlrev_b32_e32 v164, 16, v82
	v_and_b32_e32 v165, 0xffff0000, v82
	v_lshlrev_b32_e32 v168, 16, v83
	v_mov_b32_e32 v150, v157
	v_rsq_f32_e32 v152, v150
	v_lshl_add_u64 v[150:151], s[8:9], 0, v[92:93]
	v_lshlrev_b64 v[150:151], 11, v[150:151]
	v_lshl_add_u64 v[158:159], v[110:111], 0, v[150:151]
	s_nop 0
	v_mov_b32_e32 v178, v152
	v_pk_mul_f32 v[150:151], v[178:179], v[162:163] op_sel_hi:[0,1]
	v_pk_mul_f32 v[152:153], v[178:179], v[166:167] op_sel_hi:[0,1]
	v_and_b32_e32 v169, 0xffff0000, v83
	v_pk_mul_f32 v[150:151], v[6:7], v[150:151]
	v_pk_mul_f32 v[152:153], v[8:9], v[152:153]
	v_pk_mul_f32 v[150:151], v[150:151], v[164:165]
	v_pk_mul_f32 v[152:153], v[152:153], v[168:169]
	v_cvt_pk_bf16_f32 v150, v150, v151
	v_cvt_pk_bf16_f32 v151, v152, v153
	v_pk_mul_f32 v[152:153], v[178:179], v[170:171] op_sel_hi:[0,1]
	v_lshlrev_b32_e32 v172, 16, v84
	v_and_b32_e32 v173, 0xffff0000, v84
	v_pk_mul_f32 v[152:153], v[2:3], v[152:153]
	v_pk_mul_f32 v[152:153], v[152:153], v[172:173]
	v_add_u32_e32 v82, v147, v132
	v_cvt_pk_bf16_f32 v152, v152, v153
	v_mov_b32_e32 v153, v156
	v_lshlrev_b32_e32 v176, 16, v85
	v_and_b32_e32 v177, 0xffff0000, v85
	ds_read_b128 v[82:85], v82
	v_pk_mul_f32 v[162:163], v[178:179], v[174:175] op_sel_hi:[0,1]
	v_rsq_f32_e32 v164, v153
	v_pk_mul_f32 v[162:163], v[4:5], v[162:163]
	v_add_u32_e32 v171, s11, v103
	v_pk_mul_f32 v[156:157], v[162:163], v[176:177]
	s_waitcnt vmcnt(15)
	v_lshlrev_b32_e32 v162, 16, v15
	v_cvt_pk_bf16_f32 v153, v156, v157
	global_store_dwordx4 v[158:159], v[150:153], off
	v_lshlrev_b32_e32 v156, 16, v66
	v_and_b32_e32 v157, 0xffff0000, v66
	s_nop 0
	v_mov_b32_e32 v150, v164
	s_waitcnt lgkmcnt(0)
	v_lshlrev_b32_e32 v152, 16, v82
	v_and_b32_e32 v153, 0xffff0000, v82
	v_pk_mul_f32 v[152:153], v[150:151], v[152:153] op_sel_hi:[0,1]
	v_pk_mul_f32 v[152:153], v[6:7], v[152:153]
	v_lshlrev_b32_e32 v82, 16, v83
	v_and_b32_e32 v83, 0xffff0000, v83
	v_pk_mul_f32 v[152:153], v[152:153], v[156:157]
	v_pk_mul_f32 v[82:83], v[150:151], v[82:83] op_sel_hi:[0,1]
	v_cvt_pk_bf16_f32 v66, v152, v153
	v_pk_mul_f32 v[82:83], v[8:9], v[82:83]
	v_lshlrev_b32_e32 v152, 16, v67
	v_and_b32_e32 v153, 0xffff0000, v67
	v_pk_mul_f32 v[82:83], v[82:83], v[152:153]
	v_lshlrev_b32_e32 v152, 16, v68
	v_cvt_pk_bf16_f32 v67, v82, v83
	v_lshlrev_b32_e32 v82, 16, v84
	v_and_b32_e32 v83, 0xffff0000, v84
	v_pk_mul_f32 v[82:83], v[150:151], v[82:83] op_sel_hi:[0,1]
	v_pk_mul_f32 v[82:83], v[2:3], v[82:83]
	v_and_b32_e32 v153, 0xffff0000, v68
	v_pk_mul_f32 v[82:83], v[82:83], v[152:153]
	v_lshlrev_b32_e32 v84, 16, v69
	v_cvt_pk_bf16_f32 v68, v82, v83
	v_lshlrev_b32_e32 v82, 16, v85
	v_and_b32_e32 v83, 0xffff0000, v85
	v_pk_mul_f32 v[82:83], v[150:151], v[82:83] op_sel_hi:[0,1]
	v_pk_mul_f32 v[82:83], v[4:5], v[82:83]
	v_and_b32_e32 v85, 0xffff0000, v69
	v_pk_mul_f32 v[82:83], v[82:83], v[84:85]
	v_add_u32_e32 v150, s11, v107
	v_cvt_pk_bf16_f32 v69, v82, v83
	ds_read_b128 v[82:85], v150
	ds_read_b128 v[150:153], v150 offset:16
	v_lshl_add_u64 v[156:157], s[8:9], 0, v[90:91]
	v_lshlrev_b64 v[156:157], 11, v[156:157]
	v_lshl_add_u64 v[156:157], v[110:111], 0, v[156:157]
	global_store_dwordx4 v[156:157], v[66:69], off
	v_lshlrev_b32_e32 v156, 16, v14
	v_and_b32_e32 v157, 0xffff0000, v14
	s_waitcnt lgkmcnt(1)
	v_mov_b32_e32 v66, v82
	s_waitcnt lgkmcnt(0)
	v_mov_b32_e32 v67, v150
	v_mov_b32_e32 v150, v83
	v_pk_add_f32 v[82:83], v[66:67], v[150:151]
	v_add_u32_e32 v66, v147, v105
	ds_read_b128 v[66:69], v66
	v_mov_b32_e32 v150, v84
	v_mov_b32_e32 v151, v152
	v_mov_b32_e32 v152, v85
	v_pk_add_f32 v[84:85], v[150:151], v[152:153]
	v_and_b32_e32 v163, 0xffff0000, v15
	v_pk_add_f32 v[150:151], v[82:83], v[84:85]
	ds_read_b128 v[82:85], v171
	s_waitcnt lgkmcnt(1)
	v_lshlrev_b32_e32 v152, 16, v66
	v_and_b32_e32 v153, 0xffff0000, v66
	v_lshlrev_b32_e32 v158, 16, v67
	v_and_b32_e32 v159, 0xffff0000, v67
	v_lshlrev_b32_e32 v164, 16, v68
	v_and_b32_e32 v165, 0xffff0000, v68
	v_lshlrev_b32_e32 v168, 16, v69
	v_and_b32_e32 v169, 0xffff0000, v69
	ds_read_b128 v[66:69], v171 offset:16
	s_waitcnt lgkmcnt(1)
	v_mov_b32_e32 v172, v82
	v_mov_b32_e32 v82, v84
	v_lshlrev_b32_e32 v166, 16, v16
	v_and_b32_e32 v167, 0xffff0000, v16
	s_waitcnt lgkmcnt(0)
	v_mov_b32_e32 v173, v66
	v_mov_b32_e32 v66, v83
	v_mov_b32_e32 v83, v68
	v_mov_b32_e32 v68, v85
	v_pk_add_f32 v[66:67], v[172:173], v[66:67]
	v_pk_add_f32 v[68:69], v[82:83], v[68:69]
	v_add_u32_e32 v14, v147, v97
	v_pk_add_f32 v[66:67], v[66:67], v[68:69]
	v_mov_b32_e32 v69, v150
	v_mov_b32_e32 v68, v66
	v_mov_b32_e32 v150, v67
	v_pk_add_f32 v[66:67], v[68:69], v[150:151]
	v_lshlrev_b32_e32 v170, 16, v17
	v_pk_fma_f32 v[82:83], v[66:67], s[22:23], v[154:155] op_sel_hi:[1,0,0]
	v_and_b32_e32 v171, 0xffff0000, v17
	ds_read_b128 v[14:17], v14
	s_nop 0
	v_mov_b32_e32 v66, v83
	v_rsq_f32_e32 v68, v66
	v_lshl_add_u64 v[66:67], s[8:9], 0, v[88:89]
	v_lshlrev_b64 v[66:67], 11, v[66:67]
	v_lshl_add_u64 v[84:85], v[110:111], 0, v[66:67]
	s_nop 0
	v_mov_b32_e32 v150, v68
	v_pk_mul_f32 v[66:67], v[150:151], v[152:153] op_sel_hi:[0,1]
	v_pk_mul_f32 v[68:69], v[150:151], v[158:159] op_sel_hi:[0,1]
	v_pk_mul_f32 v[66:67], v[6:7], v[66:67]
	v_pk_mul_f32 v[68:69], v[8:9], v[68:69]
	v_pk_mul_f32 v[66:67], v[66:67], v[156:157]
	v_pk_mul_f32 v[68:69], v[68:69], v[162:163]
	v_cvt_pk_bf16_f32 v66, v66, v67
	v_cvt_pk_bf16_f32 v67, v68, v69
	v_pk_mul_f32 v[68:69], v[150:151], v[164:165] op_sel_hi:[0,1]
	v_pk_mul_f32 v[68:69], v[2:3], v[68:69]
	v_pk_mul_f32 v[68:69], v[68:69], v[166:167]
	v_pk_mul_f32 v[150:151], v[150:151], v[168:169] op_sel_hi:[0,1]
	v_cvt_pk_bf16_f32 v68, v68, v69
	v_mov_b32_e32 v69, v82
	v_rsq_f32_e32 v147, v69
	v_pk_mul_f32 v[150:151], v[4:5], v[150:151]
	s_nop 0
	v_pk_mul_f32 v[82:83], v[150:151], v[170:171]
	s_nop 0
	v_cvt_pk_bf16_f32 v69, v82, v83
	global_store_dwordx4 v[84:85], v[66:69], off
	s_waitcnt vmcnt(17)
	v_lshlrev_b32_e32 v82, 16, v10
	v_and_b32_e32 v83, 0xffff0000, v10
	s_nop 0
	v_mov_b32_e32 v66, v147
	s_waitcnt lgkmcnt(0)
	v_lshlrev_b32_e32 v68, 16, v14
	v_and_b32_e32 v69, 0xffff0000, v14
	v_pk_mul_f32 v[68:69], v[66:67], v[68:69] op_sel_hi:[0,1]
	v_pk_mul_f32 v[68:69], v[6:7], v[68:69]
	v_lshlrev_b32_e32 v14, 16, v15
	v_and_b32_e32 v15, 0xffff0000, v15
	v_pk_mul_f32 v[68:69], v[68:69], v[82:83]
	v_pk_mul_f32 v[14:15], v[66:67], v[14:15] op_sel_hi:[0,1]
	v_cvt_pk_bf16_f32 v10, v68, v69
	v_pk_mul_f32 v[14:15], v[8:9], v[14:15]
	v_lshlrev_b32_e32 v68, 16, v11
	v_and_b32_e32 v69, 0xffff0000, v11
	v_pk_mul_f32 v[14:15], v[14:15], v[68:69]
	v_lshlrev_b32_e32 v68, 16, v12
	v_cvt_pk_bf16_f32 v11, v14, v15
	v_lshlrev_b32_e32 v14, 16, v16
	v_and_b32_e32 v15, 0xffff0000, v16
	v_pk_mul_f32 v[14:15], v[66:67], v[14:15] op_sel_hi:[0,1]
	v_pk_mul_f32 v[14:15], v[2:3], v[14:15]
	v_and_b32_e32 v69, 0xffff0000, v12
	v_pk_mul_f32 v[14:15], v[14:15], v[68:69]
	v_lshlrev_b32_e32 v16, 16, v13
	v_cvt_pk_bf16_f32 v12, v14, v15
	v_lshlrev_b32_e32 v14, 16, v17
	v_and_b32_e32 v15, 0xffff0000, v17
	v_pk_mul_f32 v[14:15], v[66:67], v[14:15] op_sel_hi:[0,1]
	v_pk_mul_f32 v[14:15], v[4:5], v[14:15]
	v_and_b32_e32 v17, 0xffff0000, v13
	v_pk_mul_f32 v[14:15], v[14:15], v[16:17]
	s_nop 0
	v_cvt_pk_bf16_f32 v13, v14, v15
	v_lshl_add_u64 v[14:15], s[8:9], 0, v[86:87]
	v_lshlrev_b64 v[14:15], 11, v[14:15]
	v_lshl_add_u64 v[14:15], v[110:111], 0, v[14:15]
	global_store_dwordx4 v[14:15], v[10:13], off
	s_nop 1
	v_lshl_add_u64 v[10:11], v[128:129], 0, s[6:7]
	v_lshl_add_u64 v[12:13], v[126:127], 0, s[6:7]
	global_load_dwordx4 v[82:85], v[10:11], off
	global_load_dwordx4 v[66:69], v[12:13], off
	v_lshl_add_u64 v[10:11], v[124:125], 0, s[6:7]
	v_lshl_add_u64 v[12:13], v[122:123], 0, s[6:7]
	global_load_dwordx4 v[14:17], v[10:11], off
	s_nop 0
	global_load_dwordx4 v[10:13], v[12:13], off

.LBB0_1304:
	s_waitcnt vmcnt(8)
	v_readlane_b32 s1, v255, 0
	v_readlane_b32 s0, v254, 63
	s_or_b32 s2, s2, 0x7c0
	s_waitcnt vmcnt(12)
	v_add_u32_e32 v22, s1, v136
	ds_read_b128 v[18:21], v22
	ds_read_b128 v[22:25], v22 offset:16
	s_waitcnt vmcnt(5)
	v_lshl_add_u32 v50, v96, 1, s0
	s_mov_b32 s0, 0x358637bd
	s_waitcnt vmcnt(3)
	v_lshlrev_b32_e32 v34, 16, v82
	s_waitcnt lgkmcnt(1)
	v_mov_b32_e32 v26, v18
	s_waitcnt lgkmcnt(0)
	v_mov_b32_e32 v27, v22
	v_mov_b32_e32 v22, v19
	v_add_u32_e32 v18, v50, v134
	v_pk_add_f32 v[22:23], v[26:27], v[22:23]
	v_mov_b32_e32 v26, v20
	v_mov_b32_e32 v27, v24
	v_mov_b32_e32 v24, v21
	ds_read_b128 v[18:21], v18
	v_pk_add_f32 v[24:25], v[26:27], v[24:25]
	v_add_u32_e32 v26, s1, v133
	v_pk_add_f32 v[30:31], v[22:23], v[24:25]
	ds_read_b128 v[22:25], v26
	s_waitcnt lgkmcnt(1)
	v_lshlrev_b32_e32 v32, 16, v18
	v_and_b32_e32 v33, 0xffff0000, v18
	v_lshlrev_b32_e32 v36, 16, v19
	v_and_b32_e32 v37, 0xffff0000, v19
	v_lshlrev_b32_e32 v40, 16, v20
	v_and_b32_e32 v41, 0xffff0000, v20
	v_lshlrev_b32_e32 v44, 16, v21
	v_and_b32_e32 v45, 0xffff0000, v21
	ds_read_b128 v[18:21], v26 offset:16
	s_waitcnt lgkmcnt(1)
	v_mov_b32_e32 v48, v22
	v_add_u32_e32 v22, v50, v132
	ds_read_b128 v[26:29], v22
	v_mov_b32_e32 v22, v24
	s_waitcnt lgkmcnt(1)
	v_mov_b32_e32 v49, v18
	v_mov_b32_e32 v18, v23
	v_mov_b32_e32 v23, v20
	v_mov_b32_e32 v20, v25
	v_pk_add_f32 v[18:19], v[48:49], v[18:19]
	v_pk_add_f32 v[20:21], v[22:23], v[20:21]
	v_and_b32_e32 v35, 0xffff0000, v82
	v_pk_add_f32 v[18:19], v[18:19], v[20:21]
	v_mov_b32_e32 v21, v30
	v_mov_b32_e32 v20, v18
	v_mov_b32_e32 v30, v19
	v_pk_add_f32 v[18:19], v[20:21], v[30:31]
	v_mov_b64_e32 v[30:31], s[0:1]
	s_brev_b32 s0, 60
	v_pk_fma_f32 v[22:23], v[18:19], s[0:1], v[30:31] op_sel_hi:[1,0,0]
	v_lshlrev_b32_e32 v38, 16, v83
	v_and_b32_e32 v39, 0xffff0000, v83
	v_lshlrev_b32_e32 v42, 16, v84
	v_mov_b32_e32 v18, v23
	v_rsq_f32_e32 v20, v18
	v_lshl_add_u64 v[18:19], s[2:3], 0, v[92:93]
	v_lshlrev_b64 v[18:19], 11, v[18:19]
	v_lshl_add_u64 v[24:25], v[94:95], 0, v[18:19]
	s_nop 0
	v_mov_b32_e32 v48, v20
	v_pk_mul_f32 v[18:19], v[48:49], v[32:33] op_sel_hi:[0,1]
	v_pk_mul_f32 v[20:21], v[48:49], v[36:37] op_sel_hi:[0,1]
	v_pk_mul_f32 v[18:19], v[6:7], v[18:19]
	v_pk_mul_f32 v[20:21], v[8:9], v[20:21]
	v_pk_mul_f32 v[18:19], v[18:19], v[34:35]
	v_pk_mul_f32 v[20:21], v[20:21], v[38:39]
	v_cvt_pk_bf16_f32 v18, v18, v19
	v_cvt_pk_bf16_f32 v19, v20, v21
	v_pk_mul_f32 v[20:21], v[48:49], v[40:41] op_sel_hi:[0,1]
	v_and_b32_e32 v43, 0xffff0000, v84
	v_pk_mul_f32 v[20:21], v[2:3], v[20:21]
	v_pk_mul_f32 v[20:21], v[20:21], v[42:43]
	v_pk_mul_f32 v[32:33], v[48:49], v[44:45] op_sel_hi:[0,1]
	v_cvt_pk_bf16_f32 v20, v20, v21
	v_mov_b32_e32 v21, v22
	v_rsq_f32_e32 v34, v21
	v_lshlrev_b32_e32 v46, 16, v85
	v_and_b32_e32 v47, 0xffff0000, v85
	v_pk_mul_f32 v[32:33], v[4:5], v[32:33]
	v_add_u32_e32 v45, s1, v103
	v_pk_mul_f32 v[22:23], v[32:33], v[46:47]
	v_lshl_add_u64 v[32:33], s[2:3], 0, v[90:91]
	v_cvt_pk_bf16_f32 v21, v22, v23
	global_store_dwordx4 v[24:25], v[18:21], off
	s_waitcnt vmcnt(3)
	v_lshlrev_b32_e32 v24, 16, v67
	v_and_b32_e32 v25, 0xffff0000, v67
	s_nop 0
	v_mov_b32_e32 v22, v34
	s_waitcnt lgkmcnt(0)
	v_lshlrev_b32_e32 v18, 16, v26
	v_and_b32_e32 v19, 0xffff0000, v26
	v_pk_mul_f32 v[18:19], v[22:23], v[18:19] op_sel_hi:[0,1]
	v_pk_mul_f32 v[18:19], v[6:7], v[18:19]
	v_lshlrev_b32_e32 v20, 16, v66
	v_and_b32_e32 v21, 0xffff0000, v66
	v_pk_mul_f32 v[18:19], v[18:19], v[20:21]
	v_lshlrev_b32_e32 v20, 16, v27
	v_and_b32_e32 v21, 0xffff0000, v27
	v_pk_mul_f32 v[20:21], v[22:23], v[20:21] op_sel_hi:[0,1]
	v_pk_mul_f32 v[20:21], v[8:9], v[20:21]
	v_cvt_pk_bf16_f32 v18, v18, v19
	v_pk_mul_f32 v[20:21], v[20:21], v[24:25]
	v_lshlrev_b32_e32 v24, 16, v68
	v_cvt_pk_bf16_f32 v19, v20, v21
	v_lshlrev_b32_e32 v20, 16, v28
	v_and_b32_e32 v21, 0xffff0000, v28
	v_pk_mul_f32 v[20:21], v[22:23], v[20:21] op_sel_hi:[0,1]
	v_pk_mul_f32 v[20:21], v[2:3], v[20:21]
	v_and_b32_e32 v25, 0xffff0000, v68
	v_pk_mul_f32 v[20:21], v[20:21], v[24:25]
	v_lshlrev_b32_e32 v24, 16, v29
	v_and_b32_e32 v25, 0xffff0000, v29
	v_pk_mul_f32 v[22:23], v[22:23], v[24:25] op_sel_hi:[0,1]
	v_pk_mul_f32 v[22:23], v[4:5], v[22:23]
	v_lshlrev_b32_e32 v24, 16, v69
	v_and_b32_e32 v25, 0xffff0000, v69
	v_pk_mul_f32 v[22:23], v[22:23], v[24:25]
	v_add_u32_e32 v26, s1, v107
	v_cvt_pk_bf16_f32 v20, v20, v21
	v_cvt_pk_bf16_f32 v21, v22, v23
	ds_read_b128 v[22:25], v26
	ds_read_b128 v[26:29], v26 offset:16
	v_lshlrev_b64 v[32:33], 11, v[32:33]
	v_lshl_add_u64 v[32:33], v[94:95], 0, v[32:33]
	global_store_dwordx4 v[32:33], v[18:21], off
	s_waitcnt vmcnt(3)
	v_lshlrev_b32_e32 v32, 16, v14
	v_and_b32_e32 v33, 0xffff0000, v14
	s_waitcnt lgkmcnt(1)
	v_mov_b32_e32 v18, v22
	s_waitcnt lgkmcnt(0)
	v_mov_b32_e32 v19, v26
	v_mov_b32_e32 v26, v23
	v_pk_add_f32 v[22:23], v[18:19], v[26:27]
	v_add_u32_e32 v18, v50, v105
	ds_read_b128 v[18:21], v18
	v_mov_b32_e32 v26, v24
	v_mov_b32_e32 v27, v28
	v_mov_b32_e32 v28, v25
	v_pk_add_f32 v[24:25], v[26:27], v[28:29]
	v_lshlrev_b32_e32 v36, 16, v15
	v_pk_add_f32 v[26:27], v[22:23], v[24:25]
	ds_read_b128 v[22:25], v45
	s_waitcnt lgkmcnt(1)
	v_lshlrev_b32_e32 v28, 16, v18
	v_and_b32_e32 v29, 0xffff0000, v18
	v_lshlrev_b32_e32 v34, 16, v19
	v_and_b32_e32 v35, 0xffff0000, v19
	v_lshlrev_b32_e32 v38, 16, v20
	v_and_b32_e32 v39, 0xffff0000, v20
	v_lshlrev_b32_e32 v42, 16, v21
	v_and_b32_e32 v43, 0xffff0000, v21
	ds_read_b128 v[18:21], v45 offset:16
	s_waitcnt lgkmcnt(1)
	v_mov_b32_e32 v46, v22
	v_mov_b32_e32 v22, v24
	v_and_b32_e32 v37, 0xffff0000, v15
	v_lshlrev_b32_e32 v40, 16, v16
	s_waitcnt lgkmcnt(0)
	v_mov_b32_e32 v47, v18
	v_mov_b32_e32 v18, v23
	v_mov_b32_e32 v23, v20
	v_mov_b32_e32 v20, v25
	v_pk_add_f32 v[18:19], v[46:47], v[18:19]
	v_pk_add_f32 v[20:21], v[22:23], v[20:21]
	v_and_b32_e32 v41, 0xffff0000, v16
	v_pk_add_f32 v[18:19], v[18:19], v[20:21]
	v_mov_b32_e32 v21, v26
	v_mov_b32_e32 v20, v18
	v_mov_b32_e32 v26, v19
	v_pk_add_f32 v[18:19], v[20:21], v[26:27]
	v_add_u32_e32 v14, v50, v97
	v_pk_fma_f32 v[22:23], v[18:19], s[0:1], v[30:31] op_sel_hi:[1,0,0]
	v_lshlrev_b32_e32 v44, 16, v17
	v_and_b32_e32 v45, 0xffff0000, v17
	ds_read_b128 v[14:17], v14
	v_mov_b32_e32 v18, v23
	v_rsq_f32_e32 v20, v18
	v_lshl_add_u64 v[18:19], s[2:3], 0, v[88:89]
	v_lshlrev_b64 v[18:19], 11, v[18:19]
	v_lshl_add_u64 v[24:25], v[94:95], 0, v[18:19]
	s_nop 0
	v_mov_b32_e32 v26, v20
	v_pk_mul_f32 v[18:19], v[26:27], v[28:29] op_sel_hi:[0,1]
	v_pk_mul_f32 v[20:21], v[26:27], v[34:35] op_sel_hi:[0,1]
	v_pk_mul_f32 v[18:19], v[6:7], v[18:19]
	v_pk_mul_f32 v[20:21], v[8:9], v[20:21]
	v_pk_mul_f32 v[18:19], v[18:19], v[32:33]
	v_pk_mul_f32 v[20:21], v[20:21], v[36:37]
	v_cvt_pk_bf16_f32 v18, v18, v19
	v_cvt_pk_bf16_f32 v19, v20, v21
	v_pk_mul_f32 v[20:21], v[26:27], v[38:39] op_sel_hi:[0,1]
	v_pk_mul_f32 v[20:21], v[2:3], v[20:21]
	v_pk_mul_f32 v[20:21], v[20:21], v[40:41]
	v_pk_mul_f32 v[26:27], v[26:27], v[42:43] op_sel_hi:[0,1]
	v_cvt_pk_bf16_f32 v20, v20, v21
	v_mov_b32_e32 v21, v22
	v_rsq_f32_e32 v28, v21
	v_pk_mul_f32 v[26:27], v[4:5], v[26:27]
	s_mov_b64 s[0:1], 0
	v_pk_mul_f32 v[22:23], v[26:27], v[44:45]
	s_nop 0
	v_cvt_pk_bf16_f32 v21, v22, v23
	global_store_dwordx4 v[24:25], v[18:21], off
	s_nop 1
	s_nop 0
	v_mov_b32_e32 v18, v28
	s_waitcnt lgkmcnt(0)
	v_lshlrev_b32_e32 v20, 16, v14
	v_and_b32_e32 v21, 0xffff0000, v14
	v_lshlrev_b32_e32 v14, 16, v15
	v_and_b32_e32 v15, 0xffff0000, v15
	v_pk_mul_f32 v[20:21], v[18:19], v[20:21] op_sel_hi:[0,1]
	v_pk_mul_f32 v[14:15], v[18:19], v[14:15] op_sel_hi:[0,1]
	v_pk_mul_f32 v[6:7], v[6:7], v[20:21]
	s_waitcnt vmcnt(3)
	v_lshlrev_b32_e32 v20, 16, v10
	v_and_b32_e32 v21, 0xffff0000, v10
	v_pk_mul_f32 v[8:9], v[8:9], v[14:15]
	v_lshlrev_b32_e32 v10, 16, v11
	v_and_b32_e32 v11, 0xffff0000, v11
	v_pk_mul_f32 v[6:7], v[6:7], v[20:21]
	v_pk_mul_f32 v[8:9], v[8:9], v[10:11]
	v_cvt_pk_bf16_f32 v6, v6, v7
	v_cvt_pk_bf16_f32 v7, v8, v9
	v_lshlrev_b32_e32 v8, 16, v16
	v_and_b32_e32 v9, 0xffff0000, v16
	v_pk_mul_f32 v[8:9], v[18:19], v[8:9] op_sel_hi:[0,1]
	v_pk_mul_f32 v[2:3], v[2:3], v[8:9]
	v_lshlrev_b32_e32 v8, 16, v12
	v_and_b32_e32 v9, 0xffff0000, v12
	v_pk_mul_f32 v[2:3], v[2:3], v[8:9]
	s_nop 0
	v_cvt_pk_bf16_f32 v8, v2, v3
	v_lshlrev_b32_e32 v2, 16, v17
	v_and_b32_e32 v3, 0xffff0000, v17
	v_pk_mul_f32 v[2:3], v[18:19], v[2:3] op_sel_hi:[0,1]
	v_pk_mul_f32 v[2:3], v[4:5], v[2:3]
	v_lshlrev_b32_e32 v4, 16, v13
	v_and_b32_e32 v5, 0xffff0000, v13
	v_pk_mul_f32 v[2:3], v[2:3], v[4:5]
	s_nop 0
	v_cvt_pk_bf16_f32 v9, v2, v3
	v_lshl_add_u64 v[2:3], s[2:3], 0, v[86:87]
	v_lshlrev_b64 v[2:3], 11, v[2:3]
	v_lshl_add_u64 v[2:3], v[94:95], 0, v[2:3]
	global_store_dwordx4 v[2:3], v[6:9], off
	s_setprio 0
